# v51 minus the redundant s_waitcnt lgkmcnt(0) between the hand-off barrier and the first MFMA of every K-loop MFMA segment (64 sites)
# baseline (speedup 1.0000x reference)
.LBB0_303:
	s_ashr_i32 s35, s34, 31
	s_lshl_b64 s[8:9], s[34:35], 20
	s_add_u32 s36, s53, s8
	s_addc_u32 s37, s54, s9
	s_and_b64 s[8:9], s[2:3], exec
	s_cselect_b32 s35, s37, s5
	s_cselect_b32 s52, s36, s4
	s_ashr_i32 s31, s30, 31
	s_lshl_b64 s[8:9], s[30:31], 20
	s_add_u32 s38, s55, s8
	s_addc_u32 s39, s56, s9
	s_and_b64 s[8:9], s[2:3], exec
	s_cselect_b32 s31, s39, s7
	s_cselect_b32 s77, s38, s6
	s_add_u32 s4, s4, 0x80080
	s_addc_u32 s5, s5, 0
	s_add_u32 s78, s6, 0x100
	s_addc_u32 s79, s7, 0
	s_mov_b32 s80, -2
	s_waitcnt lgkmcnt(0)
	ds_read_b128 v[2:5], v234
	ds_read_b128 v[6:9], v234 offset:1024
	ds_read_b128 v[10:13], v234 offset:2048
	ds_read_b128 v[14:17], v234 offset:3072
	ds_read_b128 v[18:21], v235
	ds_read_b128 v[22:25], v235 offset:1024
	ds_read_b128 v[26:29], v235 offset:2048
	ds_read_b128 v[30:33], v235 offset:3072
	s_add_u32 s6, s4, 0xfff80080
	s_addc_u32 s7, s5, -1
	s_cmp_eq_u32 s80, 28
	s_cselect_b32 s9, s35, s7
	s_cselect_b32 s8, s52, s6
	s_cselect_b32 s7, s31, s79
	s_cselect_b32 s6, s77, s78
	v_lshl_add_u64 v[214:215], s[4:5], 0, v[206:207]
	s_add_i32 m0, s43, 0xc000
	ds_read_b128 v[98:101], v236
	ds_read_b128 v[102:105], v236 offset:1024
	ds_read_b128 v[106:109], v236 offset:2048
	ds_read_b128 v[110:113], v236 offset:3072
	ds_read_b128 v[178:181], v236 offset:4096
	ds_read_b128 v[182:185], v236 offset:5120
	ds_read_b128 v[186:189], v236 offset:6144
	ds_read_b128 v[190:193], v236 offset:7168
	global_load_lds_dwordx4 v[214:215], off
	v_lshl_add_u64 v[214:215], s[4:5], 0, v[208:209]
	s_add_i32 m0, s43, 0xe000
	s_nop 0
	global_load_lds_dwordx4 v[214:215], off
	s_waitcnt vmcnt(8)
	s_waitcnt lgkmcnt(0)
	s_barrier
	v_mfma_i32_16x16x64_i8 v[174:177], v[2:5], v[98:101], 0
	v_mfma_i32_16x16x64_i8 v[174:177], v[6:9], v[102:105], v[174:177]
	v_mfma_i32_16x16x64_i8 v[170:173], v[10:13], v[98:101], 0
	v_mfma_i32_16x16x64_i8 v[170:173], v[14:17], v[102:105], v[170:173]
	v_mfma_i32_16x16x64_i8 v[158:161], v[2:5], v[106:109], 0
	v_mfma_i32_16x16x64_i8 v[158:161], v[6:9], v[110:113], v[158:161]
	v_mfma_i32_16x16x64_i8 v[154:157], v[10:13], v[106:109], 0
	v_mfma_i32_16x16x64_i8 v[154:157], v[14:17], v[110:113], v[154:157]
	v_mfma_i32_16x16x64_i8 v[142:145], v[2:5], v[178:181], 0
	v_mfma_i32_16x16x64_i8 v[142:145], v[6:9], v[182:185], v[142:145]
	v_mfma_i32_16x16x64_i8 v[138:141], v[10:13], v[178:181], 0
	v_mfma_i32_16x16x64_i8 v[138:141], v[14:17], v[182:185], v[138:141]
	v_mfma_i32_16x16x64_i8 v[126:129], v[2:5], v[186:189], 0
	v_mfma_i32_16x16x64_i8 v[126:129], v[6:9], v[190:193], v[126:129]
	v_mfma_i32_16x16x64_i8 v[122:125], v[10:13], v[186:189], 0
	v_mfma_i32_16x16x64_i8 v[122:125], v[14:17], v[190:193], v[122:125]
	v_mfma_i32_16x16x64_i8 v[166:169], v[18:21], v[98:101], 0
	v_mfma_i32_16x16x64_i8 v[166:169], v[22:25], v[102:105], v[166:169]
	v_mfma_i32_16x16x64_i8 v[98:101], v[26:29], v[98:101], 0
	v_mfma_i32_16x16x64_i8 v[98:101], v[30:33], v[102:105], v[98:101]
	v_mfma_i32_16x16x64_i8 v[102:105], v[18:21], v[106:109], 0
	v_mfma_i32_16x16x64_i8 v[102:105], v[22:25], v[110:113], v[102:105]
	v_mfma_i32_16x16x64_i8 v[106:109], v[26:29], v[106:109], 0
	v_mfma_i32_16x16x64_i8 v[106:109], v[30:33], v[110:113], v[106:109]
	v_mfma_i32_16x16x64_i8 v[130:133], v[26:29], v[178:181], 0
	v_mfma_i32_16x16x64_i8 v[130:133], v[30:33], v[182:185], v[130:133]
	v_mfma_i32_16x16x64_i8 v[118:121], v[18:21], v[186:189], 0
	v_mfma_i32_16x16x64_i8 v[118:121], v[22:25], v[190:193], v[118:121]
	v_mfma_i32_16x16x64_i8 v[114:117], v[26:29], v[186:189], 0
	v_mfma_i32_16x16x64_i8 v[114:117], v[30:33], v[190:193], v[114:117]
	v_mfma_i32_16x16x64_i8 v[110:113], v[18:21], v[178:181], 0
	v_mfma_i32_16x16x64_i8 v[110:113], v[22:25], v[182:185], v[110:113]
	s_barrier
	s_add_i32 s81, s70, s41
	v_lshl_add_u64 v[226:227], s[6:7], 0, v[196:197]
	s_mov_b32 m0, s81
	ds_read_b128 v[134:137], v236 offset:16384
	ds_read_b128 v[146:149], v236 offset:17408
	ds_read_b128 v[150:153], v236 offset:18432
	ds_read_b128 v[162:165], v236 offset:19456
	ds_read_b128 v[178:181], v236 offset:20480
	ds_read_b128 v[182:185], v236 offset:21504
	ds_read_b128 v[186:189], v236 offset:22528
	ds_read_b128 v[190:193], v236 offset:23552
	global_load_lds_dwordx4 v[226:227], off
	s_add_i32 m0, s81, 0x2000
	s_add_u32 s82, s6, 0x80000
	v_lshl_add_u64 v[244:245], s[6:7], 0, v[198:199]
	s_addc_u32 s83, s7, 0
	s_add_i32 s81, s71, s41
	global_load_lds_dwordx4 v[244:245], off
	v_lshl_add_u64 v[214:215], s[82:83], 0, v[196:197]
	s_mov_b32 m0, s81
	v_lshl_add_u64 v[246:247], s[8:9], 0, v[196:197]
	global_load_lds_dwordx4 v[214:215], off
	v_lshl_add_u64 v[214:215], s[82:83], 0, v[198:199]
	s_add_i32 m0, s81, 0x2000
	v_lshl_add_u64 v[248:249], s[8:9], 0, v[198:199]
	global_load_lds_dwordx4 v[214:215], off
	s_mov_b32 m0, s43
	s_nop 0
	global_load_lds_dwordx4 v[246:247], off
	s_mov_b32 m0, s57
	s_nop 0
	global_load_lds_dwordx4 v[248:249], off
	s_waitcnt vmcnt(8)
	s_waitcnt lgkmcnt(0)
	s_barrier
	v_mfma_i32_16x16x64_i8 v[94:97], v[2:5], v[134:137], 0
	v_mfma_i32_16x16x64_i8 v[94:97], v[6:9], v[146:149], v[94:97]
	v_mfma_i32_16x16x64_i8 v[90:93], v[10:13], v[134:137], 0
	v_mfma_i32_16x16x64_i8 v[90:93], v[14:17], v[146:149], v[90:93]
	v_mfma_i32_16x16x64_i8 v[78:81], v[2:5], v[150:153], 0
	v_mfma_i32_16x16x64_i8 v[78:81], v[6:9], v[162:165], v[78:81]
	v_mfma_i32_16x16x64_i8 v[74:77], v[10:13], v[150:153], 0
	v_mfma_i32_16x16x64_i8 v[74:77], v[14:17], v[162:165], v[74:77]
	v_mfma_i32_16x16x64_i8 v[62:65], v[2:5], v[178:181], 0
	v_mfma_i32_16x16x64_i8 v[62:65], v[6:9], v[182:185], v[62:65]
	v_mfma_i32_16x16x64_i8 v[58:61], v[10:13], v[178:181], 0
	v_mfma_i32_16x16x64_i8 v[58:61], v[14:17], v[182:185], v[58:61]
	v_mfma_i32_16x16x64_i8 v[2:5], v[2:5], v[186:189], 0
	v_mfma_i32_16x16x64_i8 v[2:5], v[6:9], v[190:193], v[2:5]
	v_mfma_i32_16x16x64_i8 v[6:9], v[10:13], v[186:189], 0
	v_mfma_i32_16x16x64_i8 v[6:9], v[14:17], v[190:193], v[6:9]
	v_mfma_i32_16x16x64_i8 v[42:45], v[18:21], v[150:153], 0
	v_mfma_i32_16x16x64_i8 v[70:73], v[22:25], v[162:165], v[42:45]
	v_mfma_i32_16x16x64_i8 v[42:45], v[26:29], v[150:153], 0
	v_mfma_i32_16x16x64_i8 v[66:69], v[30:33], v[162:165], v[42:45]
	v_mfma_i32_16x16x64_i8 v[42:45], v[18:21], v[178:181], 0
	v_mfma_i32_16x16x64_i8 v[54:57], v[22:25], v[182:185], v[42:45]
	v_mfma_i32_16x16x64_i8 v[10:13], v[18:21], v[134:137], 0
	v_mfma_i32_16x16x64_i8 v[10:13], v[22:25], v[146:149], v[10:13]
	v_mfma_i32_16x16x64_i8 v[42:45], v[26:29], v[178:181], 0
	v_mfma_i32_16x16x64_i8 v[50:53], v[30:33], v[182:185], v[42:45]
	v_mfma_i32_16x16x64_i8 v[18:21], v[18:21], v[186:189], 0
	v_mfma_i32_16x16x64_i8 v[18:21], v[22:25], v[190:193], v[18:21]
	v_mfma_i32_16x16x64_i8 v[14:17], v[26:29], v[134:137], 0
	v_mfma_i32_16x16x64_i8 v[14:17], v[30:33], v[146:149], v[14:17]
	v_mfma_i32_16x16x64_i8 v[22:25], v[26:29], v[186:189], 0
	v_mfma_i32_16x16x64_i8 v[22:25], v[30:33], v[190:193], v[22:25]
	s_barrier
	s_add_i32 s81, 0, 0x18000
	s_add_i32 s82, 0, 0x1c000
	v_add_u32_e32 v38, s81, v229
	v_add_u32_e32 v42, s82, v229
	ds_read_b128 v[26:29], v38
	ds_read_b128 v[30:33], v38 offset:1024
	ds_read_b128 v[34:37], v38 offset:2048
	ds_read_b128 v[38:41], v38 offset:3072
	ds_read_b128 v[178:181], v42
	ds_read_b128 v[182:185], v42 offset:1024
	ds_read_b128 v[186:189], v42 offset:2048
	ds_read_b128 v[190:193], v42 offset:3072
	s_add_u32 s8, s8, 0x80000
	s_addc_u32 s9, s9, 0
	s_mov_b32 m0, s60
	v_lshl_add_u64 v[134:135], s[8:9], 0, v[196:197]
	ds_read_b128 v[42:45], v236 offset:32768
	ds_read_b128 v[46:49], v236 offset:33792
	ds_read_b128 v[82:85], v236 offset:34816
	ds_read_b128 v[86:89], v236 offset:35840
	ds_read_b128 v[214:217], v236 offset:36864
	ds_read_b128 v[218:221], v236 offset:37888
	ds_read_b128 v[222:225], v236 offset:38912
	ds_read_b128 v[240:243], v236 offset:39936
	global_load_lds_dwordx4 v[134:135], off
	v_lshl_add_u64 v[134:135], s[8:9], 0, v[198:199]
	s_mov_b32 m0, s61
	s_nop 0
	global_load_lds_dwordx4 v[134:135], off
	s_waitcnt vmcnt(8)
	s_waitcnt lgkmcnt(0)
	s_barrier
	v_mfma_i32_16x16x64_i8 v[134:137], v[26:29], v[42:45], v[174:177]
	v_mfma_i32_16x16x64_i8 v[174:177], v[30:33], v[46:49], v[134:137]
	v_mfma_i32_16x16x64_i8 v[134:137], v[34:37], v[42:45], v[170:173]
	v_mfma_i32_16x16x64_i8 v[170:173], v[38:41], v[46:49], v[134:137]
	v_mfma_i32_16x16x64_i8 v[134:137], v[26:29], v[82:85], v[158:161]
	v_mfma_i32_16x16x64_i8 v[158:161], v[30:33], v[86:89], v[134:137]
	v_mfma_i32_16x16x64_i8 v[134:137], v[34:37], v[82:85], v[154:157]
	v_mfma_i32_16x16x64_i8 v[154:157], v[38:41], v[86:89], v[134:137]
	v_mfma_i32_16x16x64_i8 v[134:137], v[26:29], v[214:217], v[142:145]
	v_mfma_i32_16x16x64_i8 v[142:145], v[30:33], v[218:221], v[134:137]
	v_mfma_i32_16x16x64_i8 v[134:137], v[34:37], v[214:217], v[138:141]
	v_mfma_i32_16x16x64_i8 v[138:141], v[38:41], v[218:221], v[134:137]
	v_mfma_i32_16x16x64_i8 v[126:129], v[26:29], v[222:225], v[126:129]
	v_mfma_i32_16x16x64_i8 v[126:129], v[30:33], v[240:243], v[126:129]
	v_mfma_i32_16x16x64_i8 v[122:125], v[34:37], v[222:225], v[122:125]
	v_mfma_i32_16x16x64_i8 v[122:125], v[38:41], v[240:243], v[122:125]
	v_mfma_i32_16x16x64_i8 v[134:137], v[178:181], v[42:45], v[166:169]
	v_mfma_i32_16x16x64_i8 v[166:169], v[182:185], v[46:49], v[134:137]
	v_mfma_i32_16x16x64_i8 v[42:45], v[186:189], v[42:45], v[98:101]
	v_mfma_i32_16x16x64_i8 v[162:165], v[190:193], v[46:49], v[42:45]
	v_mfma_i32_16x16x64_i8 v[42:45], v[178:181], v[82:85], v[102:105]
	v_mfma_i32_16x16x64_i8 v[150:153], v[182:185], v[86:89], v[42:45]
	v_mfma_i32_16x16x64_i8 v[42:45], v[186:189], v[82:85], v[106:109]
	v_mfma_i32_16x16x64_i8 v[146:149], v[190:193], v[86:89], v[42:45]
	v_mfma_i32_16x16x64_i8 v[42:45], v[178:181], v[214:217], v[110:113]
	v_mfma_i32_16x16x64_i8 v[134:137], v[182:185], v[218:221], v[42:45]
	v_mfma_i32_16x16x64_i8 v[42:45], v[186:189], v[214:217], v[130:133]
	v_mfma_i32_16x16x64_i8 v[130:133], v[190:193], v[218:221], v[42:45]
	v_mfma_i32_16x16x64_i8 v[42:45], v[178:181], v[222:225], v[118:121]
	v_mfma_i32_16x16x64_i8 v[118:121], v[182:185], v[240:243], v[42:45]
	v_mfma_i32_16x16x64_i8 v[42:45], v[186:189], v[222:225], v[114:117]
	v_mfma_i32_16x16x64_i8 v[114:117], v[190:193], v[240:243], v[42:45]
	s_barrier
	s_add_i32 s8, s81, s41
	s_nop 3
	v_lshl_add_u64 v[42:43], v[226:227], 0, s[24:25]
	s_mov_b32 m0, s8
	ds_read_b128 v[82:85], v236 offset:49152
	ds_read_b128 v[98:101], v236 offset:50176
	ds_read_b128 v[102:105], v236 offset:51200
	ds_read_b128 v[106:109], v236 offset:52224
	ds_read_b128 v[110:113], v236 offset:53248
	ds_read_b128 v[214:217], v236 offset:54272
	ds_read_b128 v[218:221], v236 offset:55296
	ds_read_b128 v[222:225], v236 offset:56320
	global_load_lds_dwordx4 v[42:43], off
	s_add_i32 m0, s8, 0x2000
	s_add_u32 s6, s6, 0x80080
	v_lshl_add_u64 v[42:43], v[244:245], 0, s[24:25]
	s_addc_u32 s7, s7, 0
	s_add_i32 s8, s82, s41
	global_load_lds_dwordx4 v[42:43], off
	v_lshl_add_u64 v[42:43], s[6:7], 0, v[196:197]
	s_mov_b32 m0, s8
	s_nop 0
	global_load_lds_dwordx4 v[42:43], off
	v_lshl_add_u64 v[42:43], s[6:7], 0, v[198:199]
	s_add_i32 m0, s8, 0x2000
	s_nop 0
	global_load_lds_dwordx4 v[42:43], off
	v_lshl_add_u64 v[42:43], v[246:247], 0, s[24:25]
	s_mov_b32 m0, s63
	s_nop 0
	global_load_lds_dwordx4 v[42:43], off
	v_lshl_add_u64 v[42:43], v[248:249], 0, s[24:25]
	s_mov_b32 m0, s64
	s_nop 0
	global_load_lds_dwordx4 v[42:43], off
	s_waitcnt vmcnt(8)
	s_waitcnt lgkmcnt(0)
	s_barrier
	v_mfma_i32_16x16x64_i8 v[42:45], v[26:29], v[82:85], v[94:97]
	v_mfma_i32_16x16x64_i8 v[94:97], v[30:33], v[98:101], v[42:45]
	v_mfma_i32_16x16x64_i8 v[42:45], v[34:37], v[82:85], v[90:93]
	v_mfma_i32_16x16x64_i8 v[90:93], v[38:41], v[98:101], v[42:45]
	v_mfma_i32_16x16x64_i8 v[42:45], v[26:29], v[102:105], v[78:81]
	v_mfma_i32_16x16x64_i8 v[78:81], v[30:33], v[106:109], v[42:45]
	v_mfma_i32_16x16x64_i8 v[42:45], v[34:37], v[102:105], v[74:77]
	v_mfma_i32_16x16x64_i8 v[74:77], v[38:41], v[106:109], v[42:45]
	v_mfma_i32_16x16x64_i8 v[42:45], v[26:29], v[110:113], v[62:65]
	v_mfma_i32_16x16x64_i8 v[62:65], v[30:33], v[214:217], v[42:45]
	v_mfma_i32_16x16x64_i8 v[2:5], v[26:29], v[218:221], v[2:5]
	v_mfma_i32_16x16x64_i8 v[46:49], v[30:33], v[222:225], v[2:5]
	v_mfma_i32_16x16x64_i8 v[42:45], v[34:37], v[110:113], v[58:61]
	v_mfma_i32_16x16x64_i8 v[58:61], v[38:41], v[214:217], v[42:45]
	v_mfma_i32_16x16x64_i8 v[2:5], v[34:37], v[218:221], v[6:9]
	v_mfma_i32_16x16x64_i8 v[42:45], v[38:41], v[222:225], v[2:5]
	v_mfma_i32_16x16x64_i8 v[2:5], v[178:181], v[82:85], v[10:13]
	v_mfma_i32_16x16x64_i8 v[86:89], v[182:185], v[98:101], v[2:5]
	v_mfma_i32_16x16x64_i8 v[2:5], v[186:189], v[82:85], v[14:17]
	v_mfma_i32_16x16x64_i8 v[82:85], v[190:193], v[98:101], v[2:5]
	v_mfma_i32_16x16x64_i8 v[2:5], v[178:181], v[102:105], v[70:73]
	v_mfma_i32_16x16x64_i8 v[70:73], v[182:185], v[106:109], v[2:5]
	v_mfma_i32_16x16x64_i8 v[2:5], v[186:189], v[102:105], v[66:69]
	v_mfma_i32_16x16x64_i8 v[66:69], v[190:193], v[106:109], v[2:5]
	v_mfma_i32_16x16x64_i8 v[2:5], v[178:181], v[110:113], v[54:57]
	v_mfma_i32_16x16x64_i8 v[54:57], v[182:185], v[214:217], v[2:5]
	v_mfma_i32_16x16x64_i8 v[2:5], v[186:189], v[110:113], v[50:53]
	v_mfma_i32_16x16x64_i8 v[50:53], v[190:193], v[214:217], v[2:5]
	v_mfma_i32_16x16x64_i8 v[2:5], v[178:181], v[218:221], v[18:21]
	v_mfma_i32_16x16x64_i8 v[38:41], v[182:185], v[222:225], v[2:5]
	v_mfma_i32_16x16x64_i8 v[2:5], v[186:189], v[218:221], v[22:25]
	v_mfma_i32_16x16x64_i8 v[34:37], v[190:193], v[222:225], v[2:5]
	s_barrier
	s_add_i32 s80, s80, 2
	s_add_u32 s4, s4, 0x100
	s_addc_u32 s5, s5, 0
	s_add_u32 s78, s78, 0x100
	s_addc_u32 s79, s79, 0
	s_cmp_gt_u32 s80, 29
.LBB0_304:
	s_waitcnt lgkmcnt(0)
	ds_read_b128 v[2:5], v234
	ds_read_b128 v[6:9], v234 offset:1024
	ds_read_b128 v[10:13], v234 offset:2048
	ds_read_b128 v[14:17], v234 offset:3072
	ds_read_b128 v[18:21], v235
	ds_read_b128 v[22:25], v235 offset:1024
	ds_read_b128 v[26:29], v235 offset:2048
	ds_read_b128 v[30:33], v235 offset:3072
	s_add_u32 s6, s4, 0xfff80080
	s_addc_u32 s7, s5, -1
	s_cmp_eq_u32 s80, 28
	s_cselect_b32 s9, s35, s7
	s_cselect_b32 s8, s52, s6
	s_cselect_b32 s7, s31, s79
	s_cselect_b32 s6, s77, s78
	v_lshl_add_u64 v[214:215], s[4:5], 0, v[206:207]
	s_add_i32 m0, s43, 0xc000
	ds_read_b128 v[98:101], v236
	ds_read_b128 v[102:105], v236 offset:1024
	ds_read_b128 v[106:109], v236 offset:2048
	ds_read_b128 v[110:113], v236 offset:3072
	ds_read_b128 v[178:181], v236 offset:4096
	ds_read_b128 v[182:185], v236 offset:5120
	ds_read_b128 v[186:189], v236 offset:6144
	ds_read_b128 v[190:193], v236 offset:7168
	global_load_lds_dwordx4 v[214:215], off
	v_lshl_add_u64 v[214:215], s[4:5], 0, v[208:209]
	s_add_i32 m0, s43, 0xe000
	s_nop 0
	global_load_lds_dwordx4 v[214:215], off
	s_waitcnt vmcnt(8)
	s_waitcnt lgkmcnt(0)
	s_barrier
	v_mfma_i32_16x16x64_i8 v[174:177], v[2:5], v[98:101], v[174:177]
	v_mfma_i32_16x16x64_i8 v[174:177], v[6:9], v[102:105], v[174:177]
	v_mfma_i32_16x16x64_i8 v[170:173], v[10:13], v[98:101], v[170:173]
	v_mfma_i32_16x16x64_i8 v[170:173], v[14:17], v[102:105], v[170:173]
	v_mfma_i32_16x16x64_i8 v[158:161], v[2:5], v[106:109], v[158:161]
	v_mfma_i32_16x16x64_i8 v[158:161], v[6:9], v[110:113], v[158:161]
	v_mfma_i32_16x16x64_i8 v[154:157], v[10:13], v[106:109], v[154:157]
	v_mfma_i32_16x16x64_i8 v[154:157], v[14:17], v[110:113], v[154:157]
	v_mfma_i32_16x16x64_i8 v[142:145], v[2:5], v[178:181], v[142:145]
	v_mfma_i32_16x16x64_i8 v[142:145], v[6:9], v[182:185], v[142:145]
	v_mfma_i32_16x16x64_i8 v[138:141], v[10:13], v[178:181], v[138:141]
	v_mfma_i32_16x16x64_i8 v[138:141], v[14:17], v[182:185], v[138:141]
	v_mfma_i32_16x16x64_i8 v[126:129], v[2:5], v[186:189], v[126:129]
	v_mfma_i32_16x16x64_i8 v[126:129], v[6:9], v[190:193], v[126:129]
	v_mfma_i32_16x16x64_i8 v[122:125], v[10:13], v[186:189], v[122:125]
	v_mfma_i32_16x16x64_i8 v[122:125], v[14:17], v[190:193], v[122:125]
	v_mfma_i32_16x16x64_i8 v[166:169], v[18:21], v[98:101], v[166:169]
	v_mfma_i32_16x16x64_i8 v[166:169], v[22:25], v[102:105], v[166:169]
	v_mfma_i32_16x16x64_i8 v[98:101], v[26:29], v[98:101], v[162:165]
	v_mfma_i32_16x16x64_i8 v[98:101], v[30:33], v[102:105], v[98:101]
	v_mfma_i32_16x16x64_i8 v[102:105], v[18:21], v[106:109], v[150:153]
	v_mfma_i32_16x16x64_i8 v[102:105], v[22:25], v[110:113], v[102:105]
	v_mfma_i32_16x16x64_i8 v[106:109], v[26:29], v[106:109], v[146:149]
	v_mfma_i32_16x16x64_i8 v[106:109], v[30:33], v[110:113], v[106:109]
	v_mfma_i32_16x16x64_i8 v[130:133], v[26:29], v[178:181], v[130:133]
	v_mfma_i32_16x16x64_i8 v[130:133], v[30:33], v[182:185], v[130:133]
	v_mfma_i32_16x16x64_i8 v[118:121], v[18:21], v[186:189], v[118:121]
	v_mfma_i32_16x16x64_i8 v[118:121], v[22:25], v[190:193], v[118:121]
	v_mfma_i32_16x16x64_i8 v[114:117], v[26:29], v[186:189], v[114:117]
	v_mfma_i32_16x16x64_i8 v[114:117], v[30:33], v[190:193], v[114:117]
	v_mfma_i32_16x16x64_i8 v[110:113], v[18:21], v[178:181], v[134:137]
	v_mfma_i32_16x16x64_i8 v[110:113], v[22:25], v[182:185], v[110:113]
	s_barrier
	s_add_i32 s81, s70, s41
	v_lshl_add_u64 v[226:227], s[6:7], 0, v[196:197]
	s_mov_b32 m0, s81
	ds_read_b128 v[134:137], v236 offset:16384
	ds_read_b128 v[146:149], v236 offset:17408
	ds_read_b128 v[150:153], v236 offset:18432
	ds_read_b128 v[162:165], v236 offset:19456
	ds_read_b128 v[178:181], v236 offset:20480
	ds_read_b128 v[182:185], v236 offset:21504
	ds_read_b128 v[186:189], v236 offset:22528
	ds_read_b128 v[190:193], v236 offset:23552
	global_load_lds_dwordx4 v[226:227], off
	s_add_i32 m0, s81, 0x2000
	s_add_u32 s82, s6, 0x80000
	v_lshl_add_u64 v[244:245], s[6:7], 0, v[198:199]
	s_addc_u32 s83, s7, 0
	s_add_i32 s81, s71, s41
	global_load_lds_dwordx4 v[244:245], off
	v_lshl_add_u64 v[214:215], s[82:83], 0, v[196:197]
	s_mov_b32 m0, s81
	v_lshl_add_u64 v[246:247], s[8:9], 0, v[196:197]
	global_load_lds_dwordx4 v[214:215], off
	v_lshl_add_u64 v[214:215], s[82:83], 0, v[198:199]
	s_add_i32 m0, s81, 0x2000
	v_lshl_add_u64 v[248:249], s[8:9], 0, v[198:199]
	global_load_lds_dwordx4 v[214:215], off
	s_mov_b32 m0, s43
	s_nop 0
	global_load_lds_dwordx4 v[246:247], off
	s_mov_b32 m0, s57
	s_nop 0
	global_load_lds_dwordx4 v[248:249], off
	s_waitcnt vmcnt(8)
	s_waitcnt lgkmcnt(0)
	s_barrier
	v_mfma_i32_16x16x64_i8 v[94:97], v[2:5], v[134:137], v[94:97]
	v_mfma_i32_16x16x64_i8 v[94:97], v[6:9], v[146:149], v[94:97]
	v_mfma_i32_16x16x64_i8 v[90:93], v[10:13], v[134:137], v[90:93]
	v_mfma_i32_16x16x64_i8 v[90:93], v[14:17], v[146:149], v[90:93]
	v_mfma_i32_16x16x64_i8 v[78:81], v[2:5], v[150:153], v[78:81]
	v_mfma_i32_16x16x64_i8 v[78:81], v[6:9], v[162:165], v[78:81]
	v_mfma_i32_16x16x64_i8 v[74:77], v[10:13], v[150:153], v[74:77]
	v_mfma_i32_16x16x64_i8 v[74:77], v[14:17], v[162:165], v[74:77]
	v_mfma_i32_16x16x64_i8 v[62:65], v[2:5], v[178:181], v[62:65]
	v_mfma_i32_16x16x64_i8 v[62:65], v[6:9], v[182:185], v[62:65]
	v_mfma_i32_16x16x64_i8 v[58:61], v[10:13], v[178:181], v[58:61]
	v_mfma_i32_16x16x64_i8 v[58:61], v[14:17], v[182:185], v[58:61]
	v_mfma_i32_16x16x64_i8 v[2:5], v[2:5], v[186:189], v[46:49]
	v_mfma_i32_16x16x64_i8 v[2:5], v[6:9], v[190:193], v[2:5]
	v_mfma_i32_16x16x64_i8 v[6:9], v[10:13], v[186:189], v[42:45]
	v_mfma_i32_16x16x64_i8 v[6:9], v[14:17], v[190:193], v[6:9]
	v_mfma_i32_16x16x64_i8 v[42:45], v[18:21], v[150:153], v[70:73]
	v_mfma_i32_16x16x64_i8 v[70:73], v[22:25], v[162:165], v[42:45]
	v_mfma_i32_16x16x64_i8 v[42:45], v[26:29], v[150:153], v[66:69]
	v_mfma_i32_16x16x64_i8 v[66:69], v[30:33], v[162:165], v[42:45]
	v_mfma_i32_16x16x64_i8 v[42:45], v[18:21], v[178:181], v[54:57]
	v_mfma_i32_16x16x64_i8 v[54:57], v[22:25], v[182:185], v[42:45]
	v_mfma_i32_16x16x64_i8 v[10:13], v[18:21], v[134:137], v[86:89]
	v_mfma_i32_16x16x64_i8 v[10:13], v[22:25], v[146:149], v[10:13]
	v_mfma_i32_16x16x64_i8 v[42:45], v[26:29], v[178:181], v[50:53]
	v_mfma_i32_16x16x64_i8 v[50:53], v[30:33], v[182:185], v[42:45]
	v_mfma_i32_16x16x64_i8 v[18:21], v[18:21], v[186:189], v[38:41]
	v_mfma_i32_16x16x64_i8 v[18:21], v[22:25], v[190:193], v[18:21]
	v_mfma_i32_16x16x64_i8 v[14:17], v[26:29], v[134:137], v[82:85]
	v_mfma_i32_16x16x64_i8 v[14:17], v[30:33], v[146:149], v[14:17]
	v_mfma_i32_16x16x64_i8 v[22:25], v[26:29], v[186:189], v[34:37]
	v_mfma_i32_16x16x64_i8 v[22:25], v[30:33], v[190:193], v[22:25]
	s_barrier
	s_add_i32 s81, 0, 0x18000
	s_add_i32 s82, 0, 0x1c000
	v_add_u32_e32 v38, s81, v229
	v_add_u32_e32 v42, s82, v229
	ds_read_b128 v[26:29], v38
	ds_read_b128 v[30:33], v38 offset:1024
	ds_read_b128 v[34:37], v38 offset:2048
	ds_read_b128 v[38:41], v38 offset:3072
	ds_read_b128 v[178:181], v42
	ds_read_b128 v[182:185], v42 offset:1024
	ds_read_b128 v[186:189], v42 offset:2048
	ds_read_b128 v[190:193], v42 offset:3072
	s_add_u32 s8, s8, 0x80000
	s_addc_u32 s9, s9, 0
	s_mov_b32 m0, s60
	v_lshl_add_u64 v[134:135], s[8:9], 0, v[196:197]
	ds_read_b128 v[42:45], v236 offset:32768
	ds_read_b128 v[46:49], v236 offset:33792
	ds_read_b128 v[82:85], v236 offset:34816
	ds_read_b128 v[86:89], v236 offset:35840
	ds_read_b128 v[214:217], v236 offset:36864
	ds_read_b128 v[218:221], v236 offset:37888
	ds_read_b128 v[222:225], v236 offset:38912
	ds_read_b128 v[240:243], v236 offset:39936
	global_load_lds_dwordx4 v[134:135], off
	v_lshl_add_u64 v[134:135], s[8:9], 0, v[198:199]
	s_mov_b32 m0, s61
	s_nop 0
	global_load_lds_dwordx4 v[134:135], off
	s_waitcnt vmcnt(8)
	s_waitcnt lgkmcnt(0)
	s_barrier
	v_mfma_i32_16x16x64_i8 v[134:137], v[26:29], v[42:45], v[174:177]
	v_mfma_i32_16x16x64_i8 v[174:177], v[30:33], v[46:49], v[134:137]
	v_mfma_i32_16x16x64_i8 v[134:137], v[34:37], v[42:45], v[170:173]
	v_mfma_i32_16x16x64_i8 v[170:173], v[38:41], v[46:49], v[134:137]
	v_mfma_i32_16x16x64_i8 v[134:137], v[26:29], v[82:85], v[158:161]
	v_mfma_i32_16x16x64_i8 v[158:161], v[30:33], v[86:89], v[134:137]
	v_mfma_i32_16x16x64_i8 v[134:137], v[34:37], v[82:85], v[154:157]
	v_mfma_i32_16x16x64_i8 v[154:157], v[38:41], v[86:89], v[134:137]
	v_mfma_i32_16x16x64_i8 v[134:137], v[26:29], v[214:217], v[142:145]
	v_mfma_i32_16x16x64_i8 v[142:145], v[30:33], v[218:221], v[134:137]
	v_mfma_i32_16x16x64_i8 v[134:137], v[34:37], v[214:217], v[138:141]
	v_mfma_i32_16x16x64_i8 v[138:141], v[38:41], v[218:221], v[134:137]
	v_mfma_i32_16x16x64_i8 v[126:129], v[26:29], v[222:225], v[126:129]
	v_mfma_i32_16x16x64_i8 v[126:129], v[30:33], v[240:243], v[126:129]
	v_mfma_i32_16x16x64_i8 v[122:125], v[34:37], v[222:225], v[122:125]
	v_mfma_i32_16x16x64_i8 v[122:125], v[38:41], v[240:243], v[122:125]
	v_mfma_i32_16x16x64_i8 v[134:137], v[178:181], v[42:45], v[166:169]
	v_mfma_i32_16x16x64_i8 v[166:169], v[182:185], v[46:49], v[134:137]
	v_mfma_i32_16x16x64_i8 v[42:45], v[186:189], v[42:45], v[98:101]
	v_mfma_i32_16x16x64_i8 v[162:165], v[190:193], v[46:49], v[42:45]
	v_mfma_i32_16x16x64_i8 v[42:45], v[178:181], v[82:85], v[102:105]
	v_mfma_i32_16x16x64_i8 v[150:153], v[182:185], v[86:89], v[42:45]
	v_mfma_i32_16x16x64_i8 v[42:45], v[186:189], v[82:85], v[106:109]
	v_mfma_i32_16x16x64_i8 v[146:149], v[190:193], v[86:89], v[42:45]
	v_mfma_i32_16x16x64_i8 v[42:45], v[178:181], v[214:217], v[110:113]
	v_mfma_i32_16x16x64_i8 v[134:137], v[182:185], v[218:221], v[42:45]
	v_mfma_i32_16x16x64_i8 v[42:45], v[186:189], v[214:217], v[130:133]
	v_mfma_i32_16x16x64_i8 v[130:133], v[190:193], v[218:221], v[42:45]
	v_mfma_i32_16x16x64_i8 v[42:45], v[178:181], v[222:225], v[118:121]
	v_mfma_i32_16x16x64_i8 v[118:121], v[182:185], v[240:243], v[42:45]
	v_mfma_i32_16x16x64_i8 v[42:45], v[186:189], v[222:225], v[114:117]
	v_mfma_i32_16x16x64_i8 v[114:117], v[190:193], v[240:243], v[42:45]
	s_barrier
	s_add_i32 s8, s81, s41
	s_nop 3
	v_lshl_add_u64 v[42:43], v[226:227], 0, s[24:25]
	s_mov_b32 m0, s8
	ds_read_b128 v[82:85], v236 offset:49152
	ds_read_b128 v[98:101], v236 offset:50176
	ds_read_b128 v[102:105], v236 offset:51200
	ds_read_b128 v[106:109], v236 offset:52224
	ds_read_b128 v[110:113], v236 offset:53248
	ds_read_b128 v[214:217], v236 offset:54272
	ds_read_b128 v[218:221], v236 offset:55296
	ds_read_b128 v[222:225], v236 offset:56320
	global_load_lds_dwordx4 v[42:43], off
	s_add_i32 m0, s8, 0x2000
	s_add_u32 s6, s6, 0x80080
	v_lshl_add_u64 v[42:43], v[244:245], 0, s[24:25]
	s_addc_u32 s7, s7, 0
	s_add_i32 s8, s82, s41
	global_load_lds_dwordx4 v[42:43], off
	v_lshl_add_u64 v[42:43], s[6:7], 0, v[196:197]
	s_mov_b32 m0, s8
	s_nop 0
	global_load_lds_dwordx4 v[42:43], off
	v_lshl_add_u64 v[42:43], s[6:7], 0, v[198:199]
	s_add_i32 m0, s8, 0x2000
	s_nop 0
	global_load_lds_dwordx4 v[42:43], off
	v_lshl_add_u64 v[42:43], v[246:247], 0, s[24:25]
	s_mov_b32 m0, s63
	s_nop 0
	global_load_lds_dwordx4 v[42:43], off
	v_lshl_add_u64 v[42:43], v[248:249], 0, s[24:25]
	s_mov_b32 m0, s64
	s_nop 0
	global_load_lds_dwordx4 v[42:43], off
	s_waitcnt vmcnt(8)
	s_waitcnt lgkmcnt(0)
	s_barrier
	v_mfma_i32_16x16x64_i8 v[42:45], v[26:29], v[82:85], v[94:97]
	v_mfma_i32_16x16x64_i8 v[94:97], v[30:33], v[98:101], v[42:45]
	v_mfma_i32_16x16x64_i8 v[42:45], v[34:37], v[82:85], v[90:93]
	v_mfma_i32_16x16x64_i8 v[90:93], v[38:41], v[98:101], v[42:45]
	v_mfma_i32_16x16x64_i8 v[42:45], v[26:29], v[102:105], v[78:81]
	v_mfma_i32_16x16x64_i8 v[78:81], v[30:33], v[106:109], v[42:45]
	v_mfma_i32_16x16x64_i8 v[42:45], v[34:37], v[102:105], v[74:77]
	v_mfma_i32_16x16x64_i8 v[74:77], v[38:41], v[106:109], v[42:45]
	v_mfma_i32_16x16x64_i8 v[42:45], v[26:29], v[110:113], v[62:65]
	v_mfma_i32_16x16x64_i8 v[62:65], v[30:33], v[214:217], v[42:45]
	v_mfma_i32_16x16x64_i8 v[2:5], v[26:29], v[218:221], v[2:5]
	v_mfma_i32_16x16x64_i8 v[46:49], v[30:33], v[222:225], v[2:5]
	v_mfma_i32_16x16x64_i8 v[42:45], v[34:37], v[110:113], v[58:61]
	v_mfma_i32_16x16x64_i8 v[58:61], v[38:41], v[214:217], v[42:45]
	v_mfma_i32_16x16x64_i8 v[2:5], v[34:37], v[218:221], v[6:9]
	v_mfma_i32_16x16x64_i8 v[42:45], v[38:41], v[222:225], v[2:5]
	v_mfma_i32_16x16x64_i8 v[2:5], v[178:181], v[82:85], v[10:13]
	v_mfma_i32_16x16x64_i8 v[86:89], v[182:185], v[98:101], v[2:5]
	v_mfma_i32_16x16x64_i8 v[2:5], v[186:189], v[82:85], v[14:17]
	v_mfma_i32_16x16x64_i8 v[82:85], v[190:193], v[98:101], v[2:5]
	v_mfma_i32_16x16x64_i8 v[2:5], v[178:181], v[102:105], v[70:73]
	v_mfma_i32_16x16x64_i8 v[70:73], v[182:185], v[106:109], v[2:5]
	v_mfma_i32_16x16x64_i8 v[2:5], v[186:189], v[102:105], v[66:69]
	v_mfma_i32_16x16x64_i8 v[66:69], v[190:193], v[106:109], v[2:5]
	v_mfma_i32_16x16x64_i8 v[2:5], v[178:181], v[110:113], v[54:57]
	v_mfma_i32_16x16x64_i8 v[54:57], v[182:185], v[214:217], v[2:5]
	v_mfma_i32_16x16x64_i8 v[2:5], v[186:189], v[110:113], v[50:53]
	v_mfma_i32_16x16x64_i8 v[50:53], v[190:193], v[214:217], v[2:5]
	v_mfma_i32_16x16x64_i8 v[2:5], v[178:181], v[218:221], v[18:21]
	v_mfma_i32_16x16x64_i8 v[38:41], v[182:185], v[222:225], v[2:5]
	v_mfma_i32_16x16x64_i8 v[2:5], v[186:189], v[218:221], v[22:25]
	v_mfma_i32_16x16x64_i8 v[34:37], v[190:193], v[222:225], v[2:5]
	s_barrier
	s_add_i32 s80, s80, 2
	s_add_u32 s4, s4, 0x100
	s_addc_u32 s5, s5, 0
	s_add_u32 s78, s78, 0x100
	s_addc_u32 s79, s79, 0
	s_cmp_gt_u32 s80, 29
	s_cbranch_scc0 .LBB0_304
	s_and_b64 vcc, exec, s[12:13]
	s_cbranch_vccz .LBB0_307
	s_barrier

.LBB0_1231:
	s_ashr_i32 s23, s22, 31
	s_lshl_b64 s[24:25], s[22:23], 20
	s_add_u32 s24, s17, s24
	s_addc_u32 s25, s36, s25
	s_and_b64 s[26:27], s[0:1], exec
	s_cselect_b32 s23, s25, s29
	s_cselect_b32 s66, s24, s28
	s_ashr_i32 s15, s14, 31
	s_lshl_b64 s[26:27], s[14:15], 20
	s_add_u32 s26, s37, s26
	s_addc_u32 s27, s38, s27
	s_and_b64 s[34:35], s[0:1], exec
	s_cselect_b32 s15, s27, s31
	s_cselect_b32 s67, s26, s30
	s_add_u32 s28, s28, 0x80080
	s_addc_u32 s29, s29, 0
	s_add_u32 s68, s30, 0x100
	s_addc_u32 s69, s31, 0
	s_mov_b32 s70, -2
	ds_read_b128 v[106:109], v197
	ds_read_b128 v[114:117], v197 offset:1024
	ds_read_b128 v[122:125], v197 offset:2048
	ds_read_b128 v[130:133], v197 offset:3072
	ds_read_b128 v[146:149], v201
	ds_read_b128 v[150:153], v201 offset:1024
	ds_read_b128 v[154:157], v201 offset:2048
	ds_read_b128 v[158:161], v201 offset:3072
	s_add_u32 s30, s28, 0xfff80080
	s_addc_u32 s31, s29, -1
	s_cmp_eq_u32 s70, 28
	s_cselect_b32 s35, s23, s31
	s_cselect_b32 s34, s66, s30
	s_cselect_b32 s31, s15, s69
	s_cselect_b32 s30, s67, s68
	v_lshl_add_u64 v[194:195], s[28:29], 0, v[174:175]
	s_add_i32 m0, s19, 0xc000
	ds_read_b128 v[162:165], v204
	ds_read_b128 v[182:185], v204 offset:1024
	ds_read_b128 v[186:189], v204 offset:2048
	ds_read_b128 v[206:209], v204 offset:3072
	ds_read_b128 v[210:213], v204 offset:4096
	ds_read_b128 v[214:217], v204 offset:5120
	ds_read_b128 v[218:221], v204 offset:6144
	ds_read_b128 v[222:225], v204 offset:7168
	global_load_lds_dwordx4 v[194:195], off
	v_lshl_add_u64 v[194:195], s[28:29], 0, v[176:177]
	s_add_i32 m0, s19, 0xe000
	s_nop 0
	global_load_lds_dwordx4 v[194:195], off
	s_waitcnt vmcnt(8)
	s_waitcnt lgkmcnt(0)
	s_barrier
	v_mfma_i32_16x16x64_i8 v[142:145], v[106:109], v[162:165], 0
	v_mfma_i32_16x16x64_i8 v[142:145], v[114:117], v[182:185], v[142:145]
	v_mfma_i32_16x16x64_i8 v[138:141], v[122:125], v[162:165], 0
	v_mfma_i32_16x16x64_i8 v[138:141], v[130:133], v[182:185], v[138:141]
	v_mfma_i32_16x16x64_i8 v[118:121], v[106:109], v[186:189], 0
	v_mfma_i32_16x16x64_i8 v[118:121], v[114:117], v[206:209], v[118:121]
	v_mfma_i32_16x16x64_i8 v[110:113], v[122:125], v[186:189], 0
	v_mfma_i32_16x16x64_i8 v[110:113], v[130:133], v[206:209], v[110:113]
	v_mfma_i32_16x16x64_i8 v[94:97], v[106:109], v[210:213], 0
	v_mfma_i32_16x16x64_i8 v[94:97], v[114:117], v[214:217], v[94:97]
	v_mfma_i32_16x16x64_i8 v[90:93], v[122:125], v[210:213], 0
	v_mfma_i32_16x16x64_i8 v[90:93], v[130:133], v[214:217], v[90:93]
	v_mfma_i32_16x16x64_i8 v[78:81], v[106:109], v[218:221], 0
	v_mfma_i32_16x16x64_i8 v[78:81], v[114:117], v[222:225], v[78:81]
	v_mfma_i32_16x16x64_i8 v[74:77], v[122:125], v[218:221], 0
	v_mfma_i32_16x16x64_i8 v[74:77], v[130:133], v[222:225], v[74:77]
	v_mfma_i32_16x16x64_i8 v[134:137], v[146:149], v[162:165], 0
	v_mfma_i32_16x16x64_i8 v[134:137], v[150:153], v[182:185], v[134:137]
	v_mfma_i32_16x16x64_i8 v[126:129], v[154:157], v[162:165], 0
	v_mfma_i32_16x16x64_i8 v[126:129], v[158:161], v[182:185], v[126:129]
	v_mfma_i32_16x16x64_i8 v[102:105], v[146:149], v[186:189], 0
	v_mfma_i32_16x16x64_i8 v[102:105], v[150:153], v[206:209], v[102:105]
	v_mfma_i32_16x16x64_i8 v[98:101], v[154:157], v[186:189], 0
	v_mfma_i32_16x16x64_i8 v[98:101], v[158:161], v[206:209], v[98:101]
	v_mfma_i32_16x16x64_i8 v[86:89], v[146:149], v[210:213], 0
	v_mfma_i32_16x16x64_i8 v[86:89], v[150:153], v[214:217], v[86:89]
	v_mfma_i32_16x16x64_i8 v[82:85], v[154:157], v[210:213], 0
	v_mfma_i32_16x16x64_i8 v[82:85], v[158:161], v[214:217], v[82:85]
	v_mfma_i32_16x16x64_i8 v[70:73], v[146:149], v[218:221], 0
	v_mfma_i32_16x16x64_i8 v[70:73], v[150:153], v[222:225], v[70:73]
	v_mfma_i32_16x16x64_i8 v[66:69], v[154:157], v[218:221], 0
	v_mfma_i32_16x16x64_i8 v[66:69], v[158:161], v[222:225], v[66:69]
	s_barrier
	s_add_i32 s71, s63, s39
	v_lshl_add_u64 v[194:195], s[30:31], 0, v[168:169]
	s_mov_b32 m0, s71
	ds_read_b128 v[162:165], v204 offset:16384
	ds_read_b128 v[182:185], v204 offset:17408
	ds_read_b128 v[186:189], v204 offset:18432
	ds_read_b128 v[206:209], v204 offset:19456
	ds_read_b128 v[210:213], v204 offset:20480
	ds_read_b128 v[214:217], v204 offset:21504
	ds_read_b128 v[218:221], v204 offset:22528
	ds_read_b128 v[222:225], v204 offset:23552
	global_load_lds_dwordx4 v[194:195], off
	s_add_i32 m0, s71, 0x2000
	s_add_u32 s72, s30, 0x80000
	v_lshl_add_u64 v[198:199], s[30:31], 0, v[172:173]
	s_addc_u32 s73, s31, 0
	s_add_i32 s71, s64, s39
	global_load_lds_dwordx4 v[198:199], off
	v_lshl_add_u64 v[202:203], s[72:73], 0, v[168:169]
	s_mov_b32 m0, s71
	v_lshl_add_u64 v[226:227], s[34:35], 0, v[170:171]
	global_load_lds_dwordx4 v[202:203], off
	v_lshl_add_u64 v[202:203], s[72:73], 0, v[172:173]
	s_add_i32 m0, s71, 0x2000
	s_nop 0
	global_load_lds_dwordx4 v[202:203], off
	v_lshl_add_u64 v[202:203], s[34:35], 0, v[166:167]
	s_mov_b32 m0, s19
	s_nop 0
	global_load_lds_dwordx4 v[202:203], off
	s_mov_b32 m0, s40
	s_nop 0
	global_load_lds_dwordx4 v[226:227], off
	s_waitcnt vmcnt(8)
	s_waitcnt lgkmcnt(0)
	s_barrier
	v_mfma_i32_16x16x64_i8 v[62:65], v[106:109], v[162:165], 0
	v_mfma_i32_16x16x64_i8 v[62:65], v[114:117], v[182:185], v[62:65]
	v_mfma_i32_16x16x64_i8 v[58:61], v[122:125], v[162:165], 0
	v_mfma_i32_16x16x64_i8 v[58:61], v[130:133], v[182:185], v[58:61]
	v_mfma_i32_16x16x64_i8 v[46:49], v[106:109], v[186:189], 0
	v_mfma_i32_16x16x64_i8 v[46:49], v[114:117], v[206:209], v[46:49]
	v_mfma_i32_16x16x64_i8 v[42:45], v[122:125], v[186:189], 0
	v_mfma_i32_16x16x64_i8 v[42:45], v[130:133], v[206:209], v[42:45]
	v_mfma_i32_16x16x64_i8 v[30:33], v[106:109], v[210:213], 0
	v_mfma_i32_16x16x64_i8 v[30:33], v[114:117], v[214:217], v[30:33]
	v_mfma_i32_16x16x64_i8 v[26:29], v[122:125], v[210:213], 0
	v_mfma_i32_16x16x64_i8 v[26:29], v[130:133], v[214:217], v[26:29]
	v_mfma_i32_16x16x64_i8 v[14:17], v[106:109], v[218:221], 0
	v_mfma_i32_16x16x64_i8 v[14:17], v[114:117], v[222:225], v[14:17]
	v_mfma_i32_16x16x64_i8 v[10:13], v[122:125], v[218:221], 0
	v_mfma_i32_16x16x64_i8 v[10:13], v[130:133], v[222:225], v[10:13]
	v_mfma_i32_16x16x64_i8 v[54:57], v[146:149], v[162:165], 0
	v_mfma_i32_16x16x64_i8 v[54:57], v[150:153], v[182:185], v[54:57]
	v_mfma_i32_16x16x64_i8 v[50:53], v[154:157], v[162:165], 0
	v_mfma_i32_16x16x64_i8 v[50:53], v[158:161], v[182:185], v[50:53]
	v_mfma_i32_16x16x64_i8 v[38:41], v[146:149], v[186:189], 0
	v_mfma_i32_16x16x64_i8 v[38:41], v[150:153], v[206:209], v[38:41]
	v_mfma_i32_16x16x64_i8 v[34:37], v[154:157], v[186:189], 0
	v_mfma_i32_16x16x64_i8 v[34:37], v[158:161], v[206:209], v[34:37]
	v_mfma_i32_16x16x64_i8 v[22:25], v[146:149], v[210:213], 0
	v_mfma_i32_16x16x64_i8 v[22:25], v[150:153], v[214:217], v[22:25]
	v_mfma_i32_16x16x64_i8 v[18:21], v[154:157], v[210:213], 0
	v_mfma_i32_16x16x64_i8 v[18:21], v[158:161], v[214:217], v[18:21]
	v_mfma_i32_16x16x64_i8 v[6:9], v[146:149], v[218:221], 0
	v_mfma_i32_16x16x64_i8 v[6:9], v[150:153], v[222:225], v[6:9]
	v_mfma_i32_16x16x64_i8 v[2:5], v[154:157], v[218:221], 0
	v_mfma_i32_16x16x64_i8 v[2:5], v[158:161], v[222:225], v[2:5]
	s_barrier
	s_add_i32 s71, 0, 0x18000
	s_add_i32 s72, 0, 0x1c000
	v_add_u32_e32 v130, s71, v193
	v_add_u32_e32 v158, s72, v193
	ds_read_b128 v[106:109], v130
	ds_read_b128 v[114:117], v130 offset:1024
	ds_read_b128 v[122:125], v130 offset:2048
	ds_read_b128 v[130:133], v130 offset:3072
	ds_read_b128 v[146:149], v158
	ds_read_b128 v[150:153], v158 offset:1024
	ds_read_b128 v[154:157], v158 offset:2048
	ds_read_b128 v[158:161], v158 offset:3072
	s_add_u32 s34, s34, 0x80000
	s_addc_u32 s35, s35, 0
	s_mov_b32 m0, s41
	v_lshl_add_u64 v[228:229], s[34:35], 0, v[166:167]
	ds_read_b128 v[162:165], v204 offset:32768
	ds_read_b128 v[182:185], v204 offset:33792
	ds_read_b128 v[186:189], v204 offset:34816
	ds_read_b128 v[206:209], v204 offset:35840
	ds_read_b128 v[210:213], v204 offset:36864
	ds_read_b128 v[214:217], v204 offset:37888
	ds_read_b128 v[218:221], v204 offset:38912
	ds_read_b128 v[222:225], v204 offset:39936
	global_load_lds_dwordx4 v[228:229], off
	v_lshl_add_u64 v[228:229], s[34:35], 0, v[170:171]
	s_mov_b32 m0, s42
	s_nop 0
	global_load_lds_dwordx4 v[228:229], off
	s_waitcnt vmcnt(8)
	s_waitcnt lgkmcnt(0)
	s_barrier
	v_mfma_i32_16x16x64_i8 v[142:145], v[106:109], v[162:165], v[142:145]
	v_mfma_i32_16x16x64_i8 v[142:145], v[114:117], v[182:185], v[142:145]
	v_mfma_i32_16x16x64_i8 v[138:141], v[122:125], v[162:165], v[138:141]
	v_mfma_i32_16x16x64_i8 v[138:141], v[130:133], v[182:185], v[138:141]
	v_mfma_i32_16x16x64_i8 v[118:121], v[106:109], v[186:189], v[118:121]
	v_mfma_i32_16x16x64_i8 v[118:121], v[114:117], v[206:209], v[118:121]
	v_mfma_i32_16x16x64_i8 v[110:113], v[122:125], v[186:189], v[110:113]
	v_mfma_i32_16x16x64_i8 v[110:113], v[130:133], v[206:209], v[110:113]
	v_mfma_i32_16x16x64_i8 v[94:97], v[106:109], v[210:213], v[94:97]
	v_mfma_i32_16x16x64_i8 v[94:97], v[114:117], v[214:217], v[94:97]
	v_mfma_i32_16x16x64_i8 v[90:93], v[122:125], v[210:213], v[90:93]
	v_mfma_i32_16x16x64_i8 v[90:93], v[130:133], v[214:217], v[90:93]
	v_mfma_i32_16x16x64_i8 v[78:81], v[106:109], v[218:221], v[78:81]
	v_mfma_i32_16x16x64_i8 v[78:81], v[114:117], v[222:225], v[78:81]
	v_mfma_i32_16x16x64_i8 v[74:77], v[122:125], v[218:221], v[74:77]
	v_mfma_i32_16x16x64_i8 v[74:77], v[130:133], v[222:225], v[74:77]
	v_mfma_i32_16x16x64_i8 v[134:137], v[146:149], v[162:165], v[134:137]
	v_mfma_i32_16x16x64_i8 v[134:137], v[150:153], v[182:185], v[134:137]
	v_mfma_i32_16x16x64_i8 v[126:129], v[154:157], v[162:165], v[126:129]
	v_mfma_i32_16x16x64_i8 v[126:129], v[158:161], v[182:185], v[126:129]
	v_mfma_i32_16x16x64_i8 v[102:105], v[146:149], v[186:189], v[102:105]
	v_mfma_i32_16x16x64_i8 v[102:105], v[150:153], v[206:209], v[102:105]
	v_mfma_i32_16x16x64_i8 v[98:101], v[154:157], v[186:189], v[98:101]
	v_mfma_i32_16x16x64_i8 v[98:101], v[158:161], v[206:209], v[98:101]
	v_mfma_i32_16x16x64_i8 v[86:89], v[146:149], v[210:213], v[86:89]
	v_mfma_i32_16x16x64_i8 v[86:89], v[150:153], v[214:217], v[86:89]
	v_mfma_i32_16x16x64_i8 v[82:85], v[154:157], v[210:213], v[82:85]
	v_mfma_i32_16x16x64_i8 v[82:85], v[158:161], v[214:217], v[82:85]
	v_mfma_i32_16x16x64_i8 v[70:73], v[146:149], v[218:221], v[70:73]
	v_mfma_i32_16x16x64_i8 v[70:73], v[150:153], v[222:225], v[70:73]
	v_mfma_i32_16x16x64_i8 v[66:69], v[154:157], v[218:221], v[66:69]
	v_mfma_i32_16x16x64_i8 v[66:69], v[158:161], v[222:225], v[66:69]
	s_barrier
	s_add_i32 s34, s71, s39
	v_lshl_add_u64 v[194:195], v[194:195], 0, s[10:11]
	s_mov_b32 m0, s34
	ds_read_b128 v[162:165], v204 offset:49152
	ds_read_b128 v[182:185], v204 offset:50176
	ds_read_b128 v[186:189], v204 offset:51200
	ds_read_b128 v[206:209], v204 offset:52224
	ds_read_b128 v[210:213], v204 offset:53248
	ds_read_b128 v[214:217], v204 offset:54272
	ds_read_b128 v[218:221], v204 offset:55296
	ds_read_b128 v[222:225], v204 offset:56320
	global_load_lds_dwordx4 v[194:195], off
	s_add_i32 m0, s34, 0x2000
	s_add_u32 s30, s30, 0x80080
	v_lshl_add_u64 v[194:195], v[198:199], 0, s[10:11]
	s_addc_u32 s31, s31, 0
	s_add_i32 s34, s72, s39
	global_load_lds_dwordx4 v[194:195], off
	v_lshl_add_u64 v[194:195], s[30:31], 0, v[168:169]
	s_mov_b32 m0, s34
	s_nop 0
	global_load_lds_dwordx4 v[194:195], off
	v_lshl_add_u64 v[194:195], s[30:31], 0, v[172:173]
	s_add_i32 m0, s34, 0x2000
	s_nop 0
	global_load_lds_dwordx4 v[194:195], off
	v_lshl_add_u64 v[194:195], v[202:203], 0, s[10:11]
	s_mov_b32 m0, s60
	s_nop 0
	global_load_lds_dwordx4 v[194:195], off
	v_lshl_add_u64 v[194:195], v[226:227], 0, s[10:11]
	s_mov_b32 m0, s61
	s_nop 0
	global_load_lds_dwordx4 v[194:195], off
	s_waitcnt vmcnt(8)
	s_waitcnt lgkmcnt(0)
	s_barrier
	v_mfma_i32_16x16x64_i8 v[62:65], v[106:109], v[162:165], v[62:65]
	v_mfma_i32_16x16x64_i8 v[62:65], v[114:117], v[182:185], v[62:65]
	v_mfma_i32_16x16x64_i8 v[58:61], v[122:125], v[162:165], v[58:61]
	v_mfma_i32_16x16x64_i8 v[58:61], v[130:133], v[182:185], v[58:61]
	v_mfma_i32_16x16x64_i8 v[46:49], v[106:109], v[186:189], v[46:49]
	v_mfma_i32_16x16x64_i8 v[46:49], v[114:117], v[206:209], v[46:49]
	v_mfma_i32_16x16x64_i8 v[42:45], v[122:125], v[186:189], v[42:45]
	v_mfma_i32_16x16x64_i8 v[42:45], v[130:133], v[206:209], v[42:45]
	v_mfma_i32_16x16x64_i8 v[30:33], v[106:109], v[210:213], v[30:33]
	v_mfma_i32_16x16x64_i8 v[30:33], v[114:117], v[214:217], v[30:33]
	v_mfma_i32_16x16x64_i8 v[26:29], v[122:125], v[210:213], v[26:29]
	v_mfma_i32_16x16x64_i8 v[26:29], v[130:133], v[214:217], v[26:29]
	v_mfma_i32_16x16x64_i8 v[14:17], v[106:109], v[218:221], v[14:17]
	v_mfma_i32_16x16x64_i8 v[14:17], v[114:117], v[222:225], v[14:17]
	v_mfma_i32_16x16x64_i8 v[10:13], v[122:125], v[218:221], v[10:13]
	v_mfma_i32_16x16x64_i8 v[10:13], v[130:133], v[222:225], v[10:13]
	v_mfma_i32_16x16x64_i8 v[54:57], v[146:149], v[162:165], v[54:57]
	v_mfma_i32_16x16x64_i8 v[54:57], v[150:153], v[182:185], v[54:57]
	v_mfma_i32_16x16x64_i8 v[50:53], v[154:157], v[162:165], v[50:53]
	v_mfma_i32_16x16x64_i8 v[50:53], v[158:161], v[182:185], v[50:53]
	v_mfma_i32_16x16x64_i8 v[38:41], v[146:149], v[186:189], v[38:41]
	v_mfma_i32_16x16x64_i8 v[38:41], v[150:153], v[206:209], v[38:41]
	v_mfma_i32_16x16x64_i8 v[34:37], v[154:157], v[186:189], v[34:37]
	v_mfma_i32_16x16x64_i8 v[34:37], v[158:161], v[206:209], v[34:37]
	v_mfma_i32_16x16x64_i8 v[22:25], v[146:149], v[210:213], v[22:25]
	v_mfma_i32_16x16x64_i8 v[22:25], v[150:153], v[214:217], v[22:25]
	v_mfma_i32_16x16x64_i8 v[18:21], v[154:157], v[210:213], v[18:21]
	v_mfma_i32_16x16x64_i8 v[18:21], v[158:161], v[214:217], v[18:21]
	v_mfma_i32_16x16x64_i8 v[6:9], v[146:149], v[218:221], v[6:9]
	v_mfma_i32_16x16x64_i8 v[6:9], v[150:153], v[222:225], v[6:9]
	v_mfma_i32_16x16x64_i8 v[2:5], v[154:157], v[218:221], v[2:5]
	v_mfma_i32_16x16x64_i8 v[2:5], v[158:161], v[222:225], v[2:5]
	s_barrier
	s_add_i32 s70, s70, 2
	s_add_u32 s28, s28, 0x100
	s_addc_u32 s29, s29, 0
	s_add_u32 s68, s68, 0x100
	s_addc_u32 s69, s69, 0
	s_cmp_gt_u32 s70, 29
.LBB0_1232:
	ds_read_b128 v[106:109], v197
	ds_read_b128 v[114:117], v197 offset:1024
	ds_read_b128 v[122:125], v197 offset:2048
	ds_read_b128 v[130:133], v197 offset:3072
	ds_read_b128 v[146:149], v201
	ds_read_b128 v[150:153], v201 offset:1024
	ds_read_b128 v[154:157], v201 offset:2048
	ds_read_b128 v[158:161], v201 offset:3072
	s_add_u32 s30, s28, 0xfff80080
	s_addc_u32 s31, s29, -1
	s_cmp_eq_u32 s70, 28
	s_cselect_b32 s35, s23, s31
	s_cselect_b32 s34, s66, s30
	s_cselect_b32 s31, s15, s69
	s_cselect_b32 s30, s67, s68
	v_lshl_add_u64 v[194:195], s[28:29], 0, v[174:175]
	s_add_i32 m0, s19, 0xc000
	ds_read_b128 v[162:165], v204
	ds_read_b128 v[182:185], v204 offset:1024
	ds_read_b128 v[186:189], v204 offset:2048
	ds_read_b128 v[206:209], v204 offset:3072
	ds_read_b128 v[210:213], v204 offset:4096
	ds_read_b128 v[214:217], v204 offset:5120
	ds_read_b128 v[218:221], v204 offset:6144
	ds_read_b128 v[222:225], v204 offset:7168
	global_load_lds_dwordx4 v[194:195], off
	v_lshl_add_u64 v[194:195], s[28:29], 0, v[176:177]
	s_add_i32 m0, s19, 0xe000
	s_nop 0
	global_load_lds_dwordx4 v[194:195], off
	s_waitcnt vmcnt(8)
	s_waitcnt lgkmcnt(0)
	s_barrier
	v_mfma_i32_16x16x64_i8 v[142:145], v[106:109], v[162:165], v[142:145]
	v_mfma_i32_16x16x64_i8 v[142:145], v[114:117], v[182:185], v[142:145]
	v_mfma_i32_16x16x64_i8 v[138:141], v[122:125], v[162:165], v[138:141]
	v_mfma_i32_16x16x64_i8 v[138:141], v[130:133], v[182:185], v[138:141]
	v_mfma_i32_16x16x64_i8 v[118:121], v[106:109], v[186:189], v[118:121]
	v_mfma_i32_16x16x64_i8 v[118:121], v[114:117], v[206:209], v[118:121]
	v_mfma_i32_16x16x64_i8 v[110:113], v[122:125], v[186:189], v[110:113]
	v_mfma_i32_16x16x64_i8 v[110:113], v[130:133], v[206:209], v[110:113]
	v_mfma_i32_16x16x64_i8 v[94:97], v[106:109], v[210:213], v[94:97]
	v_mfma_i32_16x16x64_i8 v[94:97], v[114:117], v[214:217], v[94:97]
	v_mfma_i32_16x16x64_i8 v[90:93], v[122:125], v[210:213], v[90:93]
	v_mfma_i32_16x16x64_i8 v[90:93], v[130:133], v[214:217], v[90:93]
	v_mfma_i32_16x16x64_i8 v[78:81], v[106:109], v[218:221], v[78:81]
	v_mfma_i32_16x16x64_i8 v[78:81], v[114:117], v[222:225], v[78:81]
	v_mfma_i32_16x16x64_i8 v[74:77], v[122:125], v[218:221], v[74:77]
	v_mfma_i32_16x16x64_i8 v[74:77], v[130:133], v[222:225], v[74:77]
	v_mfma_i32_16x16x64_i8 v[134:137], v[146:149], v[162:165], v[134:137]
	v_mfma_i32_16x16x64_i8 v[134:137], v[150:153], v[182:185], v[134:137]
	v_mfma_i32_16x16x64_i8 v[126:129], v[154:157], v[162:165], v[126:129]
	v_mfma_i32_16x16x64_i8 v[126:129], v[158:161], v[182:185], v[126:129]
	v_mfma_i32_16x16x64_i8 v[102:105], v[146:149], v[186:189], v[102:105]
	v_mfma_i32_16x16x64_i8 v[102:105], v[150:153], v[206:209], v[102:105]
	v_mfma_i32_16x16x64_i8 v[98:101], v[154:157], v[186:189], v[98:101]
	v_mfma_i32_16x16x64_i8 v[98:101], v[158:161], v[206:209], v[98:101]
	v_mfma_i32_16x16x64_i8 v[86:89], v[146:149], v[210:213], v[86:89]
	v_mfma_i32_16x16x64_i8 v[86:89], v[150:153], v[214:217], v[86:89]
	v_mfma_i32_16x16x64_i8 v[82:85], v[154:157], v[210:213], v[82:85]
	v_mfma_i32_16x16x64_i8 v[82:85], v[158:161], v[214:217], v[82:85]
	v_mfma_i32_16x16x64_i8 v[70:73], v[146:149], v[218:221], v[70:73]
	v_mfma_i32_16x16x64_i8 v[70:73], v[150:153], v[222:225], v[70:73]
	v_mfma_i32_16x16x64_i8 v[66:69], v[154:157], v[218:221], v[66:69]
	v_mfma_i32_16x16x64_i8 v[66:69], v[158:161], v[222:225], v[66:69]
	s_barrier
	s_add_i32 s71, s63, s39
	v_lshl_add_u64 v[194:195], s[30:31], 0, v[168:169]
	s_mov_b32 m0, s71
	ds_read_b128 v[162:165], v204 offset:16384
	ds_read_b128 v[182:185], v204 offset:17408
	ds_read_b128 v[186:189], v204 offset:18432
	ds_read_b128 v[206:209], v204 offset:19456
	ds_read_b128 v[210:213], v204 offset:20480
	ds_read_b128 v[214:217], v204 offset:21504
	ds_read_b128 v[218:221], v204 offset:22528
	ds_read_b128 v[222:225], v204 offset:23552
	global_load_lds_dwordx4 v[194:195], off
	s_add_i32 m0, s71, 0x2000
	s_add_u32 s72, s30, 0x80000
	v_lshl_add_u64 v[198:199], s[30:31], 0, v[172:173]
	s_addc_u32 s73, s31, 0
	s_add_i32 s71, s64, s39
	global_load_lds_dwordx4 v[198:199], off
	v_lshl_add_u64 v[202:203], s[72:73], 0, v[168:169]
	s_mov_b32 m0, s71
	v_lshl_add_u64 v[226:227], s[34:35], 0, v[170:171]
	global_load_lds_dwordx4 v[202:203], off
	v_lshl_add_u64 v[202:203], s[72:73], 0, v[172:173]
	s_add_i32 m0, s71, 0x2000
	s_nop 0
	global_load_lds_dwordx4 v[202:203], off
	v_lshl_add_u64 v[202:203], s[34:35], 0, v[166:167]
	s_mov_b32 m0, s19
	s_nop 0
	global_load_lds_dwordx4 v[202:203], off
	s_mov_b32 m0, s40
	s_nop 0
	global_load_lds_dwordx4 v[226:227], off
	s_waitcnt vmcnt(8)
	s_waitcnt lgkmcnt(0)
	s_barrier
	v_mfma_i32_16x16x64_i8 v[62:65], v[106:109], v[162:165], v[62:65]
	v_mfma_i32_16x16x64_i8 v[62:65], v[114:117], v[182:185], v[62:65]
	v_mfma_i32_16x16x64_i8 v[58:61], v[122:125], v[162:165], v[58:61]
	v_mfma_i32_16x16x64_i8 v[58:61], v[130:133], v[182:185], v[58:61]
	v_mfma_i32_16x16x64_i8 v[46:49], v[106:109], v[186:189], v[46:49]
	v_mfma_i32_16x16x64_i8 v[46:49], v[114:117], v[206:209], v[46:49]
	v_mfma_i32_16x16x64_i8 v[42:45], v[122:125], v[186:189], v[42:45]
	v_mfma_i32_16x16x64_i8 v[42:45], v[130:133], v[206:209], v[42:45]
	v_mfma_i32_16x16x64_i8 v[30:33], v[106:109], v[210:213], v[30:33]
	v_mfma_i32_16x16x64_i8 v[30:33], v[114:117], v[214:217], v[30:33]
	v_mfma_i32_16x16x64_i8 v[26:29], v[122:125], v[210:213], v[26:29]
	v_mfma_i32_16x16x64_i8 v[26:29], v[130:133], v[214:217], v[26:29]
	v_mfma_i32_16x16x64_i8 v[14:17], v[106:109], v[218:221], v[14:17]
	v_mfma_i32_16x16x64_i8 v[14:17], v[114:117], v[222:225], v[14:17]
	v_mfma_i32_16x16x64_i8 v[10:13], v[122:125], v[218:221], v[10:13]
	v_mfma_i32_16x16x64_i8 v[10:13], v[130:133], v[222:225], v[10:13]
	v_mfma_i32_16x16x64_i8 v[54:57], v[146:149], v[162:165], v[54:57]
	v_mfma_i32_16x16x64_i8 v[54:57], v[150:153], v[182:185], v[54:57]
	v_mfma_i32_16x16x64_i8 v[50:53], v[154:157], v[162:165], v[50:53]
	v_mfma_i32_16x16x64_i8 v[50:53], v[158:161], v[182:185], v[50:53]
	v_mfma_i32_16x16x64_i8 v[38:41], v[146:149], v[186:189], v[38:41]
	v_mfma_i32_16x16x64_i8 v[38:41], v[150:153], v[206:209], v[38:41]
	v_mfma_i32_16x16x64_i8 v[34:37], v[154:157], v[186:189], v[34:37]
	v_mfma_i32_16x16x64_i8 v[34:37], v[158:161], v[206:209], v[34:37]
	v_mfma_i32_16x16x64_i8 v[22:25], v[146:149], v[210:213], v[22:25]
	v_mfma_i32_16x16x64_i8 v[22:25], v[150:153], v[214:217], v[22:25]
	v_mfma_i32_16x16x64_i8 v[18:21], v[154:157], v[210:213], v[18:21]
	v_mfma_i32_16x16x64_i8 v[18:21], v[158:161], v[214:217], v[18:21]
	v_mfma_i32_16x16x64_i8 v[6:9], v[146:149], v[218:221], v[6:9]
	v_mfma_i32_16x16x64_i8 v[6:9], v[150:153], v[222:225], v[6:9]
	v_mfma_i32_16x16x64_i8 v[2:5], v[154:157], v[218:221], v[2:5]
	v_mfma_i32_16x16x64_i8 v[2:5], v[158:161], v[222:225], v[2:5]
	s_barrier
	s_add_i32 s71, 0, 0x18000
	s_add_i32 s72, 0, 0x1c000
	v_add_u32_e32 v130, s71, v193
	v_add_u32_e32 v158, s72, v193
	ds_read_b128 v[106:109], v130
	ds_read_b128 v[114:117], v130 offset:1024
	ds_read_b128 v[122:125], v130 offset:2048
	ds_read_b128 v[130:133], v130 offset:3072
	ds_read_b128 v[146:149], v158
	ds_read_b128 v[150:153], v158 offset:1024
	ds_read_b128 v[154:157], v158 offset:2048
	ds_read_b128 v[158:161], v158 offset:3072
	s_add_u32 s34, s34, 0x80000
	s_addc_u32 s35, s35, 0
	s_mov_b32 m0, s41
	v_lshl_add_u64 v[228:229], s[34:35], 0, v[166:167]
	ds_read_b128 v[162:165], v204 offset:32768
	ds_read_b128 v[182:185], v204 offset:33792
	ds_read_b128 v[186:189], v204 offset:34816
	ds_read_b128 v[206:209], v204 offset:35840
	ds_read_b128 v[210:213], v204 offset:36864
	ds_read_b128 v[214:217], v204 offset:37888
	ds_read_b128 v[218:221], v204 offset:38912
	ds_read_b128 v[222:225], v204 offset:39936
	global_load_lds_dwordx4 v[228:229], off
	v_lshl_add_u64 v[228:229], s[34:35], 0, v[170:171]
	s_mov_b32 m0, s42
	s_nop 0
	global_load_lds_dwordx4 v[228:229], off
	s_waitcnt vmcnt(8)
	s_waitcnt lgkmcnt(0)
	s_barrier
	v_mfma_i32_16x16x64_i8 v[142:145], v[106:109], v[162:165], v[142:145]
	v_mfma_i32_16x16x64_i8 v[142:145], v[114:117], v[182:185], v[142:145]
	v_mfma_i32_16x16x64_i8 v[138:141], v[122:125], v[162:165], v[138:141]
	v_mfma_i32_16x16x64_i8 v[138:141], v[130:133], v[182:185], v[138:141]
	v_mfma_i32_16x16x64_i8 v[118:121], v[106:109], v[186:189], v[118:121]
	v_mfma_i32_16x16x64_i8 v[118:121], v[114:117], v[206:209], v[118:121]
	v_mfma_i32_16x16x64_i8 v[110:113], v[122:125], v[186:189], v[110:113]
	v_mfma_i32_16x16x64_i8 v[110:113], v[130:133], v[206:209], v[110:113]
	v_mfma_i32_16x16x64_i8 v[94:97], v[106:109], v[210:213], v[94:97]
	v_mfma_i32_16x16x64_i8 v[94:97], v[114:117], v[214:217], v[94:97]
	v_mfma_i32_16x16x64_i8 v[90:93], v[122:125], v[210:213], v[90:93]
	v_mfma_i32_16x16x64_i8 v[90:93], v[130:133], v[214:217], v[90:93]
	v_mfma_i32_16x16x64_i8 v[78:81], v[106:109], v[218:221], v[78:81]
	v_mfma_i32_16x16x64_i8 v[78:81], v[114:117], v[222:225], v[78:81]
	v_mfma_i32_16x16x64_i8 v[74:77], v[122:125], v[218:221], v[74:77]
	v_mfma_i32_16x16x64_i8 v[74:77], v[130:133], v[222:225], v[74:77]
	v_mfma_i32_16x16x64_i8 v[134:137], v[146:149], v[162:165], v[134:137]
	v_mfma_i32_16x16x64_i8 v[134:137], v[150:153], v[182:185], v[134:137]
	v_mfma_i32_16x16x64_i8 v[126:129], v[154:157], v[162:165], v[126:129]
	v_mfma_i32_16x16x64_i8 v[126:129], v[158:161], v[182:185], v[126:129]
	v_mfma_i32_16x16x64_i8 v[102:105], v[146:149], v[186:189], v[102:105]
	v_mfma_i32_16x16x64_i8 v[102:105], v[150:153], v[206:209], v[102:105]
	v_mfma_i32_16x16x64_i8 v[98:101], v[154:157], v[186:189], v[98:101]
	v_mfma_i32_16x16x64_i8 v[98:101], v[158:161], v[206:209], v[98:101]
	v_mfma_i32_16x16x64_i8 v[86:89], v[146:149], v[210:213], v[86:89]
	v_mfma_i32_16x16x64_i8 v[86:89], v[150:153], v[214:217], v[86:89]
	v_mfma_i32_16x16x64_i8 v[82:85], v[154:157], v[210:213], v[82:85]
	v_mfma_i32_16x16x64_i8 v[82:85], v[158:161], v[214:217], v[82:85]
	v_mfma_i32_16x16x64_i8 v[70:73], v[146:149], v[218:221], v[70:73]
	v_mfma_i32_16x16x64_i8 v[70:73], v[150:153], v[222:225], v[70:73]
	v_mfma_i32_16x16x64_i8 v[66:69], v[154:157], v[218:221], v[66:69]
	v_mfma_i32_16x16x64_i8 v[66:69], v[158:161], v[222:225], v[66:69]
	s_barrier
	s_add_i32 s34, s71, s39
	v_lshl_add_u64 v[194:195], v[194:195], 0, s[10:11]
	s_mov_b32 m0, s34
	ds_read_b128 v[162:165], v204 offset:49152
	ds_read_b128 v[182:185], v204 offset:50176
	ds_read_b128 v[186:189], v204 offset:51200
	ds_read_b128 v[206:209], v204 offset:52224
	ds_read_b128 v[210:213], v204 offset:53248
	ds_read_b128 v[214:217], v204 offset:54272
	ds_read_b128 v[218:221], v204 offset:55296
	ds_read_b128 v[222:225], v204 offset:56320
	global_load_lds_dwordx4 v[194:195], off
	s_add_i32 m0, s34, 0x2000
	s_add_u32 s30, s30, 0x80080
	v_lshl_add_u64 v[194:195], v[198:199], 0, s[10:11]
	s_addc_u32 s31, s31, 0
	s_add_i32 s34, s72, s39
	global_load_lds_dwordx4 v[194:195], off
	v_lshl_add_u64 v[194:195], s[30:31], 0, v[168:169]
	s_mov_b32 m0, s34
	s_nop 0
	global_load_lds_dwordx4 v[194:195], off
	v_lshl_add_u64 v[194:195], s[30:31], 0, v[172:173]
	s_add_i32 m0, s34, 0x2000
	s_nop 0
	global_load_lds_dwordx4 v[194:195], off
	v_lshl_add_u64 v[194:195], v[202:203], 0, s[10:11]
	s_mov_b32 m0, s60
	s_nop 0
	global_load_lds_dwordx4 v[194:195], off
	v_lshl_add_u64 v[194:195], v[226:227], 0, s[10:11]
	s_mov_b32 m0, s61
	s_nop 0
	global_load_lds_dwordx4 v[194:195], off
	s_waitcnt vmcnt(8)
	s_waitcnt lgkmcnt(0)
	s_barrier
	v_mfma_i32_16x16x64_i8 v[62:65], v[106:109], v[162:165], v[62:65]
	v_mfma_i32_16x16x64_i8 v[62:65], v[114:117], v[182:185], v[62:65]
	v_mfma_i32_16x16x64_i8 v[58:61], v[122:125], v[162:165], v[58:61]
	v_mfma_i32_16x16x64_i8 v[58:61], v[130:133], v[182:185], v[58:61]
	v_mfma_i32_16x16x64_i8 v[46:49], v[106:109], v[186:189], v[46:49]
	v_mfma_i32_16x16x64_i8 v[46:49], v[114:117], v[206:209], v[46:49]
	v_mfma_i32_16x16x64_i8 v[42:45], v[122:125], v[186:189], v[42:45]
	v_mfma_i32_16x16x64_i8 v[42:45], v[130:133], v[206:209], v[42:45]
	v_mfma_i32_16x16x64_i8 v[30:33], v[106:109], v[210:213], v[30:33]
	v_mfma_i32_16x16x64_i8 v[30:33], v[114:117], v[214:217], v[30:33]
	v_mfma_i32_16x16x64_i8 v[26:29], v[122:125], v[210:213], v[26:29]
	v_mfma_i32_16x16x64_i8 v[26:29], v[130:133], v[214:217], v[26:29]
	v_mfma_i32_16x16x64_i8 v[14:17], v[106:109], v[218:221], v[14:17]
	v_mfma_i32_16x16x64_i8 v[14:17], v[114:117], v[222:225], v[14:17]
	v_mfma_i32_16x16x64_i8 v[10:13], v[122:125], v[218:221], v[10:13]
	v_mfma_i32_16x16x64_i8 v[10:13], v[130:133], v[222:225], v[10:13]
	v_mfma_i32_16x16x64_i8 v[54:57], v[146:149], v[162:165], v[54:57]
	v_mfma_i32_16x16x64_i8 v[54:57], v[150:153], v[182:185], v[54:57]
	v_mfma_i32_16x16x64_i8 v[50:53], v[154:157], v[162:165], v[50:53]
	v_mfma_i32_16x16x64_i8 v[50:53], v[158:161], v[182:185], v[50:53]
	v_mfma_i32_16x16x64_i8 v[38:41], v[146:149], v[186:189], v[38:41]
	v_mfma_i32_16x16x64_i8 v[38:41], v[150:153], v[206:209], v[38:41]
	v_mfma_i32_16x16x64_i8 v[34:37], v[154:157], v[186:189], v[34:37]
	v_mfma_i32_16x16x64_i8 v[34:37], v[158:161], v[206:209], v[34:37]
	v_mfma_i32_16x16x64_i8 v[22:25], v[146:149], v[210:213], v[22:25]
	v_mfma_i32_16x16x64_i8 v[22:25], v[150:153], v[214:217], v[22:25]
	v_mfma_i32_16x16x64_i8 v[18:21], v[154:157], v[210:213], v[18:21]
	v_mfma_i32_16x16x64_i8 v[18:21], v[158:161], v[214:217], v[18:21]
	v_mfma_i32_16x16x64_i8 v[6:9], v[146:149], v[218:221], v[6:9]
	v_mfma_i32_16x16x64_i8 v[6:9], v[150:153], v[222:225], v[6:9]
	v_mfma_i32_16x16x64_i8 v[2:5], v[154:157], v[218:221], v[2:5]
	v_mfma_i32_16x16x64_i8 v[2:5], v[158:161], v[222:225], v[2:5]
	s_barrier
	s_add_i32 s70, s70, 2
	s_add_u32 s28, s28, 0x100
	s_addc_u32 s29, s29, 0
	s_add_u32 s68, s68, 0x100
	s_addc_u32 s69, s69, 0
	s_cmp_gt_u32 s70, 29
	s_cbranch_scc0 .LBB0_1232
	s_and_b64 vcc, exec, s[12:13]
	s_cbranch_vccz .LBB0_1235
	s_barrier

.LBB0_1366:
	s_ashr_i32 s35, s34, 31
	s_lshl_b64 s[18:19], s[34:35], 20
	s_add_u32 s36, s29, s18
	s_addc_u32 s37, s60, s19
	s_and_b64 s[18:19], s[2:3], exec
	s_cselect_b32 s35, s37, s5
	s_cselect_b32 s43, s36, s4
	s_ashr_i32 s31, s30, 31
	s_lshl_b64 s[18:19], s[30:31], 20
	s_add_u32 s38, s61, s18
	s_addc_u32 s39, s62, s19
	s_and_b64 s[18:19], s[2:3], exec
	s_cselect_b32 s31, s39, s7
	s_cselect_b32 vcc_lo, s38, s6
	s_add_u32 vcc_hi, s6, 0x100
	s_addc_u32 s79, s7, 0
	s_mov_b32 s80, -2
	ds_read_b128 v[130:133], v234
	ds_read_b128 v[134:137], v234 offset:1024
	ds_read_b128 v[162:165], v234 offset:2048
	ds_read_b128 v[166:169], v234 offset:3072
	ds_read_b128 v[170:173], v235
	ds_read_b128 v[174:177], v235 offset:1024
	ds_read_b128 v[178:181], v235 offset:2048
	ds_read_b128 v[182:185], v235 offset:3072
	s_add_u32 s6, s4, 0x100
	s_addc_u32 s7, s5, 0
	s_cmp_eq_u32 s80, 28
	s_cselect_b32 s57, s35, s7
	s_cselect_b32 s56, s43, s6
	s_cselect_b32 s19, s31, s79
	s_cselect_b32 s18, vcc_lo, vcc_hi
	v_lshl_add_u64 v[218:219], s[4:5], 0, v[154:155]
	s_add_i32 m0, s65, 0xc000
	ds_read_b128 v[186:189], v236
	ds_read_b128 v[190:193], v236 offset:1024
	ds_read_b128 v[194:197], v236 offset:2048
	ds_read_b128 v[198:201], v236 offset:3072
	ds_read_b128 v[202:205], v236 offset:4096
	ds_read_b128 v[206:209], v236 offset:5120
	ds_read_b128 v[210:213], v236 offset:6144
	ds_read_b128 v[214:217], v236 offset:7168
	global_load_lds_dwordx4 v[218:219], off
	v_lshl_add_u64 v[218:219], s[4:5], 0, v[156:157]
	s_add_i32 m0, s65, 0xe000
	s_nop 0
	global_load_lds_dwordx4 v[218:219], off
	s_waitcnt vmcnt(8)
	s_waitcnt lgkmcnt(0)
	s_barrier
	v_mfma_i32_16x16x64_i8 v[118:121], v[130:133], v[186:189], 0
	v_mfma_i32_16x16x64_i8 v[118:121], v[134:137], v[190:193], v[118:121]
	v_mfma_i32_16x16x64_i8 v[102:105], v[162:165], v[186:189], 0
	v_mfma_i32_16x16x64_i8 v[102:105], v[166:169], v[190:193], v[102:105]
	v_mfma_i32_16x16x64_i8 v[114:117], v[130:133], v[194:197], 0
	v_mfma_i32_16x16x64_i8 v[114:117], v[134:137], v[198:201], v[114:117]
	v_mfma_i32_16x16x64_i8 v[98:101], v[162:165], v[194:197], 0
	v_mfma_i32_16x16x64_i8 v[98:101], v[166:169], v[198:201], v[98:101]
	v_mfma_i32_16x16x64_i8 v[126:129], v[130:133], v[202:205], 0
	v_mfma_i32_16x16x64_i8 v[126:129], v[134:137], v[206:209], v[126:129]
	v_mfma_i32_16x16x64_i8 v[110:113], v[162:165], v[202:205], 0
	v_mfma_i32_16x16x64_i8 v[110:113], v[166:169], v[206:209], v[110:113]
	v_mfma_i32_16x16x64_i8 v[122:125], v[130:133], v[210:213], 0
	v_mfma_i32_16x16x64_i8 v[122:125], v[134:137], v[214:217], v[122:125]
	v_mfma_i32_16x16x64_i8 v[106:109], v[162:165], v[210:213], 0
	v_mfma_i32_16x16x64_i8 v[106:109], v[166:169], v[214:217], v[106:109]
	v_mfma_i32_16x16x64_i8 v[86:89], v[170:173], v[186:189], 0
	v_mfma_i32_16x16x64_i8 v[86:89], v[174:177], v[190:193], v[86:89]
	v_mfma_i32_16x16x64_i8 v[70:73], v[178:181], v[186:189], 0
	v_mfma_i32_16x16x64_i8 v[70:73], v[182:185], v[190:193], v[70:73]
	v_mfma_i32_16x16x64_i8 v[82:85], v[170:173], v[194:197], 0
	v_mfma_i32_16x16x64_i8 v[82:85], v[174:177], v[198:201], v[82:85]
	v_mfma_i32_16x16x64_i8 v[66:69], v[178:181], v[194:197], 0
	v_mfma_i32_16x16x64_i8 v[66:69], v[182:185], v[198:201], v[66:69]
	v_mfma_i32_16x16x64_i8 v[94:97], v[170:173], v[202:205], 0
	v_mfma_i32_16x16x64_i8 v[94:97], v[174:177], v[206:209], v[94:97]
	v_mfma_i32_16x16x64_i8 v[78:81], v[178:181], v[202:205], 0
	v_mfma_i32_16x16x64_i8 v[78:81], v[182:185], v[206:209], v[78:81]
	v_mfma_i32_16x16x64_i8 v[90:93], v[170:173], v[210:213], 0
	v_mfma_i32_16x16x64_i8 v[90:93], v[174:177], v[214:217], v[90:93]
	v_mfma_i32_16x16x64_i8 v[74:77], v[178:181], v[210:213], 0
	v_mfma_i32_16x16x64_i8 v[74:77], v[182:185], v[214:217], v[74:77]
	s_barrier
	s_add_i32 s4, s97, s63
	v_lshl_add_u64 v[218:219], s[18:19], 0, v[144:145]
	s_mov_b32 m0, s4
	ds_read_b128 v[186:189], v236 offset:16384
	ds_read_b128 v[190:193], v236 offset:17408
	ds_read_b128 v[194:197], v236 offset:18432
	ds_read_b128 v[198:201], v236 offset:19456
	ds_read_b128 v[202:205], v236 offset:20480
	ds_read_b128 v[206:209], v236 offset:21504
	ds_read_b128 v[210:213], v236 offset:22528
	ds_read_b128 v[214:217], v236 offset:23552
	global_load_lds_dwordx4 v[218:219], off
	s_add_i32 m0, s4, 0x2000
	s_add_u32 s4, s18, 0x80000
	v_lshl_add_u64 v[220:221], s[18:19], 0, v[148:149]
	s_addc_u32 s5, s19, 0
	s_add_i32 s81, s0, s63
	global_load_lds_dwordx4 v[220:221], off
	v_lshl_add_u64 v[222:223], s[4:5], 0, v[144:145]
	s_mov_b32 m0, s81
	v_lshl_add_u64 v[224:225], s[56:57], 0, v[146:147]
	global_load_lds_dwordx4 v[222:223], off
	v_lshl_add_u64 v[222:223], s[4:5], 0, v[148:149]
	s_add_i32 m0, s81, 0x2000
	s_nop 0
	global_load_lds_dwordx4 v[222:223], off
	v_lshl_add_u64 v[222:223], s[56:57], 0, v[142:143]
	s_mov_b32 m0, s65
	s_nop 0
	global_load_lds_dwordx4 v[222:223], off
	s_mov_b32 m0, s66
	s_nop 0
	global_load_lds_dwordx4 v[224:225], off
	s_waitcnt vmcnt(8)
	s_waitcnt lgkmcnt(0)
	s_barrier
	v_mfma_i32_16x16x64_i8 v[54:57], v[130:133], v[186:189], 0
	v_mfma_i32_16x16x64_i8 v[54:57], v[134:137], v[190:193], v[54:57]
	v_mfma_i32_16x16x64_i8 v[18:21], v[162:165], v[186:189], 0
	v_mfma_i32_16x16x64_i8 v[18:21], v[166:169], v[190:193], v[18:21]
	v_mfma_i32_16x16x64_i8 v[50:53], v[130:133], v[194:197], 0
	v_mfma_i32_16x16x64_i8 v[50:53], v[134:137], v[198:201], v[50:53]
	v_mfma_i32_16x16x64_i8 v[22:25], v[162:165], v[194:197], 0
	v_mfma_i32_16x16x64_i8 v[22:25], v[166:169], v[198:201], v[22:25]
	v_mfma_i32_16x16x64_i8 v[62:65], v[130:133], v[202:205], 0
	v_mfma_i32_16x16x64_i8 v[62:65], v[134:137], v[206:209], v[62:65]
	v_mfma_i32_16x16x64_i8 v[30:33], v[162:165], v[202:205], 0
	v_mfma_i32_16x16x64_i8 v[30:33], v[166:169], v[206:209], v[30:33]
	v_mfma_i32_16x16x64_i8 v[58:61], v[130:133], v[210:213], 0
	v_mfma_i32_16x16x64_i8 v[58:61], v[134:137], v[214:217], v[58:61]
	v_mfma_i32_16x16x64_i8 v[26:29], v[162:165], v[210:213], 0
	v_mfma_i32_16x16x64_i8 v[26:29], v[166:169], v[214:217], v[26:29]
	v_mfma_i32_16x16x64_i8 v[46:49], v[170:173], v[186:189], 0
	v_mfma_i32_16x16x64_i8 v[46:49], v[174:177], v[190:193], v[46:49]
	v_mfma_i32_16x16x64_i8 v[14:17], v[178:181], v[186:189], 0
	v_mfma_i32_16x16x64_i8 v[14:17], v[182:185], v[190:193], v[14:17]
	v_mfma_i32_16x16x64_i8 v[42:45], v[170:173], v[194:197], 0
	v_mfma_i32_16x16x64_i8 v[42:45], v[174:177], v[198:201], v[42:45]
	v_mfma_i32_16x16x64_i8 v[10:13], v[178:181], v[194:197], 0
	v_mfma_i32_16x16x64_i8 v[10:13], v[182:185], v[198:201], v[10:13]
	v_mfma_i32_16x16x64_i8 v[38:41], v[170:173], v[202:205], 0
	v_mfma_i32_16x16x64_i8 v[38:41], v[174:177], v[206:209], v[38:41]
	v_mfma_i32_16x16x64_i8 v[6:9], v[178:181], v[202:205], 0
	v_mfma_i32_16x16x64_i8 v[6:9], v[182:185], v[206:209], v[6:9]
	v_mfma_i32_16x16x64_i8 v[34:37], v[170:173], v[210:213], 0
	v_mfma_i32_16x16x64_i8 v[34:37], v[174:177], v[214:217], v[34:37]
	v_mfma_i32_16x16x64_i8 v[2:5], v[178:181], v[210:213], 0
	v_mfma_i32_16x16x64_i8 v[2:5], v[182:185], v[214:217], v[2:5]
	s_barrier
	s_add_i32 s81, 0, 0x18000
	s_add_i32 s82, 0, 0x1c000
	v_add_u32_e32 v166, s81, v232
	v_add_u32_e32 v182, s82, v232
	ds_read_b128 v[130:133], v166
	ds_read_b128 v[134:137], v166 offset:1024
	ds_read_b128 v[162:165], v166 offset:2048
	ds_read_b128 v[166:169], v166 offset:3072
	ds_read_b128 v[170:173], v182
	ds_read_b128 v[174:177], v182 offset:1024
	ds_read_b128 v[178:181], v182 offset:2048
	ds_read_b128 v[182:185], v182 offset:3072
	s_add_u32 s4, s56, 0x80000
	s_addc_u32 s5, s57, 0
	s_mov_b32 m0, s67
	v_lshl_add_u64 v[226:227], s[4:5], 0, v[142:143]
	ds_read_b128 v[186:189], v236 offset:32768
	ds_read_b128 v[190:193], v236 offset:33792
	ds_read_b128 v[194:197], v236 offset:34816
	ds_read_b128 v[198:201], v236 offset:35840
	ds_read_b128 v[202:205], v236 offset:36864
	ds_read_b128 v[206:209], v236 offset:37888
	ds_read_b128 v[210:213], v236 offset:38912
	ds_read_b128 v[214:217], v236 offset:39936
	global_load_lds_dwordx4 v[226:227], off
	v_lshl_add_u64 v[226:227], s[4:5], 0, v[146:147]
	s_mov_b32 m0, s68
	s_nop 0
	global_load_lds_dwordx4 v[226:227], off
	s_waitcnt vmcnt(8)
	s_waitcnt lgkmcnt(0)
	s_barrier
	v_mfma_i32_16x16x64_i8 v[118:121], v[130:133], v[186:189], v[118:121]
	v_mfma_i32_16x16x64_i8 v[118:121], v[134:137], v[190:193], v[118:121]
	v_mfma_i32_16x16x64_i8 v[102:105], v[162:165], v[186:189], v[102:105]
	v_mfma_i32_16x16x64_i8 v[102:105], v[166:169], v[190:193], v[102:105]
	v_mfma_i32_16x16x64_i8 v[114:117], v[130:133], v[194:197], v[114:117]
	v_mfma_i32_16x16x64_i8 v[114:117], v[134:137], v[198:201], v[114:117]
	v_mfma_i32_16x16x64_i8 v[98:101], v[162:165], v[194:197], v[98:101]
	v_mfma_i32_16x16x64_i8 v[98:101], v[166:169], v[198:201], v[98:101]
	v_mfma_i32_16x16x64_i8 v[126:129], v[130:133], v[202:205], v[126:129]
	v_mfma_i32_16x16x64_i8 v[126:129], v[134:137], v[206:209], v[126:129]
	v_mfma_i32_16x16x64_i8 v[110:113], v[162:165], v[202:205], v[110:113]
	v_mfma_i32_16x16x64_i8 v[110:113], v[166:169], v[206:209], v[110:113]
	v_mfma_i32_16x16x64_i8 v[122:125], v[130:133], v[210:213], v[122:125]
	v_mfma_i32_16x16x64_i8 v[122:125], v[134:137], v[214:217], v[122:125]
	v_mfma_i32_16x16x64_i8 v[106:109], v[162:165], v[210:213], v[106:109]
	v_mfma_i32_16x16x64_i8 v[106:109], v[166:169], v[214:217], v[106:109]
	v_mfma_i32_16x16x64_i8 v[86:89], v[170:173], v[186:189], v[86:89]
	v_mfma_i32_16x16x64_i8 v[86:89], v[174:177], v[190:193], v[86:89]
	v_mfma_i32_16x16x64_i8 v[70:73], v[178:181], v[186:189], v[70:73]
	v_mfma_i32_16x16x64_i8 v[70:73], v[182:185], v[190:193], v[70:73]
	v_mfma_i32_16x16x64_i8 v[82:85], v[170:173], v[194:197], v[82:85]
	v_mfma_i32_16x16x64_i8 v[82:85], v[174:177], v[198:201], v[82:85]
	v_mfma_i32_16x16x64_i8 v[66:69], v[178:181], v[194:197], v[66:69]
	v_mfma_i32_16x16x64_i8 v[66:69], v[182:185], v[198:201], v[66:69]
	v_mfma_i32_16x16x64_i8 v[94:97], v[170:173], v[202:205], v[94:97]
	v_mfma_i32_16x16x64_i8 v[94:97], v[174:177], v[206:209], v[94:97]
	v_mfma_i32_16x16x64_i8 v[78:81], v[178:181], v[202:205], v[78:81]
	v_mfma_i32_16x16x64_i8 v[78:81], v[182:185], v[206:209], v[78:81]
	v_mfma_i32_16x16x64_i8 v[90:93], v[170:173], v[210:213], v[90:93]
	v_mfma_i32_16x16x64_i8 v[90:93], v[174:177], v[214:217], v[90:93]
	v_mfma_i32_16x16x64_i8 v[74:77], v[178:181], v[210:213], v[74:77]
	v_mfma_i32_16x16x64_i8 v[74:77], v[182:185], v[214:217], v[74:77]
	s_barrier
	s_add_i32 s4, s81, s63
	v_lshl_add_u64 v[218:219], v[218:219], 0, s[22:23]
	s_mov_b32 m0, s4
	ds_read_b128 v[186:189], v236 offset:49152
	ds_read_b128 v[190:193], v236 offset:50176
	ds_read_b128 v[194:197], v236 offset:51200
	ds_read_b128 v[198:201], v236 offset:52224
	ds_read_b128 v[202:205], v236 offset:53248
	ds_read_b128 v[206:209], v236 offset:54272
	ds_read_b128 v[210:213], v236 offset:55296
	ds_read_b128 v[214:217], v236 offset:56320
	global_load_lds_dwordx4 v[218:219], off
	s_add_i32 m0, s4, 0x2000
	s_add_u32 s4, s18, 0x80080
	v_lshl_add_u64 v[218:219], v[220:221], 0, s[22:23]
	s_addc_u32 s5, s19, 0
	s_add_i32 s18, s82, s63
	global_load_lds_dwordx4 v[218:219], off
	v_lshl_add_u64 v[218:219], s[4:5], 0, v[144:145]
	s_mov_b32 m0, s18
	s_nop 0
	global_load_lds_dwordx4 v[218:219], off
	v_lshl_add_u64 v[218:219], s[4:5], 0, v[148:149]
	s_add_i32 m0, s18, 0x2000
	s_nop 0
	global_load_lds_dwordx4 v[218:219], off
	v_lshl_add_u64 v[218:219], v[222:223], 0, s[22:23]
	s_mov_b32 m0, s77
	s_nop 0
	global_load_lds_dwordx4 v[218:219], off
	v_lshl_add_u64 v[218:219], v[224:225], 0, s[22:23]
	s_mov_b32 m0, s78
	s_nop 0
	global_load_lds_dwordx4 v[218:219], off
	s_waitcnt vmcnt(8)
	s_waitcnt lgkmcnt(0)
	s_barrier
	v_mfma_i32_16x16x64_i8 v[54:57], v[130:133], v[186:189], v[54:57]
	v_mfma_i32_16x16x64_i8 v[54:57], v[134:137], v[190:193], v[54:57]
	v_mfma_i32_16x16x64_i8 v[18:21], v[162:165], v[186:189], v[18:21]
	v_mfma_i32_16x16x64_i8 v[18:21], v[166:169], v[190:193], v[18:21]
	v_mfma_i32_16x16x64_i8 v[50:53], v[130:133], v[194:197], v[50:53]
	v_mfma_i32_16x16x64_i8 v[50:53], v[134:137], v[198:201], v[50:53]
	v_mfma_i32_16x16x64_i8 v[22:25], v[162:165], v[194:197], v[22:25]
	v_mfma_i32_16x16x64_i8 v[22:25], v[166:169], v[198:201], v[22:25]
	v_mfma_i32_16x16x64_i8 v[62:65], v[130:133], v[202:205], v[62:65]
	v_mfma_i32_16x16x64_i8 v[62:65], v[134:137], v[206:209], v[62:65]
	v_mfma_i32_16x16x64_i8 v[30:33], v[162:165], v[202:205], v[30:33]
	v_mfma_i32_16x16x64_i8 v[30:33], v[166:169], v[206:209], v[30:33]
	v_mfma_i32_16x16x64_i8 v[58:61], v[130:133], v[210:213], v[58:61]
	v_mfma_i32_16x16x64_i8 v[58:61], v[134:137], v[214:217], v[58:61]
	v_mfma_i32_16x16x64_i8 v[26:29], v[162:165], v[210:213], v[26:29]
	v_mfma_i32_16x16x64_i8 v[26:29], v[166:169], v[214:217], v[26:29]
	v_mfma_i32_16x16x64_i8 v[46:49], v[170:173], v[186:189], v[46:49]
	v_mfma_i32_16x16x64_i8 v[46:49], v[174:177], v[190:193], v[46:49]
	v_mfma_i32_16x16x64_i8 v[14:17], v[178:181], v[186:189], v[14:17]
	v_mfma_i32_16x16x64_i8 v[14:17], v[182:185], v[190:193], v[14:17]
	v_mfma_i32_16x16x64_i8 v[42:45], v[170:173], v[194:197], v[42:45]
	v_mfma_i32_16x16x64_i8 v[42:45], v[174:177], v[198:201], v[42:45]
	v_mfma_i32_16x16x64_i8 v[10:13], v[178:181], v[194:197], v[10:13]
	v_mfma_i32_16x16x64_i8 v[10:13], v[182:185], v[198:201], v[10:13]
	v_mfma_i32_16x16x64_i8 v[38:41], v[170:173], v[202:205], v[38:41]
	v_mfma_i32_16x16x64_i8 v[38:41], v[174:177], v[206:209], v[38:41]
	v_mfma_i32_16x16x64_i8 v[6:9], v[178:181], v[202:205], v[6:9]
	v_mfma_i32_16x16x64_i8 v[6:9], v[182:185], v[206:209], v[6:9]
	v_mfma_i32_16x16x64_i8 v[34:37], v[170:173], v[210:213], v[34:37]
	v_mfma_i32_16x16x64_i8 v[34:37], v[174:177], v[214:217], v[34:37]
	v_mfma_i32_16x16x64_i8 v[2:5], v[178:181], v[210:213], v[2:5]
	v_mfma_i32_16x16x64_i8 v[2:5], v[182:185], v[214:217], v[2:5]
	s_barrier
	s_add_i32 s80, s80, 2
	s_add_u32 vcc_hi, vcc_hi, 0x100
	s_addc_u32 s79, s79, 0
	s_cmp_gt_u32 s80, 29
	s_mov_b64 s[4:5], s[6:7]
.LBB0_1367:
	ds_read_b128 v[130:133], v234
	ds_read_b128 v[134:137], v234 offset:1024
	ds_read_b128 v[162:165], v234 offset:2048
	ds_read_b128 v[166:169], v234 offset:3072
	ds_read_b128 v[170:173], v235
	ds_read_b128 v[174:177], v235 offset:1024
	ds_read_b128 v[178:181], v235 offset:2048
	ds_read_b128 v[182:185], v235 offset:3072
	s_add_u32 s6, s4, 0x100
	s_addc_u32 s7, s5, 0
	s_cmp_eq_u32 s80, 28
	s_cselect_b32 s57, s35, s7
	s_cselect_b32 s56, s43, s6
	s_cselect_b32 s19, s31, s79
	s_cselect_b32 s18, vcc_lo, vcc_hi
	v_lshl_add_u64 v[218:219], s[4:5], 0, v[154:155]
	s_add_i32 m0, s65, 0xc000
	ds_read_b128 v[186:189], v236
	ds_read_b128 v[190:193], v236 offset:1024
	ds_read_b128 v[194:197], v236 offset:2048
	ds_read_b128 v[198:201], v236 offset:3072
	ds_read_b128 v[202:205], v236 offset:4096
	ds_read_b128 v[206:209], v236 offset:5120
	ds_read_b128 v[210:213], v236 offset:6144
	ds_read_b128 v[214:217], v236 offset:7168
	global_load_lds_dwordx4 v[218:219], off
	v_lshl_add_u64 v[218:219], s[4:5], 0, v[156:157]
	s_add_i32 m0, s65, 0xe000
	s_nop 0
	global_load_lds_dwordx4 v[218:219], off
	s_waitcnt vmcnt(8)
	s_waitcnt lgkmcnt(0)
	s_barrier
	v_mfma_i32_16x16x64_i8 v[118:121], v[130:133], v[186:189], v[118:121]
	v_mfma_i32_16x16x64_i8 v[118:121], v[134:137], v[190:193], v[118:121]
	v_mfma_i32_16x16x64_i8 v[102:105], v[162:165], v[186:189], v[102:105]
	v_mfma_i32_16x16x64_i8 v[102:105], v[166:169], v[190:193], v[102:105]
	v_mfma_i32_16x16x64_i8 v[114:117], v[130:133], v[194:197], v[114:117]
	v_mfma_i32_16x16x64_i8 v[114:117], v[134:137], v[198:201], v[114:117]
	v_mfma_i32_16x16x64_i8 v[98:101], v[162:165], v[194:197], v[98:101]
	v_mfma_i32_16x16x64_i8 v[98:101], v[166:169], v[198:201], v[98:101]
	v_mfma_i32_16x16x64_i8 v[126:129], v[130:133], v[202:205], v[126:129]
	v_mfma_i32_16x16x64_i8 v[126:129], v[134:137], v[206:209], v[126:129]
	v_mfma_i32_16x16x64_i8 v[110:113], v[162:165], v[202:205], v[110:113]
	v_mfma_i32_16x16x64_i8 v[110:113], v[166:169], v[206:209], v[110:113]
	v_mfma_i32_16x16x64_i8 v[122:125], v[130:133], v[210:213], v[122:125]
	v_mfma_i32_16x16x64_i8 v[122:125], v[134:137], v[214:217], v[122:125]
	v_mfma_i32_16x16x64_i8 v[106:109], v[162:165], v[210:213], v[106:109]
	v_mfma_i32_16x16x64_i8 v[106:109], v[166:169], v[214:217], v[106:109]
	v_mfma_i32_16x16x64_i8 v[86:89], v[170:173], v[186:189], v[86:89]
	v_mfma_i32_16x16x64_i8 v[86:89], v[174:177], v[190:193], v[86:89]
	v_mfma_i32_16x16x64_i8 v[70:73], v[178:181], v[186:189], v[70:73]
	v_mfma_i32_16x16x64_i8 v[70:73], v[182:185], v[190:193], v[70:73]
	v_mfma_i32_16x16x64_i8 v[82:85], v[170:173], v[194:197], v[82:85]
	v_mfma_i32_16x16x64_i8 v[82:85], v[174:177], v[198:201], v[82:85]
	v_mfma_i32_16x16x64_i8 v[66:69], v[178:181], v[194:197], v[66:69]
	v_mfma_i32_16x16x64_i8 v[66:69], v[182:185], v[198:201], v[66:69]
	v_mfma_i32_16x16x64_i8 v[94:97], v[170:173], v[202:205], v[94:97]
	v_mfma_i32_16x16x64_i8 v[94:97], v[174:177], v[206:209], v[94:97]
	v_mfma_i32_16x16x64_i8 v[78:81], v[178:181], v[202:205], v[78:81]
	v_mfma_i32_16x16x64_i8 v[78:81], v[182:185], v[206:209], v[78:81]
	v_mfma_i32_16x16x64_i8 v[90:93], v[170:173], v[210:213], v[90:93]
	v_mfma_i32_16x16x64_i8 v[90:93], v[174:177], v[214:217], v[90:93]
	v_mfma_i32_16x16x64_i8 v[74:77], v[178:181], v[210:213], v[74:77]
	v_mfma_i32_16x16x64_i8 v[74:77], v[182:185], v[214:217], v[74:77]
	s_barrier
	s_add_i32 s4, s97, s63
	v_lshl_add_u64 v[218:219], s[18:19], 0, v[144:145]
	s_mov_b32 m0, s4
	ds_read_b128 v[186:189], v236 offset:16384
	ds_read_b128 v[190:193], v236 offset:17408
	ds_read_b128 v[194:197], v236 offset:18432
	ds_read_b128 v[198:201], v236 offset:19456
	ds_read_b128 v[202:205], v236 offset:20480
	ds_read_b128 v[206:209], v236 offset:21504
	ds_read_b128 v[210:213], v236 offset:22528
	ds_read_b128 v[214:217], v236 offset:23552
	global_load_lds_dwordx4 v[218:219], off
	s_add_i32 m0, s4, 0x2000
	s_add_u32 s4, s18, 0x80000
	v_lshl_add_u64 v[220:221], s[18:19], 0, v[148:149]
	s_addc_u32 s5, s19, 0
	s_add_i32 s81, s0, s63
	global_load_lds_dwordx4 v[220:221], off
	v_lshl_add_u64 v[222:223], s[4:5], 0, v[144:145]
	s_mov_b32 m0, s81
	v_lshl_add_u64 v[224:225], s[56:57], 0, v[146:147]
	global_load_lds_dwordx4 v[222:223], off
	v_lshl_add_u64 v[222:223], s[4:5], 0, v[148:149]
	s_add_i32 m0, s81, 0x2000
	s_nop 0
	global_load_lds_dwordx4 v[222:223], off
	v_lshl_add_u64 v[222:223], s[56:57], 0, v[142:143]
	s_mov_b32 m0, s65
	s_nop 0
	global_load_lds_dwordx4 v[222:223], off
	s_mov_b32 m0, s66
	s_nop 0
	global_load_lds_dwordx4 v[224:225], off
	s_waitcnt vmcnt(8)
	s_waitcnt lgkmcnt(0)
	s_barrier
	v_mfma_i32_16x16x64_i8 v[54:57], v[130:133], v[186:189], v[54:57]
	v_mfma_i32_16x16x64_i8 v[54:57], v[134:137], v[190:193], v[54:57]
	v_mfma_i32_16x16x64_i8 v[18:21], v[162:165], v[186:189], v[18:21]
	v_mfma_i32_16x16x64_i8 v[18:21], v[166:169], v[190:193], v[18:21]
	v_mfma_i32_16x16x64_i8 v[50:53], v[130:133], v[194:197], v[50:53]
	v_mfma_i32_16x16x64_i8 v[50:53], v[134:137], v[198:201], v[50:53]
	v_mfma_i32_16x16x64_i8 v[22:25], v[162:165], v[194:197], v[22:25]
	v_mfma_i32_16x16x64_i8 v[22:25], v[166:169], v[198:201], v[22:25]
	v_mfma_i32_16x16x64_i8 v[62:65], v[130:133], v[202:205], v[62:65]
	v_mfma_i32_16x16x64_i8 v[62:65], v[134:137], v[206:209], v[62:65]
	v_mfma_i32_16x16x64_i8 v[30:33], v[162:165], v[202:205], v[30:33]
	v_mfma_i32_16x16x64_i8 v[30:33], v[166:169], v[206:209], v[30:33]
	v_mfma_i32_16x16x64_i8 v[58:61], v[130:133], v[210:213], v[58:61]
	v_mfma_i32_16x16x64_i8 v[58:61], v[134:137], v[214:217], v[58:61]
	v_mfma_i32_16x16x64_i8 v[26:29], v[162:165], v[210:213], v[26:29]
	v_mfma_i32_16x16x64_i8 v[26:29], v[166:169], v[214:217], v[26:29]
	v_mfma_i32_16x16x64_i8 v[46:49], v[170:173], v[186:189], v[46:49]
	v_mfma_i32_16x16x64_i8 v[46:49], v[174:177], v[190:193], v[46:49]
	v_mfma_i32_16x16x64_i8 v[14:17], v[178:181], v[186:189], v[14:17]
	v_mfma_i32_16x16x64_i8 v[14:17], v[182:185], v[190:193], v[14:17]
	v_mfma_i32_16x16x64_i8 v[42:45], v[170:173], v[194:197], v[42:45]
	v_mfma_i32_16x16x64_i8 v[42:45], v[174:177], v[198:201], v[42:45]
	v_mfma_i32_16x16x64_i8 v[10:13], v[178:181], v[194:197], v[10:13]
	v_mfma_i32_16x16x64_i8 v[10:13], v[182:185], v[198:201], v[10:13]
	v_mfma_i32_16x16x64_i8 v[38:41], v[170:173], v[202:205], v[38:41]
	v_mfma_i32_16x16x64_i8 v[38:41], v[174:177], v[206:209], v[38:41]
	v_mfma_i32_16x16x64_i8 v[6:9], v[178:181], v[202:205], v[6:9]
	v_mfma_i32_16x16x64_i8 v[6:9], v[182:185], v[206:209], v[6:9]
	v_mfma_i32_16x16x64_i8 v[34:37], v[170:173], v[210:213], v[34:37]
	v_mfma_i32_16x16x64_i8 v[34:37], v[174:177], v[214:217], v[34:37]
	v_mfma_i32_16x16x64_i8 v[2:5], v[178:181], v[210:213], v[2:5]
	v_mfma_i32_16x16x64_i8 v[2:5], v[182:185], v[214:217], v[2:5]
	s_barrier
	s_add_i32 s81, 0, 0x18000
	s_add_i32 s82, 0, 0x1c000
	v_add_u32_e32 v166, s81, v232
	v_add_u32_e32 v182, s82, v232
	ds_read_b128 v[130:133], v166
	ds_read_b128 v[134:137], v166 offset:1024
	ds_read_b128 v[162:165], v166 offset:2048
	ds_read_b128 v[166:169], v166 offset:3072
	ds_read_b128 v[170:173], v182
	ds_read_b128 v[174:177], v182 offset:1024
	ds_read_b128 v[178:181], v182 offset:2048
	ds_read_b128 v[182:185], v182 offset:3072
	s_add_u32 s4, s56, 0x80000
	s_addc_u32 s5, s57, 0
	s_mov_b32 m0, s67
	v_lshl_add_u64 v[226:227], s[4:5], 0, v[142:143]
	ds_read_b128 v[186:189], v236 offset:32768
	ds_read_b128 v[190:193], v236 offset:33792
	ds_read_b128 v[194:197], v236 offset:34816
	ds_read_b128 v[198:201], v236 offset:35840
	ds_read_b128 v[202:205], v236 offset:36864
	ds_read_b128 v[206:209], v236 offset:37888
	ds_read_b128 v[210:213], v236 offset:38912
	ds_read_b128 v[214:217], v236 offset:39936
	global_load_lds_dwordx4 v[226:227], off
	v_lshl_add_u64 v[226:227], s[4:5], 0, v[146:147]
	s_mov_b32 m0, s68
	s_nop 0
	global_load_lds_dwordx4 v[226:227], off
	s_waitcnt vmcnt(8)
	s_waitcnt lgkmcnt(0)
	s_barrier
	v_mfma_i32_16x16x64_i8 v[118:121], v[130:133], v[186:189], v[118:121]
	v_mfma_i32_16x16x64_i8 v[118:121], v[134:137], v[190:193], v[118:121]
	v_mfma_i32_16x16x64_i8 v[102:105], v[162:165], v[186:189], v[102:105]
	v_mfma_i32_16x16x64_i8 v[102:105], v[166:169], v[190:193], v[102:105]
	v_mfma_i32_16x16x64_i8 v[114:117], v[130:133], v[194:197], v[114:117]
	v_mfma_i32_16x16x64_i8 v[114:117], v[134:137], v[198:201], v[114:117]
	v_mfma_i32_16x16x64_i8 v[98:101], v[162:165], v[194:197], v[98:101]
	v_mfma_i32_16x16x64_i8 v[98:101], v[166:169], v[198:201], v[98:101]
	v_mfma_i32_16x16x64_i8 v[126:129], v[130:133], v[202:205], v[126:129]
	v_mfma_i32_16x16x64_i8 v[126:129], v[134:137], v[206:209], v[126:129]
	v_mfma_i32_16x16x64_i8 v[110:113], v[162:165], v[202:205], v[110:113]
	v_mfma_i32_16x16x64_i8 v[110:113], v[166:169], v[206:209], v[110:113]
	v_mfma_i32_16x16x64_i8 v[122:125], v[130:133], v[210:213], v[122:125]
	v_mfma_i32_16x16x64_i8 v[122:125], v[134:137], v[214:217], v[122:125]
	v_mfma_i32_16x16x64_i8 v[106:109], v[162:165], v[210:213], v[106:109]
	v_mfma_i32_16x16x64_i8 v[106:109], v[166:169], v[214:217], v[106:109]
	v_mfma_i32_16x16x64_i8 v[86:89], v[170:173], v[186:189], v[86:89]
	v_mfma_i32_16x16x64_i8 v[86:89], v[174:177], v[190:193], v[86:89]
	v_mfma_i32_16x16x64_i8 v[70:73], v[178:181], v[186:189], v[70:73]
	v_mfma_i32_16x16x64_i8 v[70:73], v[182:185], v[190:193], v[70:73]
	v_mfma_i32_16x16x64_i8 v[82:85], v[170:173], v[194:197], v[82:85]
	v_mfma_i32_16x16x64_i8 v[82:85], v[174:177], v[198:201], v[82:85]
	v_mfma_i32_16x16x64_i8 v[66:69], v[178:181], v[194:197], v[66:69]
	v_mfma_i32_16x16x64_i8 v[66:69], v[182:185], v[198:201], v[66:69]
	v_mfma_i32_16x16x64_i8 v[94:97], v[170:173], v[202:205], v[94:97]
	v_mfma_i32_16x16x64_i8 v[94:97], v[174:177], v[206:209], v[94:97]
	v_mfma_i32_16x16x64_i8 v[78:81], v[178:181], v[202:205], v[78:81]
	v_mfma_i32_16x16x64_i8 v[78:81], v[182:185], v[206:209], v[78:81]
	v_mfma_i32_16x16x64_i8 v[90:93], v[170:173], v[210:213], v[90:93]
	v_mfma_i32_16x16x64_i8 v[90:93], v[174:177], v[214:217], v[90:93]
	v_mfma_i32_16x16x64_i8 v[74:77], v[178:181], v[210:213], v[74:77]
	v_mfma_i32_16x16x64_i8 v[74:77], v[182:185], v[214:217], v[74:77]
	s_barrier
	s_add_i32 s4, s81, s63
	v_lshl_add_u64 v[218:219], v[218:219], 0, s[22:23]
	s_mov_b32 m0, s4
	ds_read_b128 v[186:189], v236 offset:49152
	ds_read_b128 v[190:193], v236 offset:50176
	ds_read_b128 v[194:197], v236 offset:51200
	ds_read_b128 v[198:201], v236 offset:52224
	ds_read_b128 v[202:205], v236 offset:53248
	ds_read_b128 v[206:209], v236 offset:54272
	ds_read_b128 v[210:213], v236 offset:55296
	ds_read_b128 v[214:217], v236 offset:56320
	global_load_lds_dwordx4 v[218:219], off
	s_add_i32 m0, s4, 0x2000
	s_add_u32 s4, s18, 0x80080
	v_lshl_add_u64 v[218:219], v[220:221], 0, s[22:23]
	s_addc_u32 s5, s19, 0
	s_add_i32 s18, s82, s63
	global_load_lds_dwordx4 v[218:219], off
	v_lshl_add_u64 v[218:219], s[4:5], 0, v[144:145]
	s_mov_b32 m0, s18
	s_nop 0
	global_load_lds_dwordx4 v[218:219], off
	v_lshl_add_u64 v[218:219], s[4:5], 0, v[148:149]
	s_add_i32 m0, s18, 0x2000
	s_nop 0
	global_load_lds_dwordx4 v[218:219], off
	v_lshl_add_u64 v[218:219], v[222:223], 0, s[22:23]
	s_mov_b32 m0, s77
	s_nop 0
	global_load_lds_dwordx4 v[218:219], off
	v_lshl_add_u64 v[218:219], v[224:225], 0, s[22:23]
	s_mov_b32 m0, s78
	s_nop 0
	global_load_lds_dwordx4 v[218:219], off
	s_waitcnt vmcnt(8)
	s_waitcnt lgkmcnt(0)
	s_barrier
	v_mfma_i32_16x16x64_i8 v[54:57], v[130:133], v[186:189], v[54:57]
	v_mfma_i32_16x16x64_i8 v[54:57], v[134:137], v[190:193], v[54:57]
	v_mfma_i32_16x16x64_i8 v[18:21], v[162:165], v[186:189], v[18:21]
	v_mfma_i32_16x16x64_i8 v[18:21], v[166:169], v[190:193], v[18:21]
	v_mfma_i32_16x16x64_i8 v[50:53], v[130:133], v[194:197], v[50:53]
	v_mfma_i32_16x16x64_i8 v[50:53], v[134:137], v[198:201], v[50:53]
	v_mfma_i32_16x16x64_i8 v[22:25], v[162:165], v[194:197], v[22:25]
	v_mfma_i32_16x16x64_i8 v[22:25], v[166:169], v[198:201], v[22:25]
	v_mfma_i32_16x16x64_i8 v[62:65], v[130:133], v[202:205], v[62:65]
	v_mfma_i32_16x16x64_i8 v[62:65], v[134:137], v[206:209], v[62:65]
	v_mfma_i32_16x16x64_i8 v[30:33], v[162:165], v[202:205], v[30:33]
	v_mfma_i32_16x16x64_i8 v[30:33], v[166:169], v[206:209], v[30:33]
	v_mfma_i32_16x16x64_i8 v[58:61], v[130:133], v[210:213], v[58:61]
	v_mfma_i32_16x16x64_i8 v[58:61], v[134:137], v[214:217], v[58:61]
	v_mfma_i32_16x16x64_i8 v[26:29], v[162:165], v[210:213], v[26:29]
	v_mfma_i32_16x16x64_i8 v[26:29], v[166:169], v[214:217], v[26:29]
	v_mfma_i32_16x16x64_i8 v[46:49], v[170:173], v[186:189], v[46:49]
	v_mfma_i32_16x16x64_i8 v[46:49], v[174:177], v[190:193], v[46:49]
	v_mfma_i32_16x16x64_i8 v[14:17], v[178:181], v[186:189], v[14:17]
	v_mfma_i32_16x16x64_i8 v[14:17], v[182:185], v[190:193], v[14:17]
	v_mfma_i32_16x16x64_i8 v[42:45], v[170:173], v[194:197], v[42:45]
	v_mfma_i32_16x16x64_i8 v[42:45], v[174:177], v[198:201], v[42:45]
	v_mfma_i32_16x16x64_i8 v[10:13], v[178:181], v[194:197], v[10:13]
	v_mfma_i32_16x16x64_i8 v[10:13], v[182:185], v[198:201], v[10:13]
	v_mfma_i32_16x16x64_i8 v[38:41], v[170:173], v[202:205], v[38:41]
	v_mfma_i32_16x16x64_i8 v[38:41], v[174:177], v[206:209], v[38:41]
	v_mfma_i32_16x16x64_i8 v[6:9], v[178:181], v[202:205], v[6:9]
	v_mfma_i32_16x16x64_i8 v[6:9], v[182:185], v[206:209], v[6:9]
	v_mfma_i32_16x16x64_i8 v[34:37], v[170:173], v[210:213], v[34:37]
	v_mfma_i32_16x16x64_i8 v[34:37], v[174:177], v[214:217], v[34:37]
	v_mfma_i32_16x16x64_i8 v[2:5], v[178:181], v[210:213], v[2:5]
	v_mfma_i32_16x16x64_i8 v[2:5], v[182:185], v[214:217], v[2:5]
	s_barrier
	s_add_i32 s80, s80, 2
	s_add_u32 vcc_hi, vcc_hi, 0x100
	s_addc_u32 s79, s79, 0
	s_cmp_gt_u32 s80, 29
	s_mov_b64 s[4:5], s[6:7]
	s_cbranch_scc0 .LBB0_1367
	s_and_b64 vcc, exec, s[10:11]
	s_cbranch_vccz .LBB0_1370
	s_barrier

.LBB0_1553:
	s_add_u32 s64, s26, 0x100
	s_addc_u32 s65, s27, 0
	s_mov_b32 s66, -2
	s_waitcnt lgkmcnt(0)
	ds_read_b128 v[114:117], v247
	ds_read_b128 v[118:121], v247 offset:1024
	ds_read_b128 v[126:129], v247 offset:2048
	ds_read_b128 v[134:137], v247 offset:3072
	ds_read_b128 v[138:141], v248
	ds_read_b128 v[142:145], v248 offset:1024
	ds_read_b128 v[154:157], v248 offset:2048
	ds_read_b128 v[158:161], v248 offset:3072
	s_add_u32 s4, s18, 0x100
	s_addc_u32 s5, s19, 0
	s_cmpk_eq_i32 s66, 0xdc
	s_cselect_b32 s29, s23, s5
	s_cselect_b32 s28, s22, s4
	s_cselect_b32 s27, s25, s65
	s_cselect_b32 s26, s24, s64
	v_lshl_add_u64 v[210:211], s[18:19], 0, v[202:203]
	s_add_i32 m0, s17, 0xc000
	ds_read_b128 v[162:165], v249
	ds_read_b128 v[166:169], v249 offset:1024
	ds_read_b128 v[170:173], v249 offset:2048
	ds_read_b128 v[174:177], v249 offset:3072
	ds_read_b128 v[178:181], v249 offset:4096
	ds_read_b128 v[182:185], v249 offset:5120
	ds_read_b128 v[186:189], v249 offset:6144
	ds_read_b128 v[190:193], v249 offset:7168
	global_load_lds_dwordx4 v[210:211], off
	v_lshl_add_u64 v[210:211], s[18:19], 0, v[204:205]
	s_add_i32 m0, s17, 0xe000
	s_nop 0
	global_load_lds_dwordx4 v[210:211], off
	s_waitcnt vmcnt(8)
	s_waitcnt lgkmcnt(0)
	s_barrier
	v_mfma_f32_16x16x32_bf16 v[150:153], v[114:117], v[162:165], 0
	v_mfma_f32_16x16x32_bf16 v[150:153], v[118:121], v[166:169], v[150:153]
	v_mfma_f32_16x16x32_bf16 v[146:149], v[126:129], v[162:165], 0
	v_mfma_f32_16x16x32_bf16 v[146:149], v[134:137], v[166:169], v[146:149]
	v_mfma_f32_16x16x32_bf16 v[110:113], v[114:117], v[170:173], 0
	v_mfma_f32_16x16x32_bf16 v[110:113], v[118:121], v[174:177], v[110:113]
	v_mfma_f32_16x16x32_bf16 v[106:109], v[126:129], v[170:173], 0
	v_mfma_f32_16x16x32_bf16 v[106:109], v[134:137], v[174:177], v[106:109]
	v_mfma_f32_16x16x32_bf16 v[94:97], v[114:117], v[178:181], 0
	v_mfma_f32_16x16x32_bf16 v[94:97], v[118:121], v[182:185], v[94:97]
	v_mfma_f32_16x16x32_bf16 v[90:93], v[126:129], v[178:181], 0
	v_mfma_f32_16x16x32_bf16 v[90:93], v[134:137], v[182:185], v[90:93]
	v_mfma_f32_16x16x32_bf16 v[78:81], v[114:117], v[186:189], 0
	v_mfma_f32_16x16x32_bf16 v[78:81], v[118:121], v[190:193], v[78:81]
	v_mfma_f32_16x16x32_bf16 v[74:77], v[126:129], v[186:189], 0
	v_mfma_f32_16x16x32_bf16 v[74:77], v[134:137], v[190:193], v[74:77]
	v_mfma_f32_16x16x32_bf16 v[130:133], v[138:141], v[162:165], 0
	v_mfma_f32_16x16x32_bf16 v[130:133], v[142:145], v[166:169], v[130:133]
	v_mfma_f32_16x16x32_bf16 v[122:125], v[154:157], v[162:165], 0
	v_mfma_f32_16x16x32_bf16 v[122:125], v[158:161], v[166:169], v[122:125]
	v_mfma_f32_16x16x32_bf16 v[102:105], v[138:141], v[170:173], 0
	v_mfma_f32_16x16x32_bf16 v[102:105], v[142:145], v[174:177], v[102:105]
	v_mfma_f32_16x16x32_bf16 v[98:101], v[154:157], v[170:173], 0
	v_mfma_f32_16x16x32_bf16 v[98:101], v[158:161], v[174:177], v[98:101]
	v_mfma_f32_16x16x32_bf16 v[86:89], v[138:141], v[178:181], 0
	v_mfma_f32_16x16x32_bf16 v[86:89], v[142:145], v[182:185], v[86:89]
	v_mfma_f32_16x16x32_bf16 v[82:85], v[154:157], v[178:181], 0
	v_mfma_f32_16x16x32_bf16 v[82:85], v[158:161], v[182:185], v[82:85]
	v_mfma_f32_16x16x32_bf16 v[70:73], v[138:141], v[186:189], 0
	v_mfma_f32_16x16x32_bf16 v[70:73], v[142:145], v[190:193], v[70:73]
	v_mfma_f32_16x16x32_bf16 v[66:69], v[154:157], v[186:189], 0
	v_mfma_f32_16x16x32_bf16 v[66:69], v[158:161], v[190:193], v[66:69]
	s_barrier
	s_add_i32 s18, s42, s16
	v_lshl_add_u64 v[210:211], s[26:27], 0, v[196:197]
	s_mov_b32 m0, s18
	ds_read_b128 v[162:165], v249 offset:16384
	ds_read_b128 v[166:169], v249 offset:17408
	ds_read_b128 v[170:173], v249 offset:18432
	ds_read_b128 v[174:177], v249 offset:19456
	ds_read_b128 v[178:181], v249 offset:20480
	ds_read_b128 v[182:185], v249 offset:21504
	ds_read_b128 v[186:189], v249 offset:22528
	ds_read_b128 v[190:193], v249 offset:23552
	global_load_lds_dwordx4 v[210:211], off
	s_add_i32 m0, s18, 0x2000
	s_add_u32 s18, s26, 0x380000
	v_lshl_add_u64 v[212:213], s[26:27], 0, v[200:201]
	s_addc_u32 s19, s27, 0
	s_add_i32 s67, s43, s16
	global_load_lds_dwordx4 v[212:213], off
	v_lshl_add_u64 v[214:215], s[18:19], 0, v[196:197]
	s_mov_b32 m0, s67
	v_lshl_add_u64 v[216:217], s[28:29], 0, v[198:199]
	global_load_lds_dwordx4 v[214:215], off
	v_lshl_add_u64 v[214:215], s[18:19], 0, v[200:201]
	s_add_i32 m0, s67, 0x2000
	s_nop 0
	global_load_lds_dwordx4 v[214:215], off
	v_lshl_add_u64 v[214:215], s[28:29], 0, v[194:195]
	s_mov_b32 m0, s17
	s_nop 0
	global_load_lds_dwordx4 v[214:215], off
	s_mov_b32 m0, s30
	s_nop 0
	global_load_lds_dwordx4 v[216:217], off
	s_waitcnt vmcnt(8)
	s_waitcnt lgkmcnt(0)
	s_barrier
	v_mfma_f32_16x16x32_bf16 v[62:65], v[114:117], v[162:165], 0
	v_mfma_f32_16x16x32_bf16 v[62:65], v[118:121], v[166:169], v[62:65]
	v_mfma_f32_16x16x32_bf16 v[58:61], v[126:129], v[162:165], 0
	v_mfma_f32_16x16x32_bf16 v[58:61], v[134:137], v[166:169], v[58:61]
	v_mfma_f32_16x16x32_bf16 v[46:49], v[114:117], v[170:173], 0
	v_mfma_f32_16x16x32_bf16 v[46:49], v[118:121], v[174:177], v[46:49]
	v_mfma_f32_16x16x32_bf16 v[42:45], v[126:129], v[170:173], 0
	v_mfma_f32_16x16x32_bf16 v[42:45], v[134:137], v[174:177], v[42:45]
	v_mfma_f32_16x16x32_bf16 v[30:33], v[114:117], v[178:181], 0
	v_mfma_f32_16x16x32_bf16 v[30:33], v[118:121], v[182:185], v[30:33]
	v_mfma_f32_16x16x32_bf16 v[26:29], v[126:129], v[178:181], 0
	v_mfma_f32_16x16x32_bf16 v[26:29], v[134:137], v[182:185], v[26:29]
	v_mfma_f32_16x16x32_bf16 v[14:17], v[114:117], v[186:189], 0
	v_mfma_f32_16x16x32_bf16 v[14:17], v[118:121], v[190:193], v[14:17]
	v_mfma_f32_16x16x32_bf16 v[10:13], v[126:129], v[186:189], 0
	v_mfma_f32_16x16x32_bf16 v[10:13], v[134:137], v[190:193], v[10:13]
	v_mfma_f32_16x16x32_bf16 v[54:57], v[138:141], v[162:165], 0
	v_mfma_f32_16x16x32_bf16 v[54:57], v[142:145], v[166:169], v[54:57]
	v_mfma_f32_16x16x32_bf16 v[50:53], v[154:157], v[162:165], 0
	v_mfma_f32_16x16x32_bf16 v[50:53], v[158:161], v[166:169], v[50:53]
	v_mfma_f32_16x16x32_bf16 v[38:41], v[138:141], v[170:173], 0
	v_mfma_f32_16x16x32_bf16 v[38:41], v[142:145], v[174:177], v[38:41]
	v_mfma_f32_16x16x32_bf16 v[34:37], v[154:157], v[170:173], 0
	v_mfma_f32_16x16x32_bf16 v[34:37], v[158:161], v[174:177], v[34:37]
	v_mfma_f32_16x16x32_bf16 v[22:25], v[138:141], v[178:181], 0
	v_mfma_f32_16x16x32_bf16 v[22:25], v[142:145], v[182:185], v[22:25]
	v_mfma_f32_16x16x32_bf16 v[18:21], v[154:157], v[178:181], 0
	v_mfma_f32_16x16x32_bf16 v[18:21], v[158:161], v[182:185], v[18:21]
	v_mfma_f32_16x16x32_bf16 v[6:9], v[138:141], v[186:189], 0
	v_mfma_f32_16x16x32_bf16 v[6:9], v[142:145], v[190:193], v[6:9]
	v_mfma_f32_16x16x32_bf16 v[2:5], v[154:157], v[186:189], 0
	v_mfma_f32_16x16x32_bf16 v[2:5], v[158:161], v[190:193], v[2:5]
	s_barrier
	s_add_i32 s67, 0, 0x18000
	s_add_i32 s68, 0, 0x1c000
	v_add_u32_e32 v134, s67, v244
	v_add_u32_e32 v158, s68, v244
	ds_read_b128 v[114:117], v134
	ds_read_b128 v[118:121], v134 offset:1024
	ds_read_b128 v[126:129], v134 offset:2048
	ds_read_b128 v[134:137], v134 offset:3072
	ds_read_b128 v[138:141], v158
	ds_read_b128 v[142:145], v158 offset:1024
	ds_read_b128 v[154:157], v158 offset:2048
	ds_read_b128 v[158:161], v158 offset:3072
	s_add_u32 s18, s28, 0x380000
	s_addc_u32 s19, s29, 0
	s_mov_b32 m0, s31
	v_lshl_add_u64 v[218:219], s[18:19], 0, v[194:195]
	ds_read_b128 v[162:165], v249 offset:32768
	ds_read_b128 v[166:169], v249 offset:33792
	ds_read_b128 v[170:173], v249 offset:34816
	ds_read_b128 v[174:177], v249 offset:35840
	ds_read_b128 v[178:181], v249 offset:36864
	ds_read_b128 v[182:185], v249 offset:37888
	ds_read_b128 v[186:189], v249 offset:38912
	ds_read_b128 v[190:193], v249 offset:39936
	global_load_lds_dwordx4 v[218:219], off
	v_lshl_add_u64 v[218:219], s[18:19], 0, v[198:199]
	s_mov_b32 m0, s34
	s_nop 0
	global_load_lds_dwordx4 v[218:219], off
	s_waitcnt vmcnt(8)
	s_waitcnt lgkmcnt(0)
	s_barrier
	v_mfma_f32_16x16x32_bf16 v[150:153], v[114:117], v[162:165], v[150:153]
	v_mfma_f32_16x16x32_bf16 v[150:153], v[118:121], v[166:169], v[150:153]
	v_mfma_f32_16x16x32_bf16 v[146:149], v[126:129], v[162:165], v[146:149]
	v_mfma_f32_16x16x32_bf16 v[146:149], v[134:137], v[166:169], v[146:149]
	v_mfma_f32_16x16x32_bf16 v[110:113], v[114:117], v[170:173], v[110:113]
	v_mfma_f32_16x16x32_bf16 v[110:113], v[118:121], v[174:177], v[110:113]
	v_mfma_f32_16x16x32_bf16 v[106:109], v[126:129], v[170:173], v[106:109]
	v_mfma_f32_16x16x32_bf16 v[106:109], v[134:137], v[174:177], v[106:109]
	v_mfma_f32_16x16x32_bf16 v[94:97], v[114:117], v[178:181], v[94:97]
	v_mfma_f32_16x16x32_bf16 v[94:97], v[118:121], v[182:185], v[94:97]
	v_mfma_f32_16x16x32_bf16 v[90:93], v[126:129], v[178:181], v[90:93]
	v_mfma_f32_16x16x32_bf16 v[90:93], v[134:137], v[182:185], v[90:93]
	v_mfma_f32_16x16x32_bf16 v[78:81], v[114:117], v[186:189], v[78:81]
	v_mfma_f32_16x16x32_bf16 v[78:81], v[118:121], v[190:193], v[78:81]
	v_mfma_f32_16x16x32_bf16 v[74:77], v[126:129], v[186:189], v[74:77]
	v_mfma_f32_16x16x32_bf16 v[74:77], v[134:137], v[190:193], v[74:77]
	v_mfma_f32_16x16x32_bf16 v[130:133], v[138:141], v[162:165], v[130:133]
	v_mfma_f32_16x16x32_bf16 v[130:133], v[142:145], v[166:169], v[130:133]
	v_mfma_f32_16x16x32_bf16 v[122:125], v[154:157], v[162:165], v[122:125]
	v_mfma_f32_16x16x32_bf16 v[122:125], v[158:161], v[166:169], v[122:125]
	v_mfma_f32_16x16x32_bf16 v[102:105], v[138:141], v[170:173], v[102:105]
	v_mfma_f32_16x16x32_bf16 v[102:105], v[142:145], v[174:177], v[102:105]
	v_mfma_f32_16x16x32_bf16 v[98:101], v[154:157], v[170:173], v[98:101]
	v_mfma_f32_16x16x32_bf16 v[98:101], v[158:161], v[174:177], v[98:101]
	v_mfma_f32_16x16x32_bf16 v[86:89], v[138:141], v[178:181], v[86:89]
	v_mfma_f32_16x16x32_bf16 v[86:89], v[142:145], v[182:185], v[86:89]
	v_mfma_f32_16x16x32_bf16 v[82:85], v[154:157], v[178:181], v[82:85]
	v_mfma_f32_16x16x32_bf16 v[82:85], v[158:161], v[182:185], v[82:85]
	v_mfma_f32_16x16x32_bf16 v[70:73], v[138:141], v[186:189], v[70:73]
	v_mfma_f32_16x16x32_bf16 v[70:73], v[142:145], v[190:193], v[70:73]
	v_mfma_f32_16x16x32_bf16 v[66:69], v[154:157], v[186:189], v[66:69]
	v_mfma_f32_16x16x32_bf16 v[66:69], v[158:161], v[190:193], v[66:69]
	s_barrier
	s_add_i32 s18, s67, s16
	v_lshl_add_u64 v[210:211], v[210:211], 0, s[12:13]
	s_mov_b32 m0, s18
	ds_read_b128 v[162:165], v249 offset:49152
	ds_read_b128 v[166:169], v249 offset:50176
	ds_read_b128 v[170:173], v249 offset:51200
	ds_read_b128 v[174:177], v249 offset:52224
	ds_read_b128 v[178:181], v249 offset:53248
	ds_read_b128 v[182:185], v249 offset:54272
	ds_read_b128 v[186:189], v249 offset:55296
	ds_read_b128 v[190:193], v249 offset:56320
	global_load_lds_dwordx4 v[210:211], off
	s_add_i32 m0, s18, 0x2000
	s_add_u32 s18, s26, 0x380080
	v_lshl_add_u64 v[210:211], v[212:213], 0, s[12:13]
	s_addc_u32 s19, s27, 0
	s_add_i32 s26, s68, s16
	global_load_lds_dwordx4 v[210:211], off
	v_lshl_add_u64 v[210:211], s[18:19], 0, v[196:197]
	s_mov_b32 m0, s26
	s_nop 0
	global_load_lds_dwordx4 v[210:211], off
	v_lshl_add_u64 v[210:211], s[18:19], 0, v[200:201]
	s_add_i32 m0, s26, 0x2000
	s_nop 0
	global_load_lds_dwordx4 v[210:211], off
	v_lshl_add_u64 v[210:211], v[214:215], 0, s[12:13]
	s_mov_b32 m0, s38
	s_nop 0
	global_load_lds_dwordx4 v[210:211], off
	v_lshl_add_u64 v[210:211], v[216:217], 0, s[12:13]
	s_mov_b32 m0, s39
	s_nop 0
	global_load_lds_dwordx4 v[210:211], off
	s_waitcnt vmcnt(8)
	s_waitcnt lgkmcnt(0)
	s_barrier
	v_mfma_f32_16x16x32_bf16 v[62:65], v[114:117], v[162:165], v[62:65]
	v_mfma_f32_16x16x32_bf16 v[62:65], v[118:121], v[166:169], v[62:65]
	v_mfma_f32_16x16x32_bf16 v[58:61], v[126:129], v[162:165], v[58:61]
	v_mfma_f32_16x16x32_bf16 v[58:61], v[134:137], v[166:169], v[58:61]
	v_mfma_f32_16x16x32_bf16 v[46:49], v[114:117], v[170:173], v[46:49]
	v_mfma_f32_16x16x32_bf16 v[46:49], v[118:121], v[174:177], v[46:49]
	v_mfma_f32_16x16x32_bf16 v[42:45], v[126:129], v[170:173], v[42:45]
	v_mfma_f32_16x16x32_bf16 v[42:45], v[134:137], v[174:177], v[42:45]
	v_mfma_f32_16x16x32_bf16 v[30:33], v[114:117], v[178:181], v[30:33]
	v_mfma_f32_16x16x32_bf16 v[30:33], v[118:121], v[182:185], v[30:33]
	v_mfma_f32_16x16x32_bf16 v[26:29], v[126:129], v[178:181], v[26:29]
	v_mfma_f32_16x16x32_bf16 v[26:29], v[134:137], v[182:185], v[26:29]
	v_mfma_f32_16x16x32_bf16 v[14:17], v[114:117], v[186:189], v[14:17]
	v_mfma_f32_16x16x32_bf16 v[14:17], v[118:121], v[190:193], v[14:17]
	v_mfma_f32_16x16x32_bf16 v[10:13], v[126:129], v[186:189], v[10:13]
	v_mfma_f32_16x16x32_bf16 v[10:13], v[134:137], v[190:193], v[10:13]
	v_mfma_f32_16x16x32_bf16 v[54:57], v[138:141], v[162:165], v[54:57]
	v_mfma_f32_16x16x32_bf16 v[54:57], v[142:145], v[166:169], v[54:57]
	v_mfma_f32_16x16x32_bf16 v[50:53], v[154:157], v[162:165], v[50:53]
	v_mfma_f32_16x16x32_bf16 v[50:53], v[158:161], v[166:169], v[50:53]
	v_mfma_f32_16x16x32_bf16 v[38:41], v[138:141], v[170:173], v[38:41]
	v_mfma_f32_16x16x32_bf16 v[38:41], v[142:145], v[174:177], v[38:41]
	v_mfma_f32_16x16x32_bf16 v[34:37], v[154:157], v[170:173], v[34:37]
	v_mfma_f32_16x16x32_bf16 v[34:37], v[158:161], v[174:177], v[34:37]
	v_mfma_f32_16x16x32_bf16 v[22:25], v[138:141], v[178:181], v[22:25]
	v_mfma_f32_16x16x32_bf16 v[22:25], v[142:145], v[182:185], v[22:25]
	v_mfma_f32_16x16x32_bf16 v[18:21], v[154:157], v[178:181], v[18:21]
	v_mfma_f32_16x16x32_bf16 v[18:21], v[158:161], v[182:185], v[18:21]
	v_mfma_f32_16x16x32_bf16 v[6:9], v[138:141], v[186:189], v[6:9]
	v_mfma_f32_16x16x32_bf16 v[6:9], v[142:145], v[190:193], v[6:9]
	v_mfma_f32_16x16x32_bf16 v[2:5], v[154:157], v[186:189], v[2:5]
	v_mfma_f32_16x16x32_bf16 v[2:5], v[158:161], v[190:193], v[2:5]
	s_barrier
	s_add_i32 s66, s66, 2
	s_add_u32 s64, s64, 0x100
	s_addc_u32 s65, s65, 0
	s_cmpk_gt_u32 s66, 0xdd
	s_mov_b64 s[18:19], s[4:5]
.LBB0_1554:
	ds_read_b128 v[114:117], v247
	ds_read_b128 v[118:121], v247 offset:1024
	ds_read_b128 v[126:129], v247 offset:2048
	ds_read_b128 v[134:137], v247 offset:3072
	ds_read_b128 v[138:141], v248
	ds_read_b128 v[142:145], v248 offset:1024
	ds_read_b128 v[154:157], v248 offset:2048
	ds_read_b128 v[158:161], v248 offset:3072
	s_add_u32 s4, s18, 0x100
	s_addc_u32 s5, s19, 0
	s_cmpk_eq_i32 s66, 0xdc
	s_cselect_b32 s29, s23, s5
	s_cselect_b32 s28, s22, s4
	s_cselect_b32 s27, s25, s65
	s_cselect_b32 s26, s24, s64
	v_lshl_add_u64 v[210:211], s[18:19], 0, v[202:203]
	s_add_i32 m0, s17, 0xc000
	ds_read_b128 v[162:165], v249
	ds_read_b128 v[166:169], v249 offset:1024
	ds_read_b128 v[170:173], v249 offset:2048
	ds_read_b128 v[174:177], v249 offset:3072
	ds_read_b128 v[178:181], v249 offset:4096
	ds_read_b128 v[182:185], v249 offset:5120
	ds_read_b128 v[186:189], v249 offset:6144
	ds_read_b128 v[190:193], v249 offset:7168
	global_load_lds_dwordx4 v[210:211], off
	v_lshl_add_u64 v[210:211], s[18:19], 0, v[204:205]
	s_add_i32 m0, s17, 0xe000
	s_nop 0
	global_load_lds_dwordx4 v[210:211], off
	s_waitcnt vmcnt(8)
	s_waitcnt lgkmcnt(0)
	s_barrier
	v_mfma_f32_16x16x32_bf16 v[150:153], v[114:117], v[162:165], v[150:153]
	v_mfma_f32_16x16x32_bf16 v[150:153], v[118:121], v[166:169], v[150:153]
	v_mfma_f32_16x16x32_bf16 v[146:149], v[126:129], v[162:165], v[146:149]
	v_mfma_f32_16x16x32_bf16 v[146:149], v[134:137], v[166:169], v[146:149]
	v_mfma_f32_16x16x32_bf16 v[110:113], v[114:117], v[170:173], v[110:113]
	v_mfma_f32_16x16x32_bf16 v[110:113], v[118:121], v[174:177], v[110:113]
	v_mfma_f32_16x16x32_bf16 v[106:109], v[126:129], v[170:173], v[106:109]
	v_mfma_f32_16x16x32_bf16 v[106:109], v[134:137], v[174:177], v[106:109]
	v_mfma_f32_16x16x32_bf16 v[94:97], v[114:117], v[178:181], v[94:97]
	v_mfma_f32_16x16x32_bf16 v[94:97], v[118:121], v[182:185], v[94:97]
	v_mfma_f32_16x16x32_bf16 v[90:93], v[126:129], v[178:181], v[90:93]
	v_mfma_f32_16x16x32_bf16 v[90:93], v[134:137], v[182:185], v[90:93]
	v_mfma_f32_16x16x32_bf16 v[78:81], v[114:117], v[186:189], v[78:81]
	v_mfma_f32_16x16x32_bf16 v[78:81], v[118:121], v[190:193], v[78:81]
	v_mfma_f32_16x16x32_bf16 v[74:77], v[126:129], v[186:189], v[74:77]
	v_mfma_f32_16x16x32_bf16 v[74:77], v[134:137], v[190:193], v[74:77]
	v_mfma_f32_16x16x32_bf16 v[130:133], v[138:141], v[162:165], v[130:133]
	v_mfma_f32_16x16x32_bf16 v[130:133], v[142:145], v[166:169], v[130:133]
	v_mfma_f32_16x16x32_bf16 v[122:125], v[154:157], v[162:165], v[122:125]
	v_mfma_f32_16x16x32_bf16 v[122:125], v[158:161], v[166:169], v[122:125]
	v_mfma_f32_16x16x32_bf16 v[102:105], v[138:141], v[170:173], v[102:105]
	v_mfma_f32_16x16x32_bf16 v[102:105], v[142:145], v[174:177], v[102:105]
	v_mfma_f32_16x16x32_bf16 v[98:101], v[154:157], v[170:173], v[98:101]
	v_mfma_f32_16x16x32_bf16 v[98:101], v[158:161], v[174:177], v[98:101]
	v_mfma_f32_16x16x32_bf16 v[86:89], v[138:141], v[178:181], v[86:89]
	v_mfma_f32_16x16x32_bf16 v[86:89], v[142:145], v[182:185], v[86:89]
	v_mfma_f32_16x16x32_bf16 v[82:85], v[154:157], v[178:181], v[82:85]
	v_mfma_f32_16x16x32_bf16 v[82:85], v[158:161], v[182:185], v[82:85]
	v_mfma_f32_16x16x32_bf16 v[70:73], v[138:141], v[186:189], v[70:73]
	v_mfma_f32_16x16x32_bf16 v[70:73], v[142:145], v[190:193], v[70:73]
	v_mfma_f32_16x16x32_bf16 v[66:69], v[154:157], v[186:189], v[66:69]
	v_mfma_f32_16x16x32_bf16 v[66:69], v[158:161], v[190:193], v[66:69]
	s_barrier
	s_add_i32 s18, s42, s16
	v_lshl_add_u64 v[210:211], s[26:27], 0, v[196:197]
	s_mov_b32 m0, s18
	ds_read_b128 v[162:165], v249 offset:16384
	ds_read_b128 v[166:169], v249 offset:17408
	ds_read_b128 v[170:173], v249 offset:18432
	ds_read_b128 v[174:177], v249 offset:19456
	ds_read_b128 v[178:181], v249 offset:20480
	ds_read_b128 v[182:185], v249 offset:21504
	ds_read_b128 v[186:189], v249 offset:22528
	ds_read_b128 v[190:193], v249 offset:23552
	global_load_lds_dwordx4 v[210:211], off
	s_add_i32 m0, s18, 0x2000
	s_add_u32 s18, s26, 0x380000
	v_lshl_add_u64 v[212:213], s[26:27], 0, v[200:201]
	s_addc_u32 s19, s27, 0
	s_add_i32 s67, s43, s16
	global_load_lds_dwordx4 v[212:213], off
	v_lshl_add_u64 v[214:215], s[18:19], 0, v[196:197]
	s_mov_b32 m0, s67
	v_lshl_add_u64 v[216:217], s[28:29], 0, v[198:199]
	global_load_lds_dwordx4 v[214:215], off
	v_lshl_add_u64 v[214:215], s[18:19], 0, v[200:201]
	s_add_i32 m0, s67, 0x2000
	s_nop 0
	global_load_lds_dwordx4 v[214:215], off
	v_lshl_add_u64 v[214:215], s[28:29], 0, v[194:195]
	s_mov_b32 m0, s17
	s_nop 0
	global_load_lds_dwordx4 v[214:215], off
	s_mov_b32 m0, s30
	s_nop 0
	global_load_lds_dwordx4 v[216:217], off
	s_waitcnt vmcnt(8)
	s_waitcnt lgkmcnt(0)
	s_barrier
	v_mfma_f32_16x16x32_bf16 v[62:65], v[114:117], v[162:165], v[62:65]
	v_mfma_f32_16x16x32_bf16 v[62:65], v[118:121], v[166:169], v[62:65]
	v_mfma_f32_16x16x32_bf16 v[58:61], v[126:129], v[162:165], v[58:61]
	v_mfma_f32_16x16x32_bf16 v[58:61], v[134:137], v[166:169], v[58:61]
	v_mfma_f32_16x16x32_bf16 v[46:49], v[114:117], v[170:173], v[46:49]
	v_mfma_f32_16x16x32_bf16 v[46:49], v[118:121], v[174:177], v[46:49]
	v_mfma_f32_16x16x32_bf16 v[42:45], v[126:129], v[170:173], v[42:45]
	v_mfma_f32_16x16x32_bf16 v[42:45], v[134:137], v[174:177], v[42:45]
	v_mfma_f32_16x16x32_bf16 v[30:33], v[114:117], v[178:181], v[30:33]
	v_mfma_f32_16x16x32_bf16 v[30:33], v[118:121], v[182:185], v[30:33]
	v_mfma_f32_16x16x32_bf16 v[26:29], v[126:129], v[178:181], v[26:29]
	v_mfma_f32_16x16x32_bf16 v[26:29], v[134:137], v[182:185], v[26:29]
	v_mfma_f32_16x16x32_bf16 v[14:17], v[114:117], v[186:189], v[14:17]
	v_mfma_f32_16x16x32_bf16 v[14:17], v[118:121], v[190:193], v[14:17]
	v_mfma_f32_16x16x32_bf16 v[10:13], v[126:129], v[186:189], v[10:13]
	v_mfma_f32_16x16x32_bf16 v[10:13], v[134:137], v[190:193], v[10:13]
	v_mfma_f32_16x16x32_bf16 v[54:57], v[138:141], v[162:165], v[54:57]
	v_mfma_f32_16x16x32_bf16 v[54:57], v[142:145], v[166:169], v[54:57]
	v_mfma_f32_16x16x32_bf16 v[50:53], v[154:157], v[162:165], v[50:53]
	v_mfma_f32_16x16x32_bf16 v[50:53], v[158:161], v[166:169], v[50:53]
	v_mfma_f32_16x16x32_bf16 v[38:41], v[138:141], v[170:173], v[38:41]
	v_mfma_f32_16x16x32_bf16 v[38:41], v[142:145], v[174:177], v[38:41]
	v_mfma_f32_16x16x32_bf16 v[34:37], v[154:157], v[170:173], v[34:37]
	v_mfma_f32_16x16x32_bf16 v[34:37], v[158:161], v[174:177], v[34:37]
	v_mfma_f32_16x16x32_bf16 v[22:25], v[138:141], v[178:181], v[22:25]
	v_mfma_f32_16x16x32_bf16 v[22:25], v[142:145], v[182:185], v[22:25]
	v_mfma_f32_16x16x32_bf16 v[18:21], v[154:157], v[178:181], v[18:21]
	v_mfma_f32_16x16x32_bf16 v[18:21], v[158:161], v[182:185], v[18:21]
	v_mfma_f32_16x16x32_bf16 v[6:9], v[138:141], v[186:189], v[6:9]
	v_mfma_f32_16x16x32_bf16 v[6:9], v[142:145], v[190:193], v[6:9]
	v_mfma_f32_16x16x32_bf16 v[2:5], v[154:157], v[186:189], v[2:5]
	v_mfma_f32_16x16x32_bf16 v[2:5], v[158:161], v[190:193], v[2:5]
	s_barrier
	s_add_i32 s67, 0, 0x18000
	s_add_i32 s68, 0, 0x1c000
	v_add_u32_e32 v134, s67, v244
	v_add_u32_e32 v158, s68, v244
	ds_read_b128 v[114:117], v134
	ds_read_b128 v[118:121], v134 offset:1024
	ds_read_b128 v[126:129], v134 offset:2048
	ds_read_b128 v[134:137], v134 offset:3072
	ds_read_b128 v[138:141], v158
	ds_read_b128 v[142:145], v158 offset:1024
	ds_read_b128 v[154:157], v158 offset:2048
	ds_read_b128 v[158:161], v158 offset:3072
	s_add_u32 s18, s28, 0x380000
	s_addc_u32 s19, s29, 0
	s_mov_b32 m0, s31
	v_lshl_add_u64 v[218:219], s[18:19], 0, v[194:195]
	ds_read_b128 v[162:165], v249 offset:32768
	ds_read_b128 v[166:169], v249 offset:33792
	ds_read_b128 v[170:173], v249 offset:34816
	ds_read_b128 v[174:177], v249 offset:35840
	ds_read_b128 v[178:181], v249 offset:36864
	ds_read_b128 v[182:185], v249 offset:37888
	ds_read_b128 v[186:189], v249 offset:38912
	ds_read_b128 v[190:193], v249 offset:39936
	global_load_lds_dwordx4 v[218:219], off
	v_lshl_add_u64 v[218:219], s[18:19], 0, v[198:199]
	s_mov_b32 m0, s34
	s_nop 0
	global_load_lds_dwordx4 v[218:219], off
	s_waitcnt vmcnt(8)
	s_waitcnt lgkmcnt(0)
	s_barrier
	v_mfma_f32_16x16x32_bf16 v[150:153], v[114:117], v[162:165], v[150:153]
	v_mfma_f32_16x16x32_bf16 v[150:153], v[118:121], v[166:169], v[150:153]
	v_mfma_f32_16x16x32_bf16 v[146:149], v[126:129], v[162:165], v[146:149]
	v_mfma_f32_16x16x32_bf16 v[146:149], v[134:137], v[166:169], v[146:149]
	v_mfma_f32_16x16x32_bf16 v[110:113], v[114:117], v[170:173], v[110:113]
	v_mfma_f32_16x16x32_bf16 v[110:113], v[118:121], v[174:177], v[110:113]
	v_mfma_f32_16x16x32_bf16 v[106:109], v[126:129], v[170:173], v[106:109]
	v_mfma_f32_16x16x32_bf16 v[106:109], v[134:137], v[174:177], v[106:109]
	v_mfma_f32_16x16x32_bf16 v[94:97], v[114:117], v[178:181], v[94:97]
	v_mfma_f32_16x16x32_bf16 v[94:97], v[118:121], v[182:185], v[94:97]
	v_mfma_f32_16x16x32_bf16 v[90:93], v[126:129], v[178:181], v[90:93]
	v_mfma_f32_16x16x32_bf16 v[90:93], v[134:137], v[182:185], v[90:93]
	v_mfma_f32_16x16x32_bf16 v[78:81], v[114:117], v[186:189], v[78:81]
	v_mfma_f32_16x16x32_bf16 v[78:81], v[118:121], v[190:193], v[78:81]
	v_mfma_f32_16x16x32_bf16 v[74:77], v[126:129], v[186:189], v[74:77]
	v_mfma_f32_16x16x32_bf16 v[74:77], v[134:137], v[190:193], v[74:77]
	v_mfma_f32_16x16x32_bf16 v[130:133], v[138:141], v[162:165], v[130:133]
	v_mfma_f32_16x16x32_bf16 v[130:133], v[142:145], v[166:169], v[130:133]
	v_mfma_f32_16x16x32_bf16 v[122:125], v[154:157], v[162:165], v[122:125]
	v_mfma_f32_16x16x32_bf16 v[122:125], v[158:161], v[166:169], v[122:125]
	v_mfma_f32_16x16x32_bf16 v[102:105], v[138:141], v[170:173], v[102:105]
	v_mfma_f32_16x16x32_bf16 v[102:105], v[142:145], v[174:177], v[102:105]
	v_mfma_f32_16x16x32_bf16 v[98:101], v[154:157], v[170:173], v[98:101]
	v_mfma_f32_16x16x32_bf16 v[98:101], v[158:161], v[174:177], v[98:101]
	v_mfma_f32_16x16x32_bf16 v[86:89], v[138:141], v[178:181], v[86:89]
	v_mfma_f32_16x16x32_bf16 v[86:89], v[142:145], v[182:185], v[86:89]
	v_mfma_f32_16x16x32_bf16 v[82:85], v[154:157], v[178:181], v[82:85]
	v_mfma_f32_16x16x32_bf16 v[82:85], v[158:161], v[182:185], v[82:85]
	v_mfma_f32_16x16x32_bf16 v[70:73], v[138:141], v[186:189], v[70:73]
	v_mfma_f32_16x16x32_bf16 v[70:73], v[142:145], v[190:193], v[70:73]
	v_mfma_f32_16x16x32_bf16 v[66:69], v[154:157], v[186:189], v[66:69]
	v_mfma_f32_16x16x32_bf16 v[66:69], v[158:161], v[190:193], v[66:69]
	s_barrier
	s_add_i32 s18, s67, s16
	v_lshl_add_u64 v[210:211], v[210:211], 0, s[12:13]
	s_mov_b32 m0, s18
	ds_read_b128 v[162:165], v249 offset:49152
	ds_read_b128 v[166:169], v249 offset:50176
	ds_read_b128 v[170:173], v249 offset:51200
	ds_read_b128 v[174:177], v249 offset:52224
	ds_read_b128 v[178:181], v249 offset:53248
	ds_read_b128 v[182:185], v249 offset:54272
	ds_read_b128 v[186:189], v249 offset:55296
	ds_read_b128 v[190:193], v249 offset:56320
	global_load_lds_dwordx4 v[210:211], off
	s_add_i32 m0, s18, 0x2000
	s_add_u32 s18, s26, 0x380080
	v_lshl_add_u64 v[210:211], v[212:213], 0, s[12:13]
	s_addc_u32 s19, s27, 0
	s_add_i32 s26, s68, s16
	global_load_lds_dwordx4 v[210:211], off
	v_lshl_add_u64 v[210:211], s[18:19], 0, v[196:197]
	s_mov_b32 m0, s26
	s_nop 0
	global_load_lds_dwordx4 v[210:211], off
	v_lshl_add_u64 v[210:211], s[18:19], 0, v[200:201]
	s_add_i32 m0, s26, 0x2000
	s_nop 0
	global_load_lds_dwordx4 v[210:211], off
	v_lshl_add_u64 v[210:211], v[214:215], 0, s[12:13]
	s_mov_b32 m0, s38
	s_nop 0
	global_load_lds_dwordx4 v[210:211], off
	v_lshl_add_u64 v[210:211], v[216:217], 0, s[12:13]
	s_mov_b32 m0, s39
	s_nop 0
	global_load_lds_dwordx4 v[210:211], off
	s_waitcnt vmcnt(8)
	s_waitcnt lgkmcnt(0)
	s_barrier
	v_mfma_f32_16x16x32_bf16 v[62:65], v[114:117], v[162:165], v[62:65]
	v_mfma_f32_16x16x32_bf16 v[62:65], v[118:121], v[166:169], v[62:65]
	v_mfma_f32_16x16x32_bf16 v[58:61], v[126:129], v[162:165], v[58:61]
	v_mfma_f32_16x16x32_bf16 v[58:61], v[134:137], v[166:169], v[58:61]
	v_mfma_f32_16x16x32_bf16 v[46:49], v[114:117], v[170:173], v[46:49]
	v_mfma_f32_16x16x32_bf16 v[46:49], v[118:121], v[174:177], v[46:49]
	v_mfma_f32_16x16x32_bf16 v[42:45], v[126:129], v[170:173], v[42:45]
	v_mfma_f32_16x16x32_bf16 v[42:45], v[134:137], v[174:177], v[42:45]
	v_mfma_f32_16x16x32_bf16 v[30:33], v[114:117], v[178:181], v[30:33]
	v_mfma_f32_16x16x32_bf16 v[30:33], v[118:121], v[182:185], v[30:33]
	v_mfma_f32_16x16x32_bf16 v[26:29], v[126:129], v[178:181], v[26:29]
	v_mfma_f32_16x16x32_bf16 v[26:29], v[134:137], v[182:185], v[26:29]
	v_mfma_f32_16x16x32_bf16 v[14:17], v[114:117], v[186:189], v[14:17]
	v_mfma_f32_16x16x32_bf16 v[14:17], v[118:121], v[190:193], v[14:17]
	v_mfma_f32_16x16x32_bf16 v[10:13], v[126:129], v[186:189], v[10:13]
	v_mfma_f32_16x16x32_bf16 v[10:13], v[134:137], v[190:193], v[10:13]
	v_mfma_f32_16x16x32_bf16 v[54:57], v[138:141], v[162:165], v[54:57]
	v_mfma_f32_16x16x32_bf16 v[54:57], v[142:145], v[166:169], v[54:57]
	v_mfma_f32_16x16x32_bf16 v[50:53], v[154:157], v[162:165], v[50:53]
	v_mfma_f32_16x16x32_bf16 v[50:53], v[158:161], v[166:169], v[50:53]
	v_mfma_f32_16x16x32_bf16 v[38:41], v[138:141], v[170:173], v[38:41]
	v_mfma_f32_16x16x32_bf16 v[38:41], v[142:145], v[174:177], v[38:41]
	v_mfma_f32_16x16x32_bf16 v[34:37], v[154:157], v[170:173], v[34:37]
	v_mfma_f32_16x16x32_bf16 v[34:37], v[158:161], v[174:177], v[34:37]
	v_mfma_f32_16x16x32_bf16 v[22:25], v[138:141], v[178:181], v[22:25]
	v_mfma_f32_16x16x32_bf16 v[22:25], v[142:145], v[182:185], v[22:25]
	v_mfma_f32_16x16x32_bf16 v[18:21], v[154:157], v[178:181], v[18:21]
	v_mfma_f32_16x16x32_bf16 v[18:21], v[158:161], v[182:185], v[18:21]
	v_mfma_f32_16x16x32_bf16 v[6:9], v[138:141], v[186:189], v[6:9]
	v_mfma_f32_16x16x32_bf16 v[6:9], v[142:145], v[190:193], v[6:9]
	v_mfma_f32_16x16x32_bf16 v[2:5], v[154:157], v[186:189], v[2:5]
	v_mfma_f32_16x16x32_bf16 v[2:5], v[158:161], v[190:193], v[2:5]
	s_barrier
	s_add_i32 s66, s66, 2
	s_add_u32 s64, s64, 0x100
	s_addc_u32 s65, s65, 0
	s_cmpk_gt_u32 s66, 0xdd
	s_mov_b64 s[18:19], s[4:5]
	s_cbranch_scc0 .LBB0_1554
	s_and_b64 vcc, exec, s[14:15]
	s_cbranch_vccz .LBB0_1557
	s_barrier

.LBB0_1646:
	s_ashr_i32 s63, s62, 31
	s_lshl_b64 s[0:1], s[62:63], 21
	s_add_u32 s64, s52, s0
	s_addc_u32 s65, s53, s1
	s_and_b64 s[0:1], s[4:5], exec
	s_cselect_b32 s0, s65, s11
	s_cselect_b32 s1, s64, s10
	s_ashr_i32 s61, s60, 31
	s_lshl_b64 s[16:17], s[60:61], 21
	s_add_u32 s66, s31, s16
	s_addc_u32 s67, s35, s17
	s_and_b64 s[16:17], s[4:5], exec
	s_cselect_b32 s7, s67, s19
	s_cselect_b32 s9, s66, s18
	s_add_u32 s10, s10, 0x100080
	s_addc_u32 s11, s11, 0
	s_add_u32 s16, s18, 0x100
	s_addc_u32 s17, s19, 0
	s_mov_b32 s61, -2
	s_waitcnt lgkmcnt(0)
	ds_read_b128 v[30:33], v200
	ds_read_b128 v[38:41], v200 offset:1024
	ds_read_b128 v[42:45], v200 offset:2048
	ds_read_b128 v[50:53], v200 offset:3072
	ds_read_b128 v[164:167], v201
	ds_read_b128 v[168:171], v201 offset:1024
	ds_read_b128 v[172:175], v201 offset:2048
	ds_read_b128 v[176:179], v201 offset:3072
	s_add_u32 s18, s10, 0xfff00080
	s_addc_u32 s19, s11, -1
	s_cmp_eq_u32 s61, 60
	s_cselect_b32 s69, s0, s19
	s_cselect_b32 s68, s1, s18
	s_cselect_b32 s19, s7, s17
	s_cselect_b32 s18, s9, s16
	v_lshl_add_u64 v[222:223], s[10:11], 0, v[156:157]
	s_add_i32 m0, s39, 0xc000
	ds_read_b128 v[180:183], v202
	ds_read_b128 v[184:187], v202 offset:1024
	ds_read_b128 v[188:191], v202 offset:2048
	ds_read_b128 v[192:195], v202 offset:3072
	ds_read_b128 v[206:209], v202 offset:4096
	ds_read_b128 v[210:213], v202 offset:5120
	ds_read_b128 v[214:217], v202 offset:6144
	ds_read_b128 v[218:221], v202 offset:7168
	global_load_lds_dwordx4 v[222:223], off
	v_lshl_add_u64 v[222:223], s[10:11], 0, v[158:159]
	s_add_i32 m0, s39, 0xe000
	s_nop 0
	global_load_lds_dwordx4 v[222:223], off
	s_waitcnt vmcnt(8)
	s_waitcnt lgkmcnt(0)
	s_barrier
	v_mfma_f32_16x16x32_bf16 v[138:141], v[30:33], v[180:183], 0
	v_mfma_f32_16x16x32_bf16 v[138:141], v[38:41], v[184:187], v[138:141]
	v_mfma_f32_16x16x32_bf16 v[142:145], v[42:45], v[180:183], 0
	v_mfma_f32_16x16x32_bf16 v[142:145], v[50:53], v[184:187], v[142:145]
	v_mfma_f32_16x16x32_bf16 v[122:125], v[30:33], v[188:191], 0
	v_mfma_f32_16x16x32_bf16 v[122:125], v[38:41], v[192:195], v[122:125]
	v_mfma_f32_16x16x32_bf16 v[126:129], v[42:45], v[188:191], 0
	v_mfma_f32_16x16x32_bf16 v[126:129], v[50:53], v[192:195], v[126:129]
	v_mfma_f32_16x16x32_bf16 v[106:109], v[30:33], v[206:209], 0
	v_mfma_f32_16x16x32_bf16 v[106:109], v[38:41], v[210:213], v[106:109]
	v_mfma_f32_16x16x32_bf16 v[110:113], v[42:45], v[206:209], 0
	v_mfma_f32_16x16x32_bf16 v[110:113], v[50:53], v[210:213], v[110:113]
	v_mfma_f32_16x16x32_bf16 v[90:93], v[30:33], v[214:217], 0
	v_mfma_f32_16x16x32_bf16 v[90:93], v[38:41], v[218:221], v[90:93]
	v_mfma_f32_16x16x32_bf16 v[94:97], v[42:45], v[214:217], 0
	v_mfma_f32_16x16x32_bf16 v[94:97], v[50:53], v[218:221], v[94:97]
	v_mfma_f32_16x16x32_bf16 v[130:133], v[164:167], v[180:183], 0
	v_mfma_f32_16x16x32_bf16 v[130:133], v[168:171], v[184:187], v[130:133]
	v_mfma_f32_16x16x32_bf16 v[134:137], v[172:175], v[180:183], 0
	v_mfma_f32_16x16x32_bf16 v[134:137], v[176:179], v[184:187], v[134:137]
	v_mfma_f32_16x16x32_bf16 v[114:117], v[164:167], v[188:191], 0
	v_mfma_f32_16x16x32_bf16 v[114:117], v[168:171], v[192:195], v[114:117]
	v_mfma_f32_16x16x32_bf16 v[118:121], v[172:175], v[188:191], 0
	v_mfma_f32_16x16x32_bf16 v[118:121], v[176:179], v[192:195], v[118:121]
	v_mfma_f32_16x16x32_bf16 v[98:101], v[164:167], v[206:209], 0
	v_mfma_f32_16x16x32_bf16 v[98:101], v[168:171], v[210:213], v[98:101]
	v_mfma_f32_16x16x32_bf16 v[102:105], v[172:175], v[206:209], 0
	v_mfma_f32_16x16x32_bf16 v[102:105], v[176:179], v[210:213], v[102:105]
	v_mfma_f32_16x16x32_bf16 v[82:85], v[164:167], v[214:217], 0
	v_mfma_f32_16x16x32_bf16 v[82:85], v[168:171], v[218:221], v[82:85]
	v_mfma_f32_16x16x32_bf16 v[86:89], v[172:175], v[214:217], 0
	v_mfma_f32_16x16x32_bf16 v[86:89], v[176:179], v[218:221], v[86:89]
	s_barrier
	s_add_i32 s63, s77, s37
	v_lshl_add_u64 v[222:223], s[18:19], 0, v[148:149]
	s_mov_b32 m0, s63
	ds_read_b128 v[180:183], v202 offset:16384
	ds_read_b128 v[184:187], v202 offset:17408
	ds_read_b128 v[188:191], v202 offset:18432
	ds_read_b128 v[192:195], v202 offset:19456
	ds_read_b128 v[206:209], v202 offset:20480
	ds_read_b128 v[210:213], v202 offset:21504
	ds_read_b128 v[214:217], v202 offset:22528
	ds_read_b128 v[218:221], v202 offset:23552
	global_load_lds_dwordx4 v[222:223], off
	s_add_i32 m0, s63, 0x2000
	s_add_u32 s82, s18, 0x100000
	v_lshl_add_u64 v[224:225], s[18:19], 0, v[152:153]
	s_addc_u32 s83, s19, 0
	s_add_i32 s63, s78, s37
	global_load_lds_dwordx4 v[224:225], off
	v_lshl_add_u64 v[226:227], s[82:83], 0, v[148:149]
	s_mov_b32 m0, s63
	v_lshl_add_u64 v[228:229], s[68:69], 0, v[150:151]
	global_load_lds_dwordx4 v[226:227], off
	v_lshl_add_u64 v[226:227], s[82:83], 0, v[152:153]
	s_add_i32 m0, s63, 0x2000
	s_nop 0
	global_load_lds_dwordx4 v[226:227], off
	v_lshl_add_u64 v[226:227], s[68:69], 0, v[146:147]
	s_mov_b32 m0, s39
	s_nop 0
	global_load_lds_dwordx4 v[226:227], off
	s_mov_b32 m0, s41
	s_nop 0
	global_load_lds_dwordx4 v[228:229], off
	s_waitcnt vmcnt(8)
	s_waitcnt lgkmcnt(0)
	s_barrier
	v_mfma_f32_16x16x32_bf16 v[74:77], v[30:33], v[180:183], 0
	v_mfma_f32_16x16x32_bf16 v[74:77], v[38:41], v[184:187], v[74:77]
	v_mfma_f32_16x16x32_bf16 v[78:81], v[42:45], v[180:183], 0
	v_mfma_f32_16x16x32_bf16 v[78:81], v[50:53], v[184:187], v[78:81]
	v_mfma_f32_16x16x32_bf16 v[58:61], v[30:33], v[188:191], 0
	v_mfma_f32_16x16x32_bf16 v[58:61], v[38:41], v[192:195], v[58:61]
	v_mfma_f32_16x16x32_bf16 v[62:65], v[42:45], v[188:191], 0
	v_mfma_f32_16x16x32_bf16 v[62:65], v[50:53], v[192:195], v[62:65]
	v_mfma_f32_16x16x32_bf16 v[26:29], v[30:33], v[206:209], 0
	v_mfma_f32_16x16x32_bf16 v[26:29], v[38:41], v[210:213], v[26:29]
	v_mfma_f32_16x16x32_bf16 v[34:37], v[42:45], v[206:209], 0
	v_mfma_f32_16x16x32_bf16 v[34:37], v[50:53], v[210:213], v[34:37]
	v_mfma_f32_16x16x32_bf16 v[10:13], v[30:33], v[214:217], 0
	v_mfma_f32_16x16x32_bf16 v[10:13], v[38:41], v[218:221], v[10:13]
	v_mfma_f32_16x16x32_bf16 v[14:17], v[42:45], v[214:217], 0
	v_mfma_f32_16x16x32_bf16 v[14:17], v[50:53], v[218:221], v[14:17]
	v_mfma_f32_16x16x32_bf16 v[18:21], v[164:167], v[206:209], 0
	v_mfma_f32_16x16x32_bf16 v[18:21], v[168:171], v[210:213], v[18:21]
	v_mfma_f32_16x16x32_bf16 v[22:25], v[172:175], v[206:209], 0
	v_mfma_f32_16x16x32_bf16 v[22:25], v[176:179], v[210:213], v[22:25]
	v_mfma_f32_16x16x32_bf16 v[2:5], v[164:167], v[214:217], 0
	v_mfma_f32_16x16x32_bf16 v[2:5], v[168:171], v[218:221], v[2:5]
	v_mfma_f32_16x16x32_bf16 v[6:9], v[172:175], v[214:217], 0
	v_mfma_f32_16x16x32_bf16 v[6:9], v[176:179], v[218:221], v[6:9]
	v_mfma_f32_16x16x32_bf16 v[30:33], v[164:167], v[180:183], 0
	v_mfma_f32_16x16x32_bf16 v[30:33], v[168:171], v[184:187], v[30:33]
	v_mfma_f32_16x16x32_bf16 v[38:41], v[172:175], v[180:183], 0
	v_mfma_f32_16x16x32_bf16 v[38:41], v[176:179], v[184:187], v[38:41]
	v_mfma_f32_16x16x32_bf16 v[42:45], v[164:167], v[188:191], 0
	v_mfma_f32_16x16x32_bf16 v[42:45], v[168:171], v[192:195], v[42:45]
	v_mfma_f32_16x16x32_bf16 v[46:49], v[172:175], v[188:191], 0
	v_mfma_f32_16x16x32_bf16 v[50:53], v[176:179], v[192:195], v[46:49]
	s_barrier
	s_add_i32 s63, 0, 0x18000
	s_add_i32 s82, 0, 0x1c000
	v_add_u32_e32 v70, s63, v196
	v_add_u32_e32 v155, s82, v196
	ds_read_b128 v[46:49], v70
	ds_read_b128 v[54:57], v70 offset:1024
	ds_read_b128 v[66:69], v70 offset:2048
	ds_read_b128 v[70:73], v70 offset:3072
	ds_read_b128 v[164:167], v155
	ds_read_b128 v[168:171], v155 offset:1024
	ds_read_b128 v[172:175], v155 offset:2048
	ds_read_b128 v[176:179], v155 offset:3072
	s_add_u32 s68, s68, 0x100000
	s_addc_u32 s69, s69, 0
	s_mov_b32 m0, s43
	v_lshl_add_u64 v[230:231], s[68:69], 0, v[146:147]
	ds_read_b128 v[180:183], v202 offset:32768
	ds_read_b128 v[184:187], v202 offset:33792
	ds_read_b128 v[188:191], v202 offset:34816
	ds_read_b128 v[192:195], v202 offset:35840
	ds_read_b128 v[206:209], v202 offset:36864
	ds_read_b128 v[210:213], v202 offset:37888
	ds_read_b128 v[214:217], v202 offset:38912
	ds_read_b128 v[218:221], v202 offset:39936
	global_load_lds_dwordx4 v[230:231], off
	v_lshl_add_u64 v[230:231], s[68:69], 0, v[150:151]
	s_mov_b32 m0, s57
	s_nop 0
	global_load_lds_dwordx4 v[230:231], off
	s_waitcnt vmcnt(8)
	s_waitcnt lgkmcnt(0)
	s_barrier
	v_mfma_f32_16x16x32_bf16 v[138:141], v[46:49], v[180:183], v[138:141]
	v_mfma_f32_16x16x32_bf16 v[138:141], v[54:57], v[184:187], v[138:141]
	v_mfma_f32_16x16x32_bf16 v[142:145], v[66:69], v[180:183], v[142:145]
	v_mfma_f32_16x16x32_bf16 v[142:145], v[70:73], v[184:187], v[142:145]
	v_mfma_f32_16x16x32_bf16 v[122:125], v[46:49], v[188:191], v[122:125]
	v_mfma_f32_16x16x32_bf16 v[122:125], v[54:57], v[192:195], v[122:125]
	v_mfma_f32_16x16x32_bf16 v[126:129], v[66:69], v[188:191], v[126:129]
	v_mfma_f32_16x16x32_bf16 v[126:129], v[70:73], v[192:195], v[126:129]
	v_mfma_f32_16x16x32_bf16 v[106:109], v[46:49], v[206:209], v[106:109]
	v_mfma_f32_16x16x32_bf16 v[106:109], v[54:57], v[210:213], v[106:109]
	v_mfma_f32_16x16x32_bf16 v[110:113], v[66:69], v[206:209], v[110:113]
	v_mfma_f32_16x16x32_bf16 v[110:113], v[70:73], v[210:213], v[110:113]
	v_mfma_f32_16x16x32_bf16 v[90:93], v[46:49], v[214:217], v[90:93]
	v_mfma_f32_16x16x32_bf16 v[90:93], v[54:57], v[218:221], v[90:93]
	v_mfma_f32_16x16x32_bf16 v[94:97], v[66:69], v[214:217], v[94:97]
	v_mfma_f32_16x16x32_bf16 v[94:97], v[70:73], v[218:221], v[94:97]
	v_mfma_f32_16x16x32_bf16 v[130:133], v[164:167], v[180:183], v[130:133]
	v_mfma_f32_16x16x32_bf16 v[130:133], v[168:171], v[184:187], v[130:133]
	v_mfma_f32_16x16x32_bf16 v[134:137], v[172:175], v[180:183], v[134:137]
	v_mfma_f32_16x16x32_bf16 v[134:137], v[176:179], v[184:187], v[134:137]
	v_mfma_f32_16x16x32_bf16 v[114:117], v[164:167], v[188:191], v[114:117]
	v_mfma_f32_16x16x32_bf16 v[114:117], v[168:171], v[192:195], v[114:117]
	v_mfma_f32_16x16x32_bf16 v[118:121], v[172:175], v[188:191], v[118:121]
	v_mfma_f32_16x16x32_bf16 v[118:121], v[176:179], v[192:195], v[118:121]
	v_mfma_f32_16x16x32_bf16 v[98:101], v[164:167], v[206:209], v[98:101]
	v_mfma_f32_16x16x32_bf16 v[98:101], v[168:171], v[210:213], v[98:101]
	v_mfma_f32_16x16x32_bf16 v[102:105], v[172:175], v[206:209], v[102:105]
	v_mfma_f32_16x16x32_bf16 v[102:105], v[176:179], v[210:213], v[102:105]
	v_mfma_f32_16x16x32_bf16 v[82:85], v[164:167], v[214:217], v[82:85]
	v_mfma_f32_16x16x32_bf16 v[82:85], v[168:171], v[218:221], v[82:85]
	v_mfma_f32_16x16x32_bf16 v[86:89], v[172:175], v[214:217], v[86:89]
	v_mfma_f32_16x16x32_bf16 v[86:89], v[176:179], v[218:221], v[86:89]
	s_barrier
	s_add_i32 s63, s63, s37
	v_lshl_add_u64 v[222:223], v[222:223], 0, s[26:27]
	s_mov_b32 m0, s63
	ds_read_b128 v[180:183], v202 offset:49152
	ds_read_b128 v[184:187], v202 offset:50176
	ds_read_b128 v[188:191], v202 offset:51200
	ds_read_b128 v[192:195], v202 offset:52224
	ds_read_b128 v[206:209], v202 offset:53248
	ds_read_b128 v[210:213], v202 offset:54272
	ds_read_b128 v[214:217], v202 offset:55296
	ds_read_b128 v[218:221], v202 offset:56320
	global_load_lds_dwordx4 v[222:223], off
	s_add_i32 m0, s63, 0x2000
	s_add_u32 s18, s18, 0x100080
	v_lshl_add_u64 v[222:223], v[224:225], 0, s[26:27]
	s_addc_u32 s19, s19, 0
	s_add_i32 s63, s82, s37
	global_load_lds_dwordx4 v[222:223], off
	v_lshl_add_u64 v[222:223], s[18:19], 0, v[148:149]
	s_mov_b32 m0, s63
	s_nop 0
	global_load_lds_dwordx4 v[222:223], off
	v_lshl_add_u64 v[222:223], s[18:19], 0, v[152:153]
	s_add_i32 m0, s63, 0x2000
	s_nop 0
	global_load_lds_dwordx4 v[222:223], off
	v_lshl_add_u64 v[222:223], v[226:227], 0, s[26:27]
	s_mov_b32 m0, s71
	s_nop 0
	global_load_lds_dwordx4 v[222:223], off
	v_lshl_add_u64 v[222:223], v[228:229], 0, s[26:27]
	s_mov_b32 m0, s72
	s_nop 0
	global_load_lds_dwordx4 v[222:223], off
	s_waitcnt vmcnt(8)
	s_waitcnt lgkmcnt(0)
	s_barrier
	v_mfma_f32_16x16x32_bf16 v[74:77], v[46:49], v[180:183], v[74:77]
	v_mfma_f32_16x16x32_bf16 v[74:77], v[54:57], v[184:187], v[74:77]
	v_mfma_f32_16x16x32_bf16 v[78:81], v[66:69], v[180:183], v[78:81]
	v_mfma_f32_16x16x32_bf16 v[78:81], v[70:73], v[184:187], v[78:81]
	v_mfma_f32_16x16x32_bf16 v[58:61], v[46:49], v[188:191], v[58:61]
	v_mfma_f32_16x16x32_bf16 v[58:61], v[54:57], v[192:195], v[58:61]
	v_mfma_f32_16x16x32_bf16 v[62:65], v[66:69], v[188:191], v[62:65]
	v_mfma_f32_16x16x32_bf16 v[62:65], v[70:73], v[192:195], v[62:65]
	v_mfma_f32_16x16x32_bf16 v[26:29], v[46:49], v[206:209], v[26:29]
	v_mfma_f32_16x16x32_bf16 v[26:29], v[54:57], v[210:213], v[26:29]
	v_mfma_f32_16x16x32_bf16 v[34:37], v[66:69], v[206:209], v[34:37]
	v_mfma_f32_16x16x32_bf16 v[34:37], v[70:73], v[210:213], v[34:37]
	v_mfma_f32_16x16x32_bf16 v[10:13], v[46:49], v[214:217], v[10:13]
	v_mfma_f32_16x16x32_bf16 v[10:13], v[54:57], v[218:221], v[10:13]
	v_mfma_f32_16x16x32_bf16 v[14:17], v[66:69], v[214:217], v[14:17]
	v_mfma_f32_16x16x32_bf16 v[14:17], v[70:73], v[218:221], v[14:17]
	v_mfma_f32_16x16x32_bf16 v[30:33], v[164:167], v[180:183], v[30:33]
	v_mfma_f32_16x16x32_bf16 v[66:69], v[168:171], v[184:187], v[30:33]
	v_mfma_f32_16x16x32_bf16 v[30:33], v[172:175], v[180:183], v[38:41]
	v_mfma_f32_16x16x32_bf16 v[70:73], v[176:179], v[184:187], v[30:33]
	v_mfma_f32_16x16x32_bf16 v[30:33], v[164:167], v[188:191], v[42:45]
	v_mfma_f32_16x16x32_bf16 v[46:49], v[168:171], v[192:195], v[30:33]
	v_mfma_f32_16x16x32_bf16 v[30:33], v[172:175], v[188:191], v[50:53]
	v_mfma_f32_16x16x32_bf16 v[54:57], v[176:179], v[192:195], v[30:33]
	v_mfma_f32_16x16x32_bf16 v[18:21], v[164:167], v[206:209], v[18:21]
	v_mfma_f32_16x16x32_bf16 v[18:21], v[168:171], v[210:213], v[18:21]
	v_mfma_f32_16x16x32_bf16 v[22:25], v[172:175], v[206:209], v[22:25]
	v_mfma_f32_16x16x32_bf16 v[22:25], v[176:179], v[210:213], v[22:25]
	v_mfma_f32_16x16x32_bf16 v[2:5], v[164:167], v[214:217], v[2:5]
	v_mfma_f32_16x16x32_bf16 v[2:5], v[168:171], v[218:221], v[2:5]
	v_mfma_f32_16x16x32_bf16 v[6:9], v[172:175], v[214:217], v[6:9]
	v_mfma_f32_16x16x32_bf16 v[6:9], v[176:179], v[218:221], v[6:9]
	s_barrier
	s_add_i32 s61, s61, 2
	s_add_u32 s10, s10, 0x100
	s_addc_u32 s11, s11, 0
	s_add_u32 s16, s16, 0x100
	s_addc_u32 s17, s17, 0
	s_cmp_gt_u32 s61, 61
.LBB0_1647:
	ds_read_b128 v[30:33], v200
	ds_read_b128 v[38:41], v200 offset:1024
	ds_read_b128 v[42:45], v200 offset:2048
	ds_read_b128 v[50:53], v200 offset:3072
	ds_read_b128 v[164:167], v201
	ds_read_b128 v[168:171], v201 offset:1024
	ds_read_b128 v[172:175], v201 offset:2048
	ds_read_b128 v[176:179], v201 offset:3072
	s_add_u32 s18, s10, 0xfff00080
	s_addc_u32 s19, s11, -1
	s_cmp_eq_u32 s61, 60
	s_cselect_b32 s69, s0, s19
	s_cselect_b32 s68, s1, s18
	s_cselect_b32 s19, s7, s17
	s_cselect_b32 s18, s9, s16
	v_lshl_add_u64 v[222:223], s[10:11], 0, v[156:157]
	s_add_i32 m0, s39, 0xc000
	ds_read_b128 v[180:183], v202
	ds_read_b128 v[184:187], v202 offset:1024
	ds_read_b128 v[188:191], v202 offset:2048
	ds_read_b128 v[192:195], v202 offset:3072
	ds_read_b128 v[206:209], v202 offset:4096
	ds_read_b128 v[210:213], v202 offset:5120
	ds_read_b128 v[214:217], v202 offset:6144
	ds_read_b128 v[218:221], v202 offset:7168
	global_load_lds_dwordx4 v[222:223], off
	v_lshl_add_u64 v[222:223], s[10:11], 0, v[158:159]
	s_add_i32 m0, s39, 0xe000
	s_nop 0
	global_load_lds_dwordx4 v[222:223], off
	s_waitcnt vmcnt(8)
	s_waitcnt lgkmcnt(0)
	s_barrier
	v_mfma_f32_16x16x32_bf16 v[138:141], v[30:33], v[180:183], v[138:141]
	v_mfma_f32_16x16x32_bf16 v[138:141], v[38:41], v[184:187], v[138:141]
	v_mfma_f32_16x16x32_bf16 v[142:145], v[42:45], v[180:183], v[142:145]
	v_mfma_f32_16x16x32_bf16 v[142:145], v[50:53], v[184:187], v[142:145]
	v_mfma_f32_16x16x32_bf16 v[122:125], v[30:33], v[188:191], v[122:125]
	v_mfma_f32_16x16x32_bf16 v[122:125], v[38:41], v[192:195], v[122:125]
	v_mfma_f32_16x16x32_bf16 v[126:129], v[42:45], v[188:191], v[126:129]
	v_mfma_f32_16x16x32_bf16 v[126:129], v[50:53], v[192:195], v[126:129]
	v_mfma_f32_16x16x32_bf16 v[106:109], v[30:33], v[206:209], v[106:109]
	v_mfma_f32_16x16x32_bf16 v[106:109], v[38:41], v[210:213], v[106:109]
	v_mfma_f32_16x16x32_bf16 v[110:113], v[42:45], v[206:209], v[110:113]
	v_mfma_f32_16x16x32_bf16 v[110:113], v[50:53], v[210:213], v[110:113]
	v_mfma_f32_16x16x32_bf16 v[90:93], v[30:33], v[214:217], v[90:93]
	v_mfma_f32_16x16x32_bf16 v[90:93], v[38:41], v[218:221], v[90:93]
	v_mfma_f32_16x16x32_bf16 v[94:97], v[42:45], v[214:217], v[94:97]
	v_mfma_f32_16x16x32_bf16 v[94:97], v[50:53], v[218:221], v[94:97]
	v_mfma_f32_16x16x32_bf16 v[130:133], v[164:167], v[180:183], v[130:133]
	v_mfma_f32_16x16x32_bf16 v[130:133], v[168:171], v[184:187], v[130:133]
	v_mfma_f32_16x16x32_bf16 v[134:137], v[172:175], v[180:183], v[134:137]
	v_mfma_f32_16x16x32_bf16 v[134:137], v[176:179], v[184:187], v[134:137]
	v_mfma_f32_16x16x32_bf16 v[114:117], v[164:167], v[188:191], v[114:117]
	v_mfma_f32_16x16x32_bf16 v[114:117], v[168:171], v[192:195], v[114:117]
	v_mfma_f32_16x16x32_bf16 v[118:121], v[172:175], v[188:191], v[118:121]
	v_mfma_f32_16x16x32_bf16 v[118:121], v[176:179], v[192:195], v[118:121]
	v_mfma_f32_16x16x32_bf16 v[98:101], v[164:167], v[206:209], v[98:101]
	v_mfma_f32_16x16x32_bf16 v[98:101], v[168:171], v[210:213], v[98:101]
	v_mfma_f32_16x16x32_bf16 v[102:105], v[172:175], v[206:209], v[102:105]
	v_mfma_f32_16x16x32_bf16 v[102:105], v[176:179], v[210:213], v[102:105]
	v_mfma_f32_16x16x32_bf16 v[82:85], v[164:167], v[214:217], v[82:85]
	v_mfma_f32_16x16x32_bf16 v[82:85], v[168:171], v[218:221], v[82:85]
	v_mfma_f32_16x16x32_bf16 v[86:89], v[172:175], v[214:217], v[86:89]
	v_mfma_f32_16x16x32_bf16 v[86:89], v[176:179], v[218:221], v[86:89]
	s_barrier
	s_add_i32 s63, s77, s37
	v_lshl_add_u64 v[222:223], s[18:19], 0, v[148:149]
	s_mov_b32 m0, s63
	ds_read_b128 v[180:183], v202 offset:16384
	ds_read_b128 v[184:187], v202 offset:17408
	ds_read_b128 v[188:191], v202 offset:18432
	ds_read_b128 v[192:195], v202 offset:19456
	ds_read_b128 v[206:209], v202 offset:20480
	ds_read_b128 v[210:213], v202 offset:21504
	ds_read_b128 v[214:217], v202 offset:22528
	ds_read_b128 v[218:221], v202 offset:23552
	global_load_lds_dwordx4 v[222:223], off
	s_add_i32 m0, s63, 0x2000
	s_add_u32 s82, s18, 0x100000
	v_lshl_add_u64 v[224:225], s[18:19], 0, v[152:153]
	s_addc_u32 s83, s19, 0
	s_add_i32 s63, s78, s37
	global_load_lds_dwordx4 v[224:225], off
	v_lshl_add_u64 v[226:227], s[82:83], 0, v[148:149]
	s_mov_b32 m0, s63
	v_lshl_add_u64 v[228:229], s[68:69], 0, v[150:151]
	global_load_lds_dwordx4 v[226:227], off
	v_lshl_add_u64 v[226:227], s[82:83], 0, v[152:153]
	s_add_i32 m0, s63, 0x2000
	s_nop 0
	global_load_lds_dwordx4 v[226:227], off
	v_lshl_add_u64 v[226:227], s[68:69], 0, v[146:147]
	s_mov_b32 m0, s39
	s_nop 0
	global_load_lds_dwordx4 v[226:227], off
	s_mov_b32 m0, s41
	s_nop 0
	global_load_lds_dwordx4 v[228:229], off
	s_waitcnt vmcnt(8)
	s_waitcnt lgkmcnt(0)
	s_barrier
	v_mfma_f32_16x16x32_bf16 v[74:77], v[30:33], v[180:183], v[74:77]
	v_mfma_f32_16x16x32_bf16 v[74:77], v[38:41], v[184:187], v[74:77]
	v_mfma_f32_16x16x32_bf16 v[78:81], v[42:45], v[180:183], v[78:81]
	v_mfma_f32_16x16x32_bf16 v[78:81], v[50:53], v[184:187], v[78:81]
	v_mfma_f32_16x16x32_bf16 v[58:61], v[30:33], v[188:191], v[58:61]
	v_mfma_f32_16x16x32_bf16 v[58:61], v[38:41], v[192:195], v[58:61]
	v_mfma_f32_16x16x32_bf16 v[62:65], v[42:45], v[188:191], v[62:65]
	v_mfma_f32_16x16x32_bf16 v[62:65], v[50:53], v[192:195], v[62:65]
	v_mfma_f32_16x16x32_bf16 v[26:29], v[30:33], v[206:209], v[26:29]
	v_mfma_f32_16x16x32_bf16 v[26:29], v[38:41], v[210:213], v[26:29]
	v_mfma_f32_16x16x32_bf16 v[34:37], v[42:45], v[206:209], v[34:37]
	v_mfma_f32_16x16x32_bf16 v[34:37], v[50:53], v[210:213], v[34:37]
	v_mfma_f32_16x16x32_bf16 v[10:13], v[30:33], v[214:217], v[10:13]
	v_mfma_f32_16x16x32_bf16 v[10:13], v[38:41], v[218:221], v[10:13]
	v_mfma_f32_16x16x32_bf16 v[14:17], v[42:45], v[214:217], v[14:17]
	v_mfma_f32_16x16x32_bf16 v[14:17], v[50:53], v[218:221], v[14:17]
	v_mfma_f32_16x16x32_bf16 v[18:21], v[164:167], v[206:209], v[18:21]
	v_mfma_f32_16x16x32_bf16 v[18:21], v[168:171], v[210:213], v[18:21]
	v_mfma_f32_16x16x32_bf16 v[22:25], v[172:175], v[206:209], v[22:25]
	v_mfma_f32_16x16x32_bf16 v[22:25], v[176:179], v[210:213], v[22:25]
	v_mfma_f32_16x16x32_bf16 v[2:5], v[164:167], v[214:217], v[2:5]
	v_mfma_f32_16x16x32_bf16 v[2:5], v[168:171], v[218:221], v[2:5]
	v_mfma_f32_16x16x32_bf16 v[6:9], v[172:175], v[214:217], v[6:9]
	v_mfma_f32_16x16x32_bf16 v[6:9], v[176:179], v[218:221], v[6:9]
	v_mfma_f32_16x16x32_bf16 v[30:33], v[164:167], v[180:183], v[66:69]
	v_mfma_f32_16x16x32_bf16 v[30:33], v[168:171], v[184:187], v[30:33]
	v_mfma_f32_16x16x32_bf16 v[38:41], v[172:175], v[180:183], v[70:73]
	v_mfma_f32_16x16x32_bf16 v[38:41], v[176:179], v[184:187], v[38:41]
	v_mfma_f32_16x16x32_bf16 v[42:45], v[164:167], v[188:191], v[46:49]
	v_mfma_f32_16x16x32_bf16 v[42:45], v[168:171], v[192:195], v[42:45]
	v_mfma_f32_16x16x32_bf16 v[46:49], v[172:175], v[188:191], v[54:57]
	v_mfma_f32_16x16x32_bf16 v[50:53], v[176:179], v[192:195], v[46:49]
	s_barrier
	s_add_i32 s63, 0, 0x18000
	s_add_i32 s82, 0, 0x1c000
	v_add_u32_e32 v70, s63, v196
	v_add_u32_e32 v155, s82, v196
	ds_read_b128 v[46:49], v70
	ds_read_b128 v[54:57], v70 offset:1024
	ds_read_b128 v[66:69], v70 offset:2048
	ds_read_b128 v[70:73], v70 offset:3072
	ds_read_b128 v[164:167], v155
	ds_read_b128 v[168:171], v155 offset:1024
	ds_read_b128 v[172:175], v155 offset:2048
	ds_read_b128 v[176:179], v155 offset:3072
	s_add_u32 s68, s68, 0x100000
	s_addc_u32 s69, s69, 0
	s_mov_b32 m0, s43
	v_lshl_add_u64 v[230:231], s[68:69], 0, v[146:147]
	ds_read_b128 v[180:183], v202 offset:32768
	ds_read_b128 v[184:187], v202 offset:33792
	ds_read_b128 v[188:191], v202 offset:34816
	ds_read_b128 v[192:195], v202 offset:35840
	ds_read_b128 v[206:209], v202 offset:36864
	ds_read_b128 v[210:213], v202 offset:37888
	ds_read_b128 v[214:217], v202 offset:38912
	ds_read_b128 v[218:221], v202 offset:39936
	global_load_lds_dwordx4 v[230:231], off
	v_lshl_add_u64 v[230:231], s[68:69], 0, v[150:151]
	s_mov_b32 m0, s57
	s_nop 0
	global_load_lds_dwordx4 v[230:231], off
	s_waitcnt vmcnt(8)
	s_waitcnt lgkmcnt(0)
	s_barrier
	v_mfma_f32_16x16x32_bf16 v[138:141], v[46:49], v[180:183], v[138:141]
	v_mfma_f32_16x16x32_bf16 v[138:141], v[54:57], v[184:187], v[138:141]
	v_mfma_f32_16x16x32_bf16 v[142:145], v[66:69], v[180:183], v[142:145]
	v_mfma_f32_16x16x32_bf16 v[142:145], v[70:73], v[184:187], v[142:145]
	v_mfma_f32_16x16x32_bf16 v[122:125], v[46:49], v[188:191], v[122:125]
	v_mfma_f32_16x16x32_bf16 v[122:125], v[54:57], v[192:195], v[122:125]
	v_mfma_f32_16x16x32_bf16 v[126:129], v[66:69], v[188:191], v[126:129]
	v_mfma_f32_16x16x32_bf16 v[126:129], v[70:73], v[192:195], v[126:129]
	v_mfma_f32_16x16x32_bf16 v[106:109], v[46:49], v[206:209], v[106:109]
	v_mfma_f32_16x16x32_bf16 v[106:109], v[54:57], v[210:213], v[106:109]
	v_mfma_f32_16x16x32_bf16 v[110:113], v[66:69], v[206:209], v[110:113]
	v_mfma_f32_16x16x32_bf16 v[110:113], v[70:73], v[210:213], v[110:113]
	v_mfma_f32_16x16x32_bf16 v[90:93], v[46:49], v[214:217], v[90:93]
	v_mfma_f32_16x16x32_bf16 v[90:93], v[54:57], v[218:221], v[90:93]
	v_mfma_f32_16x16x32_bf16 v[94:97], v[66:69], v[214:217], v[94:97]
	v_mfma_f32_16x16x32_bf16 v[94:97], v[70:73], v[218:221], v[94:97]
	v_mfma_f32_16x16x32_bf16 v[130:133], v[164:167], v[180:183], v[130:133]
	v_mfma_f32_16x16x32_bf16 v[130:133], v[168:171], v[184:187], v[130:133]
	v_mfma_f32_16x16x32_bf16 v[134:137], v[172:175], v[180:183], v[134:137]
	v_mfma_f32_16x16x32_bf16 v[134:137], v[176:179], v[184:187], v[134:137]
	v_mfma_f32_16x16x32_bf16 v[114:117], v[164:167], v[188:191], v[114:117]
	v_mfma_f32_16x16x32_bf16 v[114:117], v[168:171], v[192:195], v[114:117]
	v_mfma_f32_16x16x32_bf16 v[118:121], v[172:175], v[188:191], v[118:121]
	v_mfma_f32_16x16x32_bf16 v[118:121], v[176:179], v[192:195], v[118:121]
	v_mfma_f32_16x16x32_bf16 v[98:101], v[164:167], v[206:209], v[98:101]
	v_mfma_f32_16x16x32_bf16 v[98:101], v[168:171], v[210:213], v[98:101]
	v_mfma_f32_16x16x32_bf16 v[102:105], v[172:175], v[206:209], v[102:105]
	v_mfma_f32_16x16x32_bf16 v[102:105], v[176:179], v[210:213], v[102:105]
	v_mfma_f32_16x16x32_bf16 v[82:85], v[164:167], v[214:217], v[82:85]
	v_mfma_f32_16x16x32_bf16 v[82:85], v[168:171], v[218:221], v[82:85]
	v_mfma_f32_16x16x32_bf16 v[86:89], v[172:175], v[214:217], v[86:89]
	v_mfma_f32_16x16x32_bf16 v[86:89], v[176:179], v[218:221], v[86:89]
	s_barrier
	s_add_i32 s63, s63, s37
	v_lshl_add_u64 v[222:223], v[222:223], 0, s[26:27]
	s_mov_b32 m0, s63
	ds_read_b128 v[180:183], v202 offset:49152
	ds_read_b128 v[184:187], v202 offset:50176
	ds_read_b128 v[188:191], v202 offset:51200
	ds_read_b128 v[192:195], v202 offset:52224
	ds_read_b128 v[206:209], v202 offset:53248
	ds_read_b128 v[210:213], v202 offset:54272
	ds_read_b128 v[214:217], v202 offset:55296
	ds_read_b128 v[218:221], v202 offset:56320
	global_load_lds_dwordx4 v[222:223], off
	s_add_i32 m0, s63, 0x2000
	s_add_u32 s18, s18, 0x100080
	v_lshl_add_u64 v[222:223], v[224:225], 0, s[26:27]
	s_addc_u32 s19, s19, 0
	s_add_i32 s63, s82, s37
	global_load_lds_dwordx4 v[222:223], off
	v_lshl_add_u64 v[222:223], s[18:19], 0, v[148:149]
	s_mov_b32 m0, s63
	s_nop 0
	global_load_lds_dwordx4 v[222:223], off
	v_lshl_add_u64 v[222:223], s[18:19], 0, v[152:153]
	s_add_i32 m0, s63, 0x2000
	s_nop 0
	global_load_lds_dwordx4 v[222:223], off
	v_lshl_add_u64 v[222:223], v[226:227], 0, s[26:27]
	s_mov_b32 m0, s71
	s_nop 0
	global_load_lds_dwordx4 v[222:223], off
	v_lshl_add_u64 v[222:223], v[228:229], 0, s[26:27]
	s_mov_b32 m0, s72
	s_nop 0
	global_load_lds_dwordx4 v[222:223], off
	s_waitcnt vmcnt(8)
	s_waitcnt lgkmcnt(0)
	s_barrier
	v_mfma_f32_16x16x32_bf16 v[74:77], v[46:49], v[180:183], v[74:77]
	v_mfma_f32_16x16x32_bf16 v[74:77], v[54:57], v[184:187], v[74:77]
	v_mfma_f32_16x16x32_bf16 v[78:81], v[66:69], v[180:183], v[78:81]
	v_mfma_f32_16x16x32_bf16 v[78:81], v[70:73], v[184:187], v[78:81]
	v_mfma_f32_16x16x32_bf16 v[58:61], v[46:49], v[188:191], v[58:61]
	v_mfma_f32_16x16x32_bf16 v[58:61], v[54:57], v[192:195], v[58:61]
	v_mfma_f32_16x16x32_bf16 v[62:65], v[66:69], v[188:191], v[62:65]
	v_mfma_f32_16x16x32_bf16 v[62:65], v[70:73], v[192:195], v[62:65]
	v_mfma_f32_16x16x32_bf16 v[26:29], v[46:49], v[206:209], v[26:29]
	v_mfma_f32_16x16x32_bf16 v[26:29], v[54:57], v[210:213], v[26:29]
	v_mfma_f32_16x16x32_bf16 v[34:37], v[66:69], v[206:209], v[34:37]
	v_mfma_f32_16x16x32_bf16 v[34:37], v[70:73], v[210:213], v[34:37]
	v_mfma_f32_16x16x32_bf16 v[10:13], v[46:49], v[214:217], v[10:13]
	v_mfma_f32_16x16x32_bf16 v[10:13], v[54:57], v[218:221], v[10:13]
	v_mfma_f32_16x16x32_bf16 v[14:17], v[66:69], v[214:217], v[14:17]
	v_mfma_f32_16x16x32_bf16 v[14:17], v[70:73], v[218:221], v[14:17]
	v_mfma_f32_16x16x32_bf16 v[30:33], v[164:167], v[180:183], v[30:33]
	v_mfma_f32_16x16x32_bf16 v[66:69], v[168:171], v[184:187], v[30:33]
	v_mfma_f32_16x16x32_bf16 v[30:33], v[172:175], v[180:183], v[38:41]
	v_mfma_f32_16x16x32_bf16 v[70:73], v[176:179], v[184:187], v[30:33]
	v_mfma_f32_16x16x32_bf16 v[30:33], v[164:167], v[188:191], v[42:45]
	v_mfma_f32_16x16x32_bf16 v[46:49], v[168:171], v[192:195], v[30:33]
	v_mfma_f32_16x16x32_bf16 v[30:33], v[172:175], v[188:191], v[50:53]
	v_mfma_f32_16x16x32_bf16 v[54:57], v[176:179], v[192:195], v[30:33]
	v_mfma_f32_16x16x32_bf16 v[18:21], v[164:167], v[206:209], v[18:21]
	v_mfma_f32_16x16x32_bf16 v[18:21], v[168:171], v[210:213], v[18:21]
	v_mfma_f32_16x16x32_bf16 v[22:25], v[172:175], v[206:209], v[22:25]
	v_mfma_f32_16x16x32_bf16 v[22:25], v[176:179], v[210:213], v[22:25]
	v_mfma_f32_16x16x32_bf16 v[2:5], v[164:167], v[214:217], v[2:5]
	v_mfma_f32_16x16x32_bf16 v[2:5], v[168:171], v[218:221], v[2:5]
	v_mfma_f32_16x16x32_bf16 v[6:9], v[172:175], v[214:217], v[6:9]
	v_mfma_f32_16x16x32_bf16 v[6:9], v[176:179], v[218:221], v[6:9]
	s_barrier
	s_add_i32 s61, s61, 2
	s_add_u32 s10, s10, 0x100
	s_addc_u32 s11, s11, 0
	s_add_u32 s16, s16, 0x100
	s_addc_u32 s17, s17, 0
	s_cmp_gt_u32 s61, 61
	s_cbranch_scc0 .LBB0_1647
	s_and_b64 vcc, exec, s[28:29]
	s_cbranch_vccz .LBB0_1650
	s_barrier

.LBB0_1920:
	s_ashr_i32 s31, s30, 31
	s_lshl_b64 s[34:35], s[30:31], 21
	s_add_u32 s34, s54, s34
	s_addc_u32 s35, s55, s35
	s_and_b64 s[36:37], s[2:3], exec
	s_cselect_b32 s31, s35, s39
	s_cselect_b32 s69, s34, s38
	s_ashr_i32 s29, s28, 31
	s_lshl_b64 s[36:37], s[28:29], 21
	s_add_u32 s36, s1, s36
	s_addc_u32 s37, s16, s37
	s_and_b64 s[42:43], s[2:3], exec
	s_cselect_b32 s29, s37, s41
	s_cselect_b32 s70, s36, s40
	s_add_u32 s38, s38, 0x100080
	s_addc_u32 s39, s39, 0
	s_add_u32 s71, s40, 0x100
	s_addc_u32 s72, s41, 0
	s_mov_b32 s73, -2
	ds_read_b128 v[130:133], v212
	ds_read_b128 v[134:137], v212 offset:1024
	ds_read_b128 v[138:141], v212 offset:2048
	ds_read_b128 v[142:145], v212 offset:3072
	ds_read_b128 v[146:149], v213
	ds_read_b128 v[150:153], v213 offset:1024
	ds_read_b128 v[154:157], v213 offset:2048
	ds_read_b128 v[158:161], v213 offset:3072
	s_add_u32 s40, s38, 0xfff00080
	s_addc_u32 s41, s39, -1
	s_cmp_eq_u32 s73, 60
	s_cselect_b32 s43, s31, s41
	s_cselect_b32 s42, s69, s40
	s_cselect_b32 s41, s29, s72
	s_cselect_b32 s40, s70, s71
	v_lshl_add_u64 v[216:217], s[38:39], 0, v[178:179]
	s_add_i32 m0, s19, 0xc000
	ds_read_b128 v[162:165], v214
	ds_read_b128 v[166:169], v214 offset:1024
	ds_read_b128 v[186:189], v214 offset:2048
	ds_read_b128 v[190:193], v214 offset:3072
	ds_read_b128 v[194:197], v214 offset:4096
	ds_read_b128 v[198:201], v214 offset:5120
	ds_read_b128 v[202:205], v214 offset:6144
	ds_read_b128 v[206:209], v214 offset:7168
	global_load_lds_dwordx4 v[216:217], off
	v_lshl_add_u64 v[216:217], s[38:39], 0, v[180:181]
	s_add_i32 m0, s19, 0xe000
	s_nop 0
	global_load_lds_dwordx4 v[216:217], off
	s_waitcnt vmcnt(8)
	s_waitcnt lgkmcnt(0)
	s_barrier
	v_mfma_f32_16x16x32_bf16 v[126:129], v[130:133], v[162:165], 0
	v_mfma_f32_16x16x32_bf16 v[126:129], v[134:137], v[166:169], v[126:129]
	v_mfma_f32_16x16x32_bf16 v[122:125], v[138:141], v[162:165], 0
	v_mfma_f32_16x16x32_bf16 v[122:125], v[142:145], v[166:169], v[122:125]
	v_mfma_f32_16x16x32_bf16 v[110:113], v[130:133], v[186:189], 0
	v_mfma_f32_16x16x32_bf16 v[110:113], v[134:137], v[190:193], v[110:113]
	v_mfma_f32_16x16x32_bf16 v[106:109], v[138:141], v[186:189], 0
	v_mfma_f32_16x16x32_bf16 v[106:109], v[142:145], v[190:193], v[106:109]
	v_mfma_f32_16x16x32_bf16 v[94:97], v[130:133], v[194:197], 0
	v_mfma_f32_16x16x32_bf16 v[94:97], v[134:137], v[198:201], v[94:97]
	v_mfma_f32_16x16x32_bf16 v[90:93], v[138:141], v[194:197], 0
	v_mfma_f32_16x16x32_bf16 v[90:93], v[142:145], v[198:201], v[90:93]
	v_mfma_f32_16x16x32_bf16 v[78:81], v[130:133], v[202:205], 0
	v_mfma_f32_16x16x32_bf16 v[78:81], v[134:137], v[206:209], v[78:81]
	v_mfma_f32_16x16x32_bf16 v[74:77], v[138:141], v[202:205], 0
	v_mfma_f32_16x16x32_bf16 v[74:77], v[142:145], v[206:209], v[74:77]
	v_mfma_f32_16x16x32_bf16 v[118:121], v[146:149], v[162:165], 0
	v_mfma_f32_16x16x32_bf16 v[118:121], v[150:153], v[166:169], v[118:121]
	v_mfma_f32_16x16x32_bf16 v[114:117], v[154:157], v[162:165], 0
	v_mfma_f32_16x16x32_bf16 v[114:117], v[158:161], v[166:169], v[114:117]
	v_mfma_f32_16x16x32_bf16 v[102:105], v[146:149], v[186:189], 0
	v_mfma_f32_16x16x32_bf16 v[102:105], v[150:153], v[190:193], v[102:105]
	v_mfma_f32_16x16x32_bf16 v[98:101], v[154:157], v[186:189], 0
	v_mfma_f32_16x16x32_bf16 v[98:101], v[158:161], v[190:193], v[98:101]
	v_mfma_f32_16x16x32_bf16 v[86:89], v[146:149], v[194:197], 0
	v_mfma_f32_16x16x32_bf16 v[86:89], v[150:153], v[198:201], v[86:89]
	v_mfma_f32_16x16x32_bf16 v[82:85], v[154:157], v[194:197], 0
	v_mfma_f32_16x16x32_bf16 v[82:85], v[158:161], v[198:201], v[82:85]
	v_mfma_f32_16x16x32_bf16 v[70:73], v[146:149], v[202:205], 0
	v_mfma_f32_16x16x32_bf16 v[70:73], v[150:153], v[206:209], v[70:73]
	v_mfma_f32_16x16x32_bf16 v[66:69], v[154:157], v[202:205], 0
	v_mfma_f32_16x16x32_bf16 v[66:69], v[158:161], v[206:209], v[66:69]
	s_barrier
	s_add_i32 s76, s57, s17
	v_lshl_add_u64 v[216:217], s[40:41], 0, v[172:173]
	s_mov_b32 m0, s76
	ds_read_b128 v[162:165], v214 offset:16384
	ds_read_b128 v[166:169], v214 offset:17408
	ds_read_b128 v[186:189], v214 offset:18432
	ds_read_b128 v[190:193], v214 offset:19456
	ds_read_b128 v[194:197], v214 offset:20480
	ds_read_b128 v[198:201], v214 offset:21504
	ds_read_b128 v[202:205], v214 offset:22528
	ds_read_b128 v[206:209], v214 offset:23552
	global_load_lds_dwordx4 v[216:217], off
	s_add_i32 m0, s76, 0x2000
	s_add_u32 s76, s40, 0x100000
	v_lshl_add_u64 v[218:219], s[40:41], 0, v[176:177]
	s_addc_u32 s77, s41, 0
	s_add_i32 s78, s60, s17
	global_load_lds_dwordx4 v[218:219], off
	v_lshl_add_u64 v[220:221], s[76:77], 0, v[172:173]
	s_mov_b32 m0, s78
	v_lshl_add_u64 v[222:223], s[42:43], 0, v[174:175]
	global_load_lds_dwordx4 v[220:221], off
	v_lshl_add_u64 v[220:221], s[76:77], 0, v[176:177]
	s_add_i32 m0, s78, 0x2000
	s_nop 0
	global_load_lds_dwordx4 v[220:221], off
	v_lshl_add_u64 v[220:221], s[42:43], 0, v[170:171]
	s_mov_b32 m0, s19
	s_nop 0
	global_load_lds_dwordx4 v[220:221], off
	s_mov_b32 m0, s44
	s_nop 0
	global_load_lds_dwordx4 v[222:223], off
	s_waitcnt vmcnt(8)
	s_waitcnt lgkmcnt(0)
	s_barrier
	v_mfma_f32_16x16x32_bf16 v[62:65], v[130:133], v[162:165], 0
	v_mfma_f32_16x16x32_bf16 v[62:65], v[134:137], v[166:169], v[62:65]
	v_mfma_f32_16x16x32_bf16 v[58:61], v[138:141], v[162:165], 0
	v_mfma_f32_16x16x32_bf16 v[58:61], v[142:145], v[166:169], v[58:61]
	v_mfma_f32_16x16x32_bf16 v[46:49], v[130:133], v[186:189], 0
	v_mfma_f32_16x16x32_bf16 v[46:49], v[134:137], v[190:193], v[46:49]
	v_mfma_f32_16x16x32_bf16 v[42:45], v[138:141], v[186:189], 0
	v_mfma_f32_16x16x32_bf16 v[42:45], v[142:145], v[190:193], v[42:45]
	v_mfma_f32_16x16x32_bf16 v[30:33], v[130:133], v[194:197], 0
	v_mfma_f32_16x16x32_bf16 v[30:33], v[134:137], v[198:201], v[30:33]
	v_mfma_f32_16x16x32_bf16 v[26:29], v[138:141], v[194:197], 0
	v_mfma_f32_16x16x32_bf16 v[26:29], v[142:145], v[198:201], v[26:29]
	v_mfma_f32_16x16x32_bf16 v[14:17], v[130:133], v[202:205], 0
	v_mfma_f32_16x16x32_bf16 v[14:17], v[134:137], v[206:209], v[14:17]
	v_mfma_f32_16x16x32_bf16 v[10:13], v[138:141], v[202:205], 0
	v_mfma_f32_16x16x32_bf16 v[10:13], v[142:145], v[206:209], v[10:13]
	v_mfma_f32_16x16x32_bf16 v[54:57], v[146:149], v[162:165], 0
	v_mfma_f32_16x16x32_bf16 v[54:57], v[150:153], v[166:169], v[54:57]
	v_mfma_f32_16x16x32_bf16 v[50:53], v[154:157], v[162:165], 0
	v_mfma_f32_16x16x32_bf16 v[50:53], v[158:161], v[166:169], v[50:53]
	v_mfma_f32_16x16x32_bf16 v[38:41], v[146:149], v[186:189], 0
	v_mfma_f32_16x16x32_bf16 v[38:41], v[150:153], v[190:193], v[38:41]
	v_mfma_f32_16x16x32_bf16 v[34:37], v[154:157], v[186:189], 0
	v_mfma_f32_16x16x32_bf16 v[34:37], v[158:161], v[190:193], v[34:37]
	v_mfma_f32_16x16x32_bf16 v[22:25], v[146:149], v[194:197], 0
	v_mfma_f32_16x16x32_bf16 v[22:25], v[150:153], v[198:201], v[22:25]
	v_mfma_f32_16x16x32_bf16 v[18:21], v[154:157], v[194:197], 0
	v_mfma_f32_16x16x32_bf16 v[18:21], v[158:161], v[198:201], v[18:21]
	v_mfma_f32_16x16x32_bf16 v[6:9], v[146:149], v[202:205], 0
	v_mfma_f32_16x16x32_bf16 v[6:9], v[150:153], v[206:209], v[6:9]
	v_mfma_f32_16x16x32_bf16 v[2:5], v[154:157], v[202:205], 0
	v_mfma_f32_16x16x32_bf16 v[2:5], v[158:161], v[206:209], v[2:5]
	s_barrier
	s_add_i32 s76, 0, 0x18000
	s_add_i32 s77, 0, 0x1c000
	v_add_u32_e32 v142, s76, v211
	v_add_u32_e32 v158, s77, v211
	ds_read_b128 v[130:133], v142
	ds_read_b128 v[134:137], v142 offset:1024
	ds_read_b128 v[138:141], v142 offset:2048
	ds_read_b128 v[142:145], v142 offset:3072
	ds_read_b128 v[146:149], v158
	ds_read_b128 v[150:153], v158 offset:1024
	ds_read_b128 v[154:157], v158 offset:2048
	ds_read_b128 v[158:161], v158 offset:3072
	s_add_u32 s42, s42, 0x100000
	s_addc_u32 s43, s43, 0
	s_mov_b32 m0, s45
	v_lshl_add_u64 v[224:225], s[42:43], 0, v[170:171]
	ds_read_b128 v[162:165], v214 offset:32768
	ds_read_b128 v[166:169], v214 offset:33792
	ds_read_b128 v[186:189], v214 offset:34816
	ds_read_b128 v[190:193], v214 offset:35840
	ds_read_b128 v[194:197], v214 offset:36864
	ds_read_b128 v[198:201], v214 offset:37888
	ds_read_b128 v[202:205], v214 offset:38912
	ds_read_b128 v[206:209], v214 offset:39936
	global_load_lds_dwordx4 v[224:225], off
	v_lshl_add_u64 v[224:225], s[42:43], 0, v[174:175]
	s_mov_b32 m0, s46
	s_nop 0
	global_load_lds_dwordx4 v[224:225], off
	s_waitcnt vmcnt(8)
	s_waitcnt lgkmcnt(0)
	s_barrier
	v_mfma_f32_16x16x32_bf16 v[126:129], v[130:133], v[162:165], v[126:129]
	v_mfma_f32_16x16x32_bf16 v[126:129], v[134:137], v[166:169], v[126:129]
	v_mfma_f32_16x16x32_bf16 v[122:125], v[138:141], v[162:165], v[122:125]
	v_mfma_f32_16x16x32_bf16 v[122:125], v[142:145], v[166:169], v[122:125]
	v_mfma_f32_16x16x32_bf16 v[110:113], v[130:133], v[186:189], v[110:113]
	v_mfma_f32_16x16x32_bf16 v[110:113], v[134:137], v[190:193], v[110:113]
	v_mfma_f32_16x16x32_bf16 v[106:109], v[138:141], v[186:189], v[106:109]
	v_mfma_f32_16x16x32_bf16 v[106:109], v[142:145], v[190:193], v[106:109]
	v_mfma_f32_16x16x32_bf16 v[94:97], v[130:133], v[194:197], v[94:97]
	v_mfma_f32_16x16x32_bf16 v[94:97], v[134:137], v[198:201], v[94:97]
	v_mfma_f32_16x16x32_bf16 v[90:93], v[138:141], v[194:197], v[90:93]
	v_mfma_f32_16x16x32_bf16 v[90:93], v[142:145], v[198:201], v[90:93]
	v_mfma_f32_16x16x32_bf16 v[78:81], v[130:133], v[202:205], v[78:81]
	v_mfma_f32_16x16x32_bf16 v[78:81], v[134:137], v[206:209], v[78:81]
	v_mfma_f32_16x16x32_bf16 v[74:77], v[138:141], v[202:205], v[74:77]
	v_mfma_f32_16x16x32_bf16 v[74:77], v[142:145], v[206:209], v[74:77]
	v_mfma_f32_16x16x32_bf16 v[118:121], v[146:149], v[162:165], v[118:121]
	v_mfma_f32_16x16x32_bf16 v[118:121], v[150:153], v[166:169], v[118:121]
	v_mfma_f32_16x16x32_bf16 v[114:117], v[154:157], v[162:165], v[114:117]
	v_mfma_f32_16x16x32_bf16 v[114:117], v[158:161], v[166:169], v[114:117]
	v_mfma_f32_16x16x32_bf16 v[102:105], v[146:149], v[186:189], v[102:105]
	v_mfma_f32_16x16x32_bf16 v[102:105], v[150:153], v[190:193], v[102:105]
	v_mfma_f32_16x16x32_bf16 v[98:101], v[154:157], v[186:189], v[98:101]
	v_mfma_f32_16x16x32_bf16 v[98:101], v[158:161], v[190:193], v[98:101]
	v_mfma_f32_16x16x32_bf16 v[86:89], v[146:149], v[194:197], v[86:89]
	v_mfma_f32_16x16x32_bf16 v[86:89], v[150:153], v[198:201], v[86:89]
	v_mfma_f32_16x16x32_bf16 v[82:85], v[154:157], v[194:197], v[82:85]
	v_mfma_f32_16x16x32_bf16 v[82:85], v[158:161], v[198:201], v[82:85]
	v_mfma_f32_16x16x32_bf16 v[70:73], v[146:149], v[202:205], v[70:73]
	v_mfma_f32_16x16x32_bf16 v[70:73], v[150:153], v[206:209], v[70:73]
	v_mfma_f32_16x16x32_bf16 v[66:69], v[154:157], v[202:205], v[66:69]
	v_mfma_f32_16x16x32_bf16 v[66:69], v[158:161], v[206:209], v[66:69]
	s_barrier
	s_add_i32 s42, s76, s17
	v_lshl_add_u64 v[216:217], v[216:217], 0, s[8:9]
	s_mov_b32 m0, s42
	ds_read_b128 v[162:165], v214 offset:49152
	ds_read_b128 v[166:169], v214 offset:50176
	ds_read_b128 v[186:189], v214 offset:51200
	ds_read_b128 v[190:193], v214 offset:52224
	ds_read_b128 v[194:197], v214 offset:53248
	ds_read_b128 v[198:201], v214 offset:54272
	ds_read_b128 v[202:205], v214 offset:55296
	ds_read_b128 v[206:209], v214 offset:56320
	global_load_lds_dwordx4 v[216:217], off
	s_add_i32 m0, s42, 0x2000
	s_add_u32 s40, s40, 0x100080
	v_lshl_add_u64 v[216:217], v[218:219], 0, s[8:9]
	s_addc_u32 s41, s41, 0
	s_add_i32 s42, s77, s17
	global_load_lds_dwordx4 v[216:217], off
	v_lshl_add_u64 v[216:217], s[40:41], 0, v[172:173]
	s_mov_b32 m0, s42
	s_nop 0
	global_load_lds_dwordx4 v[216:217], off
	v_lshl_add_u64 v[216:217], s[40:41], 0, v[176:177]
	s_add_i32 m0, s42, 0x2000
	s_nop 0
	global_load_lds_dwordx4 v[216:217], off
	v_lshl_add_u64 v[216:217], v[220:221], 0, s[8:9]
	s_mov_b32 m0, s50
	s_nop 0
	global_load_lds_dwordx4 v[216:217], off
	v_lshl_add_u64 v[216:217], v[222:223], 0, s[8:9]
	s_mov_b32 m0, s51
	s_nop 0
	global_load_lds_dwordx4 v[216:217], off
	s_waitcnt vmcnt(8)
	s_waitcnt lgkmcnt(0)
	s_barrier
	v_mfma_f32_16x16x32_bf16 v[62:65], v[130:133], v[162:165], v[62:65]
	v_mfma_f32_16x16x32_bf16 v[62:65], v[134:137], v[166:169], v[62:65]
	v_mfma_f32_16x16x32_bf16 v[58:61], v[138:141], v[162:165], v[58:61]
	v_mfma_f32_16x16x32_bf16 v[58:61], v[142:145], v[166:169], v[58:61]
	v_mfma_f32_16x16x32_bf16 v[46:49], v[130:133], v[186:189], v[46:49]
	v_mfma_f32_16x16x32_bf16 v[46:49], v[134:137], v[190:193], v[46:49]
	v_mfma_f32_16x16x32_bf16 v[42:45], v[138:141], v[186:189], v[42:45]
	v_mfma_f32_16x16x32_bf16 v[42:45], v[142:145], v[190:193], v[42:45]
	v_mfma_f32_16x16x32_bf16 v[30:33], v[130:133], v[194:197], v[30:33]
	v_mfma_f32_16x16x32_bf16 v[30:33], v[134:137], v[198:201], v[30:33]
	v_mfma_f32_16x16x32_bf16 v[26:29], v[138:141], v[194:197], v[26:29]
	v_mfma_f32_16x16x32_bf16 v[26:29], v[142:145], v[198:201], v[26:29]
	v_mfma_f32_16x16x32_bf16 v[14:17], v[130:133], v[202:205], v[14:17]
	v_mfma_f32_16x16x32_bf16 v[14:17], v[134:137], v[206:209], v[14:17]
	v_mfma_f32_16x16x32_bf16 v[10:13], v[138:141], v[202:205], v[10:13]
	v_mfma_f32_16x16x32_bf16 v[10:13], v[142:145], v[206:209], v[10:13]
	v_mfma_f32_16x16x32_bf16 v[54:57], v[146:149], v[162:165], v[54:57]
	v_mfma_f32_16x16x32_bf16 v[54:57], v[150:153], v[166:169], v[54:57]
	v_mfma_f32_16x16x32_bf16 v[50:53], v[154:157], v[162:165], v[50:53]
	v_mfma_f32_16x16x32_bf16 v[50:53], v[158:161], v[166:169], v[50:53]
	v_mfma_f32_16x16x32_bf16 v[38:41], v[146:149], v[186:189], v[38:41]
	v_mfma_f32_16x16x32_bf16 v[38:41], v[150:153], v[190:193], v[38:41]
	v_mfma_f32_16x16x32_bf16 v[34:37], v[154:157], v[186:189], v[34:37]
	v_mfma_f32_16x16x32_bf16 v[34:37], v[158:161], v[190:193], v[34:37]
	v_mfma_f32_16x16x32_bf16 v[22:25], v[146:149], v[194:197], v[22:25]
	v_mfma_f32_16x16x32_bf16 v[22:25], v[150:153], v[198:201], v[22:25]
	v_mfma_f32_16x16x32_bf16 v[18:21], v[154:157], v[194:197], v[18:21]
	v_mfma_f32_16x16x32_bf16 v[18:21], v[158:161], v[198:201], v[18:21]
	v_mfma_f32_16x16x32_bf16 v[6:9], v[146:149], v[202:205], v[6:9]
	v_mfma_f32_16x16x32_bf16 v[6:9], v[150:153], v[206:209], v[6:9]
	v_mfma_f32_16x16x32_bf16 v[2:5], v[154:157], v[202:205], v[2:5]
	v_mfma_f32_16x16x32_bf16 v[2:5], v[158:161], v[206:209], v[2:5]
	s_barrier
	s_add_i32 s73, s73, 2
	s_add_u32 s38, s38, 0x100
	s_addc_u32 s39, s39, 0
	s_add_u32 s71, s71, 0x100
	s_addc_u32 s72, s72, 0
	s_cmp_gt_u32 s73, 61
.LBB0_1921:
	ds_read_b128 v[130:133], v212
	ds_read_b128 v[134:137], v212 offset:1024
	ds_read_b128 v[138:141], v212 offset:2048
	ds_read_b128 v[142:145], v212 offset:3072
	ds_read_b128 v[146:149], v213
	ds_read_b128 v[150:153], v213 offset:1024
	ds_read_b128 v[154:157], v213 offset:2048
	ds_read_b128 v[158:161], v213 offset:3072
	s_add_u32 s40, s38, 0xfff00080
	s_addc_u32 s41, s39, -1
	s_cmp_eq_u32 s73, 60
	s_cselect_b32 s43, s31, s41
	s_cselect_b32 s42, s69, s40
	s_cselect_b32 s41, s29, s72
	s_cselect_b32 s40, s70, s71
	v_lshl_add_u64 v[216:217], s[38:39], 0, v[178:179]
	s_add_i32 m0, s19, 0xc000
	ds_read_b128 v[162:165], v214
	ds_read_b128 v[166:169], v214 offset:1024
	ds_read_b128 v[186:189], v214 offset:2048
	ds_read_b128 v[190:193], v214 offset:3072
	ds_read_b128 v[194:197], v214 offset:4096
	ds_read_b128 v[198:201], v214 offset:5120
	ds_read_b128 v[202:205], v214 offset:6144
	ds_read_b128 v[206:209], v214 offset:7168
	global_load_lds_dwordx4 v[216:217], off
	v_lshl_add_u64 v[216:217], s[38:39], 0, v[180:181]
	s_add_i32 m0, s19, 0xe000
	s_nop 0
	global_load_lds_dwordx4 v[216:217], off
	s_waitcnt vmcnt(8)
	s_waitcnt lgkmcnt(0)
	s_barrier
	v_mfma_f32_16x16x32_bf16 v[126:129], v[130:133], v[162:165], v[126:129]
	v_mfma_f32_16x16x32_bf16 v[126:129], v[134:137], v[166:169], v[126:129]
	v_mfma_f32_16x16x32_bf16 v[122:125], v[138:141], v[162:165], v[122:125]
	v_mfma_f32_16x16x32_bf16 v[122:125], v[142:145], v[166:169], v[122:125]
	v_mfma_f32_16x16x32_bf16 v[110:113], v[130:133], v[186:189], v[110:113]
	v_mfma_f32_16x16x32_bf16 v[110:113], v[134:137], v[190:193], v[110:113]
	v_mfma_f32_16x16x32_bf16 v[106:109], v[138:141], v[186:189], v[106:109]
	v_mfma_f32_16x16x32_bf16 v[106:109], v[142:145], v[190:193], v[106:109]
	v_mfma_f32_16x16x32_bf16 v[94:97], v[130:133], v[194:197], v[94:97]
	v_mfma_f32_16x16x32_bf16 v[94:97], v[134:137], v[198:201], v[94:97]
	v_mfma_f32_16x16x32_bf16 v[90:93], v[138:141], v[194:197], v[90:93]
	v_mfma_f32_16x16x32_bf16 v[90:93], v[142:145], v[198:201], v[90:93]
	v_mfma_f32_16x16x32_bf16 v[78:81], v[130:133], v[202:205], v[78:81]
	v_mfma_f32_16x16x32_bf16 v[78:81], v[134:137], v[206:209], v[78:81]
	v_mfma_f32_16x16x32_bf16 v[74:77], v[138:141], v[202:205], v[74:77]
	v_mfma_f32_16x16x32_bf16 v[74:77], v[142:145], v[206:209], v[74:77]
	v_mfma_f32_16x16x32_bf16 v[118:121], v[146:149], v[162:165], v[118:121]
	v_mfma_f32_16x16x32_bf16 v[118:121], v[150:153], v[166:169], v[118:121]
	v_mfma_f32_16x16x32_bf16 v[114:117], v[154:157], v[162:165], v[114:117]
	v_mfma_f32_16x16x32_bf16 v[114:117], v[158:161], v[166:169], v[114:117]
	v_mfma_f32_16x16x32_bf16 v[102:105], v[146:149], v[186:189], v[102:105]
	v_mfma_f32_16x16x32_bf16 v[102:105], v[150:153], v[190:193], v[102:105]
	v_mfma_f32_16x16x32_bf16 v[98:101], v[154:157], v[186:189], v[98:101]
	v_mfma_f32_16x16x32_bf16 v[98:101], v[158:161], v[190:193], v[98:101]
	v_mfma_f32_16x16x32_bf16 v[86:89], v[146:149], v[194:197], v[86:89]
	v_mfma_f32_16x16x32_bf16 v[86:89], v[150:153], v[198:201], v[86:89]
	v_mfma_f32_16x16x32_bf16 v[82:85], v[154:157], v[194:197], v[82:85]
	v_mfma_f32_16x16x32_bf16 v[82:85], v[158:161], v[198:201], v[82:85]
	v_mfma_f32_16x16x32_bf16 v[70:73], v[146:149], v[202:205], v[70:73]
	v_mfma_f32_16x16x32_bf16 v[70:73], v[150:153], v[206:209], v[70:73]
	v_mfma_f32_16x16x32_bf16 v[66:69], v[154:157], v[202:205], v[66:69]
	v_mfma_f32_16x16x32_bf16 v[66:69], v[158:161], v[206:209], v[66:69]
	s_barrier
	s_add_i32 s76, s57, s17
	v_lshl_add_u64 v[216:217], s[40:41], 0, v[172:173]
	s_mov_b32 m0, s76
	ds_read_b128 v[162:165], v214 offset:16384
	ds_read_b128 v[166:169], v214 offset:17408
	ds_read_b128 v[186:189], v214 offset:18432
	ds_read_b128 v[190:193], v214 offset:19456
	ds_read_b128 v[194:197], v214 offset:20480
	ds_read_b128 v[198:201], v214 offset:21504
	ds_read_b128 v[202:205], v214 offset:22528
	ds_read_b128 v[206:209], v214 offset:23552
	global_load_lds_dwordx4 v[216:217], off
	s_add_i32 m0, s76, 0x2000
	s_add_u32 s76, s40, 0x100000
	v_lshl_add_u64 v[218:219], s[40:41], 0, v[176:177]
	s_addc_u32 s77, s41, 0
	s_add_i32 s78, s60, s17
	global_load_lds_dwordx4 v[218:219], off
	v_lshl_add_u64 v[220:221], s[76:77], 0, v[172:173]
	s_mov_b32 m0, s78
	v_lshl_add_u64 v[222:223], s[42:43], 0, v[174:175]
	global_load_lds_dwordx4 v[220:221], off
	v_lshl_add_u64 v[220:221], s[76:77], 0, v[176:177]
	s_add_i32 m0, s78, 0x2000
	s_nop 0
	global_load_lds_dwordx4 v[220:221], off
	v_lshl_add_u64 v[220:221], s[42:43], 0, v[170:171]
	s_mov_b32 m0, s19
	s_nop 0
	global_load_lds_dwordx4 v[220:221], off
	s_mov_b32 m0, s44
	s_nop 0
	global_load_lds_dwordx4 v[222:223], off
	s_waitcnt vmcnt(8)
	s_waitcnt lgkmcnt(0)
	s_barrier
	v_mfma_f32_16x16x32_bf16 v[62:65], v[130:133], v[162:165], v[62:65]
	v_mfma_f32_16x16x32_bf16 v[62:65], v[134:137], v[166:169], v[62:65]
	v_mfma_f32_16x16x32_bf16 v[58:61], v[138:141], v[162:165], v[58:61]
	v_mfma_f32_16x16x32_bf16 v[58:61], v[142:145], v[166:169], v[58:61]
	v_mfma_f32_16x16x32_bf16 v[46:49], v[130:133], v[186:189], v[46:49]
	v_mfma_f32_16x16x32_bf16 v[46:49], v[134:137], v[190:193], v[46:49]
	v_mfma_f32_16x16x32_bf16 v[42:45], v[138:141], v[186:189], v[42:45]
	v_mfma_f32_16x16x32_bf16 v[42:45], v[142:145], v[190:193], v[42:45]
	v_mfma_f32_16x16x32_bf16 v[30:33], v[130:133], v[194:197], v[30:33]
	v_mfma_f32_16x16x32_bf16 v[30:33], v[134:137], v[198:201], v[30:33]
	v_mfma_f32_16x16x32_bf16 v[26:29], v[138:141], v[194:197], v[26:29]
	v_mfma_f32_16x16x32_bf16 v[26:29], v[142:145], v[198:201], v[26:29]
	v_mfma_f32_16x16x32_bf16 v[14:17], v[130:133], v[202:205], v[14:17]
	v_mfma_f32_16x16x32_bf16 v[14:17], v[134:137], v[206:209], v[14:17]
	v_mfma_f32_16x16x32_bf16 v[10:13], v[138:141], v[202:205], v[10:13]
	v_mfma_f32_16x16x32_bf16 v[10:13], v[142:145], v[206:209], v[10:13]
	v_mfma_f32_16x16x32_bf16 v[54:57], v[146:149], v[162:165], v[54:57]
	v_mfma_f32_16x16x32_bf16 v[54:57], v[150:153], v[166:169], v[54:57]
	v_mfma_f32_16x16x32_bf16 v[50:53], v[154:157], v[162:165], v[50:53]
	v_mfma_f32_16x16x32_bf16 v[50:53], v[158:161], v[166:169], v[50:53]
	v_mfma_f32_16x16x32_bf16 v[38:41], v[146:149], v[186:189], v[38:41]
	v_mfma_f32_16x16x32_bf16 v[38:41], v[150:153], v[190:193], v[38:41]
	v_mfma_f32_16x16x32_bf16 v[34:37], v[154:157], v[186:189], v[34:37]
	v_mfma_f32_16x16x32_bf16 v[34:37], v[158:161], v[190:193], v[34:37]
	v_mfma_f32_16x16x32_bf16 v[22:25], v[146:149], v[194:197], v[22:25]
	v_mfma_f32_16x16x32_bf16 v[22:25], v[150:153], v[198:201], v[22:25]
	v_mfma_f32_16x16x32_bf16 v[18:21], v[154:157], v[194:197], v[18:21]
	v_mfma_f32_16x16x32_bf16 v[18:21], v[158:161], v[198:201], v[18:21]
	v_mfma_f32_16x16x32_bf16 v[6:9], v[146:149], v[202:205], v[6:9]
	v_mfma_f32_16x16x32_bf16 v[6:9], v[150:153], v[206:209], v[6:9]
	v_mfma_f32_16x16x32_bf16 v[2:5], v[154:157], v[202:205], v[2:5]
	v_mfma_f32_16x16x32_bf16 v[2:5], v[158:161], v[206:209], v[2:5]
	s_barrier
	s_add_i32 s76, 0, 0x18000
	s_add_i32 s77, 0, 0x1c000
	v_add_u32_e32 v142, s76, v211
	v_add_u32_e32 v158, s77, v211
	ds_read_b128 v[130:133], v142
	ds_read_b128 v[134:137], v142 offset:1024
	ds_read_b128 v[138:141], v142 offset:2048
	ds_read_b128 v[142:145], v142 offset:3072
	ds_read_b128 v[146:149], v158
	ds_read_b128 v[150:153], v158 offset:1024
	ds_read_b128 v[154:157], v158 offset:2048
	ds_read_b128 v[158:161], v158 offset:3072
	s_add_u32 s42, s42, 0x100000
	s_addc_u32 s43, s43, 0
	s_mov_b32 m0, s45
	v_lshl_add_u64 v[224:225], s[42:43], 0, v[170:171]
	ds_read_b128 v[162:165], v214 offset:32768
	ds_read_b128 v[166:169], v214 offset:33792
	ds_read_b128 v[186:189], v214 offset:34816
	ds_read_b128 v[190:193], v214 offset:35840
	ds_read_b128 v[194:197], v214 offset:36864
	ds_read_b128 v[198:201], v214 offset:37888
	ds_read_b128 v[202:205], v214 offset:38912
	ds_read_b128 v[206:209], v214 offset:39936
	global_load_lds_dwordx4 v[224:225], off
	v_lshl_add_u64 v[224:225], s[42:43], 0, v[174:175]
	s_mov_b32 m0, s46
	s_nop 0
	global_load_lds_dwordx4 v[224:225], off
	s_waitcnt vmcnt(8)
	s_waitcnt lgkmcnt(0)
	s_barrier
	v_mfma_f32_16x16x32_bf16 v[126:129], v[130:133], v[162:165], v[126:129]
	v_mfma_f32_16x16x32_bf16 v[126:129], v[134:137], v[166:169], v[126:129]
	v_mfma_f32_16x16x32_bf16 v[122:125], v[138:141], v[162:165], v[122:125]
	v_mfma_f32_16x16x32_bf16 v[122:125], v[142:145], v[166:169], v[122:125]
	v_mfma_f32_16x16x32_bf16 v[110:113], v[130:133], v[186:189], v[110:113]
	v_mfma_f32_16x16x32_bf16 v[110:113], v[134:137], v[190:193], v[110:113]
	v_mfma_f32_16x16x32_bf16 v[106:109], v[138:141], v[186:189], v[106:109]
	v_mfma_f32_16x16x32_bf16 v[106:109], v[142:145], v[190:193], v[106:109]
	v_mfma_f32_16x16x32_bf16 v[94:97], v[130:133], v[194:197], v[94:97]
	v_mfma_f32_16x16x32_bf16 v[94:97], v[134:137], v[198:201], v[94:97]
	v_mfma_f32_16x16x32_bf16 v[90:93], v[138:141], v[194:197], v[90:93]
	v_mfma_f32_16x16x32_bf16 v[90:93], v[142:145], v[198:201], v[90:93]
	v_mfma_f32_16x16x32_bf16 v[78:81], v[130:133], v[202:205], v[78:81]
	v_mfma_f32_16x16x32_bf16 v[78:81], v[134:137], v[206:209], v[78:81]
	v_mfma_f32_16x16x32_bf16 v[74:77], v[138:141], v[202:205], v[74:77]
	v_mfma_f32_16x16x32_bf16 v[74:77], v[142:145], v[206:209], v[74:77]
	v_mfma_f32_16x16x32_bf16 v[118:121], v[146:149], v[162:165], v[118:121]
	v_mfma_f32_16x16x32_bf16 v[118:121], v[150:153], v[166:169], v[118:121]
	v_mfma_f32_16x16x32_bf16 v[114:117], v[154:157], v[162:165], v[114:117]
	v_mfma_f32_16x16x32_bf16 v[114:117], v[158:161], v[166:169], v[114:117]
	v_mfma_f32_16x16x32_bf16 v[102:105], v[146:149], v[186:189], v[102:105]
	v_mfma_f32_16x16x32_bf16 v[102:105], v[150:153], v[190:193], v[102:105]
	v_mfma_f32_16x16x32_bf16 v[98:101], v[154:157], v[186:189], v[98:101]
	v_mfma_f32_16x16x32_bf16 v[98:101], v[158:161], v[190:193], v[98:101]
	v_mfma_f32_16x16x32_bf16 v[86:89], v[146:149], v[194:197], v[86:89]
	v_mfma_f32_16x16x32_bf16 v[86:89], v[150:153], v[198:201], v[86:89]
	v_mfma_f32_16x16x32_bf16 v[82:85], v[154:157], v[194:197], v[82:85]
	v_mfma_f32_16x16x32_bf16 v[82:85], v[158:161], v[198:201], v[82:85]
	v_mfma_f32_16x16x32_bf16 v[70:73], v[146:149], v[202:205], v[70:73]
	v_mfma_f32_16x16x32_bf16 v[70:73], v[150:153], v[206:209], v[70:73]
	v_mfma_f32_16x16x32_bf16 v[66:69], v[154:157], v[202:205], v[66:69]
	v_mfma_f32_16x16x32_bf16 v[66:69], v[158:161], v[206:209], v[66:69]
	s_barrier
	s_add_i32 s42, s76, s17
	v_lshl_add_u64 v[216:217], v[216:217], 0, s[8:9]
	s_mov_b32 m0, s42
	ds_read_b128 v[162:165], v214 offset:49152
	ds_read_b128 v[166:169], v214 offset:50176
	ds_read_b128 v[186:189], v214 offset:51200
	ds_read_b128 v[190:193], v214 offset:52224
	ds_read_b128 v[194:197], v214 offset:53248
	ds_read_b128 v[198:201], v214 offset:54272
	ds_read_b128 v[202:205], v214 offset:55296
	ds_read_b128 v[206:209], v214 offset:56320
	global_load_lds_dwordx4 v[216:217], off
	s_add_i32 m0, s42, 0x2000
	s_add_u32 s40, s40, 0x100080
	v_lshl_add_u64 v[216:217], v[218:219], 0, s[8:9]
	s_addc_u32 s41, s41, 0
	s_add_i32 s42, s77, s17
	global_load_lds_dwordx4 v[216:217], off
	v_lshl_add_u64 v[216:217], s[40:41], 0, v[172:173]
	s_mov_b32 m0, s42
	s_nop 0
	global_load_lds_dwordx4 v[216:217], off
	v_lshl_add_u64 v[216:217], s[40:41], 0, v[176:177]
	s_add_i32 m0, s42, 0x2000
	s_nop 0
	global_load_lds_dwordx4 v[216:217], off
	v_lshl_add_u64 v[216:217], v[220:221], 0, s[8:9]
	s_mov_b32 m0, s50
	s_nop 0
	global_load_lds_dwordx4 v[216:217], off
	v_lshl_add_u64 v[216:217], v[222:223], 0, s[8:9]
	s_mov_b32 m0, s51
	s_nop 0
	global_load_lds_dwordx4 v[216:217], off
	s_waitcnt vmcnt(8)
	s_waitcnt lgkmcnt(0)
	s_barrier
	v_mfma_f32_16x16x32_bf16 v[62:65], v[130:133], v[162:165], v[62:65]
	v_mfma_f32_16x16x32_bf16 v[62:65], v[134:137], v[166:169], v[62:65]
	v_mfma_f32_16x16x32_bf16 v[58:61], v[138:141], v[162:165], v[58:61]
	v_mfma_f32_16x16x32_bf16 v[58:61], v[142:145], v[166:169], v[58:61]
	v_mfma_f32_16x16x32_bf16 v[46:49], v[130:133], v[186:189], v[46:49]
	v_mfma_f32_16x16x32_bf16 v[46:49], v[134:137], v[190:193], v[46:49]
	v_mfma_f32_16x16x32_bf16 v[42:45], v[138:141], v[186:189], v[42:45]
	v_mfma_f32_16x16x32_bf16 v[42:45], v[142:145], v[190:193], v[42:45]
	v_mfma_f32_16x16x32_bf16 v[30:33], v[130:133], v[194:197], v[30:33]
	v_mfma_f32_16x16x32_bf16 v[30:33], v[134:137], v[198:201], v[30:33]
	v_mfma_f32_16x16x32_bf16 v[26:29], v[138:141], v[194:197], v[26:29]
	v_mfma_f32_16x16x32_bf16 v[26:29], v[142:145], v[198:201], v[26:29]
	v_mfma_f32_16x16x32_bf16 v[14:17], v[130:133], v[202:205], v[14:17]
	v_mfma_f32_16x16x32_bf16 v[14:17], v[134:137], v[206:209], v[14:17]
	v_mfma_f32_16x16x32_bf16 v[10:13], v[138:141], v[202:205], v[10:13]
	v_mfma_f32_16x16x32_bf16 v[10:13], v[142:145], v[206:209], v[10:13]
	v_mfma_f32_16x16x32_bf16 v[54:57], v[146:149], v[162:165], v[54:57]
	v_mfma_f32_16x16x32_bf16 v[54:57], v[150:153], v[166:169], v[54:57]
	v_mfma_f32_16x16x32_bf16 v[50:53], v[154:157], v[162:165], v[50:53]
	v_mfma_f32_16x16x32_bf16 v[50:53], v[158:161], v[166:169], v[50:53]
	v_mfma_f32_16x16x32_bf16 v[38:41], v[146:149], v[186:189], v[38:41]
	v_mfma_f32_16x16x32_bf16 v[38:41], v[150:153], v[190:193], v[38:41]
	v_mfma_f32_16x16x32_bf16 v[34:37], v[154:157], v[186:189], v[34:37]
	v_mfma_f32_16x16x32_bf16 v[34:37], v[158:161], v[190:193], v[34:37]
	v_mfma_f32_16x16x32_bf16 v[22:25], v[146:149], v[194:197], v[22:25]
	v_mfma_f32_16x16x32_bf16 v[22:25], v[150:153], v[198:201], v[22:25]
	v_mfma_f32_16x16x32_bf16 v[18:21], v[154:157], v[194:197], v[18:21]
	v_mfma_f32_16x16x32_bf16 v[18:21], v[158:161], v[198:201], v[18:21]
	v_mfma_f32_16x16x32_bf16 v[6:9], v[146:149], v[202:205], v[6:9]
	v_mfma_f32_16x16x32_bf16 v[6:9], v[150:153], v[206:209], v[6:9]
	v_mfma_f32_16x16x32_bf16 v[2:5], v[154:157], v[202:205], v[2:5]
	v_mfma_f32_16x16x32_bf16 v[2:5], v[158:161], v[206:209], v[2:5]
	s_barrier
	s_add_i32 s73, s73, 2
	s_add_u32 s38, s38, 0x100
	s_addc_u32 s39, s39, 0
	s_add_u32 s71, s71, 0x100
	s_addc_u32 s72, s72, 0
	s_cmp_gt_u32 s73, 61
	s_cbranch_scc0 .LBB0_1921
	s_and_b64 vcc, exec, s[10:11]
	s_cbranch_vccz .LBB0_1924
	s_barrier

.LBB0_2055:
	s_ashr_i32 s31, s30, 31
	s_lshl_b64 s[18:19], s[30:31], 20
	s_add_u32 s34, s27, s18
	s_addc_u32 s35, s44, s19
	s_and_b64 s[18:19], s[0:1], exec
	s_cselect_b32 s31, s35, s3
	s_cselect_b32 s87, s34, s2
	s_ashr_i32 s29, s28, 31
	s_lshl_b64 s[18:19], s[28:29], 20
	s_add_u32 s36, s45, s18
	s_addc_u32 s37, s46, s19
	s_and_b64 s[18:19], s[0:1], exec
	s_cselect_b32 s29, s37, s5
	s_cselect_b32 s90, s36, s4
	s_add_u32 s91, s4, 0x100
	s_addc_u32 s92, s5, 0
	s_mov_b32 s93, -2
	ds_read_b128 v[130:133], v234
	ds_read_b128 v[134:137], v234 offset:1024
	ds_read_b128 v[162:165], v234 offset:2048
	ds_read_b128 v[166:169], v234 offset:3072
	ds_read_b128 v[170:173], v235
	ds_read_b128 v[174:177], v235 offset:1024
	ds_read_b128 v[178:181], v235 offset:2048
	ds_read_b128 v[182:185], v235 offset:3072
	s_add_u32 s4, s2, 0x100
	s_addc_u32 s5, s3, 0
	s_cmp_eq_u32 s93, 28
	s_cselect_b32 s43, s31, s5
	s_cselect_b32 s42, s87, s4
	s_cselect_b32 s19, s29, s92
	s_cselect_b32 s18, s90, s91
	v_lshl_add_u64 v[218:219], s[2:3], 0, v[154:155]
	s_add_i32 m0, s49, 0xc000
	ds_read_b128 v[186:189], v236
	ds_read_b128 v[190:193], v236 offset:1024
	ds_read_b128 v[194:197], v236 offset:2048
	ds_read_b128 v[198:201], v236 offset:3072
	ds_read_b128 v[202:205], v236 offset:4096
	ds_read_b128 v[206:209], v236 offset:5120
	ds_read_b128 v[210:213], v236 offset:6144
	ds_read_b128 v[214:217], v236 offset:7168
	global_load_lds_dwordx4 v[218:219], off
	v_lshl_add_u64 v[218:219], s[2:3], 0, v[156:157]
	s_add_i32 m0, s49, 0xe000
	s_nop 0
	global_load_lds_dwordx4 v[218:219], off
	s_waitcnt vmcnt(8)
	s_waitcnt lgkmcnt(0)
	s_barrier
	v_mfma_i32_16x16x64_i8 v[118:121], v[130:133], v[186:189], 0
	v_mfma_i32_16x16x64_i8 v[118:121], v[134:137], v[190:193], v[118:121]
	v_mfma_i32_16x16x64_i8 v[102:105], v[162:165], v[186:189], 0
	v_mfma_i32_16x16x64_i8 v[102:105], v[166:169], v[190:193], v[102:105]
	v_mfma_i32_16x16x64_i8 v[114:117], v[130:133], v[194:197], 0
	v_mfma_i32_16x16x64_i8 v[114:117], v[134:137], v[198:201], v[114:117]
	v_mfma_i32_16x16x64_i8 v[98:101], v[162:165], v[194:197], 0
	v_mfma_i32_16x16x64_i8 v[98:101], v[166:169], v[198:201], v[98:101]
	v_mfma_i32_16x16x64_i8 v[126:129], v[130:133], v[202:205], 0
	v_mfma_i32_16x16x64_i8 v[126:129], v[134:137], v[206:209], v[126:129]
	v_mfma_i32_16x16x64_i8 v[110:113], v[162:165], v[202:205], 0
	v_mfma_i32_16x16x64_i8 v[110:113], v[166:169], v[206:209], v[110:113]
	v_mfma_i32_16x16x64_i8 v[122:125], v[130:133], v[210:213], 0
	v_mfma_i32_16x16x64_i8 v[122:125], v[134:137], v[214:217], v[122:125]
	v_mfma_i32_16x16x64_i8 v[106:109], v[162:165], v[210:213], 0
	v_mfma_i32_16x16x64_i8 v[106:109], v[166:169], v[214:217], v[106:109]
	v_mfma_i32_16x16x64_i8 v[86:89], v[170:173], v[186:189], 0
	v_mfma_i32_16x16x64_i8 v[86:89], v[174:177], v[190:193], v[86:89]
	v_mfma_i32_16x16x64_i8 v[70:73], v[178:181], v[186:189], 0
	v_mfma_i32_16x16x64_i8 v[70:73], v[182:185], v[190:193], v[70:73]
	v_mfma_i32_16x16x64_i8 v[82:85], v[170:173], v[194:197], 0
	v_mfma_i32_16x16x64_i8 v[82:85], v[174:177], v[198:201], v[82:85]
	v_mfma_i32_16x16x64_i8 v[66:69], v[178:181], v[194:197], 0
	v_mfma_i32_16x16x64_i8 v[66:69], v[182:185], v[198:201], v[66:69]
	v_mfma_i32_16x16x64_i8 v[94:97], v[170:173], v[202:205], 0
	v_mfma_i32_16x16x64_i8 v[94:97], v[174:177], v[206:209], v[94:97]
	v_mfma_i32_16x16x64_i8 v[78:81], v[178:181], v[202:205], 0
	v_mfma_i32_16x16x64_i8 v[78:81], v[182:185], v[206:209], v[78:81]
	v_mfma_i32_16x16x64_i8 v[90:93], v[170:173], v[210:213], 0
	v_mfma_i32_16x16x64_i8 v[90:93], v[174:177], v[214:217], v[90:93]
	v_mfma_i32_16x16x64_i8 v[74:77], v[178:181], v[210:213], 0
	v_mfma_i32_16x16x64_i8 v[74:77], v[182:185], v[214:217], v[74:77]
	s_barrier
	s_add_i32 s2, s82, s47
	v_lshl_add_u64 v[218:219], s[18:19], 0, v[144:145]
	s_mov_b32 m0, s2
	ds_read_b128 v[186:189], v236 offset:16384
	ds_read_b128 v[190:193], v236 offset:17408
	ds_read_b128 v[194:197], v236 offset:18432
	ds_read_b128 v[198:201], v236 offset:19456
	ds_read_b128 v[202:205], v236 offset:20480
	ds_read_b128 v[206:209], v236 offset:21504
	ds_read_b128 v[210:213], v236 offset:22528
	ds_read_b128 v[214:217], v236 offset:23552
	global_load_lds_dwordx4 v[218:219], off
	s_add_i32 m0, s2, 0x2000
	s_add_u32 s2, s18, 0x80000
	v_lshl_add_u64 v[220:221], s[18:19], 0, v[148:149]
	s_addc_u32 s3, s19, 0
	s_add_i32 s94, s16, s47
	global_load_lds_dwordx4 v[220:221], off
	v_lshl_add_u64 v[222:223], s[2:3], 0, v[144:145]
	s_mov_b32 m0, s94
	v_lshl_add_u64 v[224:225], s[42:43], 0, v[146:147]
	global_load_lds_dwordx4 v[222:223], off
	v_lshl_add_u64 v[222:223], s[2:3], 0, v[148:149]
	s_add_i32 m0, s94, 0x2000
	s_nop 0
	global_load_lds_dwordx4 v[222:223], off
	v_lshl_add_u64 v[222:223], s[42:43], 0, v[142:143]
	s_mov_b32 m0, s49
	s_nop 0
	global_load_lds_dwordx4 v[222:223], off
	s_mov_b32 m0, s50
	s_nop 0
	global_load_lds_dwordx4 v[224:225], off
	s_waitcnt vmcnt(8)
	s_waitcnt lgkmcnt(0)
	s_barrier
	v_mfma_i32_16x16x64_i8 v[54:57], v[130:133], v[186:189], 0
	v_mfma_i32_16x16x64_i8 v[54:57], v[134:137], v[190:193], v[54:57]
	v_mfma_i32_16x16x64_i8 v[18:21], v[162:165], v[186:189], 0
	v_mfma_i32_16x16x64_i8 v[18:21], v[166:169], v[190:193], v[18:21]
	v_mfma_i32_16x16x64_i8 v[50:53], v[130:133], v[194:197], 0
	v_mfma_i32_16x16x64_i8 v[50:53], v[134:137], v[198:201], v[50:53]
	v_mfma_i32_16x16x64_i8 v[22:25], v[162:165], v[194:197], 0
	v_mfma_i32_16x16x64_i8 v[22:25], v[166:169], v[198:201], v[22:25]
	v_mfma_i32_16x16x64_i8 v[62:65], v[130:133], v[202:205], 0
	v_mfma_i32_16x16x64_i8 v[62:65], v[134:137], v[206:209], v[62:65]
	v_mfma_i32_16x16x64_i8 v[30:33], v[162:165], v[202:205], 0
	v_mfma_i32_16x16x64_i8 v[30:33], v[166:169], v[206:209], v[30:33]
	v_mfma_i32_16x16x64_i8 v[58:61], v[130:133], v[210:213], 0
	v_mfma_i32_16x16x64_i8 v[58:61], v[134:137], v[214:217], v[58:61]
	v_mfma_i32_16x16x64_i8 v[26:29], v[162:165], v[210:213], 0
	v_mfma_i32_16x16x64_i8 v[26:29], v[166:169], v[214:217], v[26:29]
	v_mfma_i32_16x16x64_i8 v[46:49], v[170:173], v[186:189], 0
	v_mfma_i32_16x16x64_i8 v[46:49], v[174:177], v[190:193], v[46:49]
	v_mfma_i32_16x16x64_i8 v[14:17], v[178:181], v[186:189], 0
	v_mfma_i32_16x16x64_i8 v[14:17], v[182:185], v[190:193], v[14:17]
	v_mfma_i32_16x16x64_i8 v[42:45], v[170:173], v[194:197], 0
	v_mfma_i32_16x16x64_i8 v[42:45], v[174:177], v[198:201], v[42:45]
	v_mfma_i32_16x16x64_i8 v[10:13], v[178:181], v[194:197], 0
	v_mfma_i32_16x16x64_i8 v[10:13], v[182:185], v[198:201], v[10:13]
	v_mfma_i32_16x16x64_i8 v[38:41], v[170:173], v[202:205], 0
	v_mfma_i32_16x16x64_i8 v[38:41], v[174:177], v[206:209], v[38:41]
	v_mfma_i32_16x16x64_i8 v[6:9], v[178:181], v[202:205], 0
	v_mfma_i32_16x16x64_i8 v[6:9], v[182:185], v[206:209], v[6:9]
	v_mfma_i32_16x16x64_i8 v[34:37], v[170:173], v[210:213], 0
	v_mfma_i32_16x16x64_i8 v[34:37], v[174:177], v[214:217], v[34:37]
	v_mfma_i32_16x16x64_i8 v[2:5], v[178:181], v[210:213], 0
	v_mfma_i32_16x16x64_i8 v[2:5], v[182:185], v[214:217], v[2:5]
	s_barrier
	s_add_i32 s94, 0, 0x18000
	s_add_i32 s95, 0, 0x1c000
	v_add_u32_e32 v166, s94, v232
	v_add_u32_e32 v182, s95, v232
	ds_read_b128 v[130:133], v166
	ds_read_b128 v[134:137], v166 offset:1024
	ds_read_b128 v[162:165], v166 offset:2048
	ds_read_b128 v[166:169], v166 offset:3072
	ds_read_b128 v[170:173], v182
	ds_read_b128 v[174:177], v182 offset:1024
	ds_read_b128 v[178:181], v182 offset:2048
	ds_read_b128 v[182:185], v182 offset:3072
	s_add_u32 s2, s42, 0x80000
	s_addc_u32 s3, s43, 0
	s_mov_b32 m0, s51
	v_lshl_add_u64 v[226:227], s[2:3], 0, v[142:143]
	ds_read_b128 v[186:189], v236 offset:32768
	ds_read_b128 v[190:193], v236 offset:33792
	ds_read_b128 v[194:197], v236 offset:34816
	ds_read_b128 v[198:201], v236 offset:35840
	ds_read_b128 v[202:205], v236 offset:36864
	ds_read_b128 v[206:209], v236 offset:37888
	ds_read_b128 v[210:213], v236 offset:38912
	ds_read_b128 v[214:217], v236 offset:39936
	global_load_lds_dwordx4 v[226:227], off
	v_lshl_add_u64 v[226:227], s[2:3], 0, v[146:147]
	s_mov_b32 m0, s54
	s_nop 0
	global_load_lds_dwordx4 v[226:227], off
	s_waitcnt vmcnt(8)
	s_waitcnt lgkmcnt(0)
	s_barrier
	v_mfma_i32_16x16x64_i8 v[118:121], v[130:133], v[186:189], v[118:121]
	v_mfma_i32_16x16x64_i8 v[118:121], v[134:137], v[190:193], v[118:121]
	v_mfma_i32_16x16x64_i8 v[102:105], v[162:165], v[186:189], v[102:105]
	v_mfma_i32_16x16x64_i8 v[102:105], v[166:169], v[190:193], v[102:105]
	v_mfma_i32_16x16x64_i8 v[114:117], v[130:133], v[194:197], v[114:117]
	v_mfma_i32_16x16x64_i8 v[114:117], v[134:137], v[198:201], v[114:117]
	v_mfma_i32_16x16x64_i8 v[98:101], v[162:165], v[194:197], v[98:101]
	v_mfma_i32_16x16x64_i8 v[98:101], v[166:169], v[198:201], v[98:101]
	v_mfma_i32_16x16x64_i8 v[126:129], v[130:133], v[202:205], v[126:129]
	v_mfma_i32_16x16x64_i8 v[126:129], v[134:137], v[206:209], v[126:129]
	v_mfma_i32_16x16x64_i8 v[110:113], v[162:165], v[202:205], v[110:113]
	v_mfma_i32_16x16x64_i8 v[110:113], v[166:169], v[206:209], v[110:113]
	v_mfma_i32_16x16x64_i8 v[122:125], v[130:133], v[210:213], v[122:125]
	v_mfma_i32_16x16x64_i8 v[122:125], v[134:137], v[214:217], v[122:125]
	v_mfma_i32_16x16x64_i8 v[106:109], v[162:165], v[210:213], v[106:109]
	v_mfma_i32_16x16x64_i8 v[106:109], v[166:169], v[214:217], v[106:109]
	v_mfma_i32_16x16x64_i8 v[86:89], v[170:173], v[186:189], v[86:89]
	v_mfma_i32_16x16x64_i8 v[86:89], v[174:177], v[190:193], v[86:89]
	v_mfma_i32_16x16x64_i8 v[70:73], v[178:181], v[186:189], v[70:73]
	v_mfma_i32_16x16x64_i8 v[70:73], v[182:185], v[190:193], v[70:73]
	v_mfma_i32_16x16x64_i8 v[82:85], v[170:173], v[194:197], v[82:85]
	v_mfma_i32_16x16x64_i8 v[82:85], v[174:177], v[198:201], v[82:85]
	v_mfma_i32_16x16x64_i8 v[66:69], v[178:181], v[194:197], v[66:69]
	v_mfma_i32_16x16x64_i8 v[66:69], v[182:185], v[198:201], v[66:69]
	v_mfma_i32_16x16x64_i8 v[94:97], v[170:173], v[202:205], v[94:97]
	v_mfma_i32_16x16x64_i8 v[94:97], v[174:177], v[206:209], v[94:97]
	v_mfma_i32_16x16x64_i8 v[78:81], v[178:181], v[202:205], v[78:81]
	v_mfma_i32_16x16x64_i8 v[78:81], v[182:185], v[206:209], v[78:81]
	v_mfma_i32_16x16x64_i8 v[90:93], v[170:173], v[210:213], v[90:93]
	v_mfma_i32_16x16x64_i8 v[90:93], v[174:177], v[214:217], v[90:93]
	v_mfma_i32_16x16x64_i8 v[74:77], v[178:181], v[210:213], v[74:77]
	v_mfma_i32_16x16x64_i8 v[74:77], v[182:185], v[214:217], v[74:77]
	s_barrier
	s_add_i32 s2, s94, s47
	v_lshl_add_u64 v[218:219], v[218:219], 0, s[14:15]
	s_mov_b32 m0, s2
	ds_read_b128 v[186:189], v236 offset:49152
	ds_read_b128 v[190:193], v236 offset:50176
	ds_read_b128 v[194:197], v236 offset:51200
	ds_read_b128 v[198:201], v236 offset:52224
	ds_read_b128 v[202:205], v236 offset:53248
	ds_read_b128 v[206:209], v236 offset:54272
	ds_read_b128 v[210:213], v236 offset:55296
	ds_read_b128 v[214:217], v236 offset:56320
	global_load_lds_dwordx4 v[218:219], off
	s_add_i32 m0, s2, 0x2000
	s_add_u32 s2, s18, 0x80080
	v_lshl_add_u64 v[218:219], v[220:221], 0, s[14:15]
	s_addc_u32 s3, s19, 0
	s_add_i32 s18, s95, s47
	global_load_lds_dwordx4 v[218:219], off
	v_lshl_add_u64 v[218:219], s[2:3], 0, v[144:145]
	s_mov_b32 m0, s18
	s_nop 0
	global_load_lds_dwordx4 v[218:219], off
	v_lshl_add_u64 v[218:219], s[2:3], 0, v[148:149]
	s_add_i32 m0, s18, 0x2000
	s_nop 0
	global_load_lds_dwordx4 v[218:219], off
	v_lshl_add_u64 v[218:219], v[222:223], 0, s[14:15]
	s_mov_b32 m0, s63
	s_nop 0
	global_load_lds_dwordx4 v[218:219], off
	v_lshl_add_u64 v[218:219], v[224:225], 0, s[14:15]
	s_mov_b32 m0, s64
	s_nop 0
	global_load_lds_dwordx4 v[218:219], off
	s_waitcnt vmcnt(8)
	s_waitcnt lgkmcnt(0)
	s_barrier
	v_mfma_i32_16x16x64_i8 v[54:57], v[130:133], v[186:189], v[54:57]
	v_mfma_i32_16x16x64_i8 v[54:57], v[134:137], v[190:193], v[54:57]
	v_mfma_i32_16x16x64_i8 v[18:21], v[162:165], v[186:189], v[18:21]
	v_mfma_i32_16x16x64_i8 v[18:21], v[166:169], v[190:193], v[18:21]
	v_mfma_i32_16x16x64_i8 v[50:53], v[130:133], v[194:197], v[50:53]
	v_mfma_i32_16x16x64_i8 v[50:53], v[134:137], v[198:201], v[50:53]
	v_mfma_i32_16x16x64_i8 v[22:25], v[162:165], v[194:197], v[22:25]
	v_mfma_i32_16x16x64_i8 v[22:25], v[166:169], v[198:201], v[22:25]
	v_mfma_i32_16x16x64_i8 v[62:65], v[130:133], v[202:205], v[62:65]
	v_mfma_i32_16x16x64_i8 v[62:65], v[134:137], v[206:209], v[62:65]
	v_mfma_i32_16x16x64_i8 v[30:33], v[162:165], v[202:205], v[30:33]
	v_mfma_i32_16x16x64_i8 v[30:33], v[166:169], v[206:209], v[30:33]
	v_mfma_i32_16x16x64_i8 v[58:61], v[130:133], v[210:213], v[58:61]
	v_mfma_i32_16x16x64_i8 v[58:61], v[134:137], v[214:217], v[58:61]
	v_mfma_i32_16x16x64_i8 v[26:29], v[162:165], v[210:213], v[26:29]
	v_mfma_i32_16x16x64_i8 v[26:29], v[166:169], v[214:217], v[26:29]
	v_mfma_i32_16x16x64_i8 v[46:49], v[170:173], v[186:189], v[46:49]
	v_mfma_i32_16x16x64_i8 v[46:49], v[174:177], v[190:193], v[46:49]
	v_mfma_i32_16x16x64_i8 v[14:17], v[178:181], v[186:189], v[14:17]
	v_mfma_i32_16x16x64_i8 v[14:17], v[182:185], v[190:193], v[14:17]
	v_mfma_i32_16x16x64_i8 v[42:45], v[170:173], v[194:197], v[42:45]
	v_mfma_i32_16x16x64_i8 v[42:45], v[174:177], v[198:201], v[42:45]
	v_mfma_i32_16x16x64_i8 v[10:13], v[178:181], v[194:197], v[10:13]
	v_mfma_i32_16x16x64_i8 v[10:13], v[182:185], v[198:201], v[10:13]
	v_mfma_i32_16x16x64_i8 v[38:41], v[170:173], v[202:205], v[38:41]
	v_mfma_i32_16x16x64_i8 v[38:41], v[174:177], v[206:209], v[38:41]
	v_mfma_i32_16x16x64_i8 v[6:9], v[178:181], v[202:205], v[6:9]
	v_mfma_i32_16x16x64_i8 v[6:9], v[182:185], v[206:209], v[6:9]
	v_mfma_i32_16x16x64_i8 v[34:37], v[170:173], v[210:213], v[34:37]
	v_mfma_i32_16x16x64_i8 v[34:37], v[174:177], v[214:217], v[34:37]
	v_mfma_i32_16x16x64_i8 v[2:5], v[178:181], v[210:213], v[2:5]
	v_mfma_i32_16x16x64_i8 v[2:5], v[182:185], v[214:217], v[2:5]
	s_barrier
	s_add_i32 s93, s93, 2
	s_add_u32 s91, s91, 0x100
	s_addc_u32 s92, s92, 0
	s_cmp_gt_u32 s93, 29
	s_mov_b64 s[2:3], s[4:5]
.LBB0_2056:
	ds_read_b128 v[130:133], v234
	ds_read_b128 v[134:137], v234 offset:1024
	ds_read_b128 v[162:165], v234 offset:2048
	ds_read_b128 v[166:169], v234 offset:3072
	ds_read_b128 v[170:173], v235
	ds_read_b128 v[174:177], v235 offset:1024
	ds_read_b128 v[178:181], v235 offset:2048
	ds_read_b128 v[182:185], v235 offset:3072
	s_add_u32 s4, s2, 0x100
	s_addc_u32 s5, s3, 0
	s_cmp_eq_u32 s93, 28
	s_cselect_b32 s43, s31, s5
	s_cselect_b32 s42, s87, s4
	s_cselect_b32 s19, s29, s92
	s_cselect_b32 s18, s90, s91
	v_lshl_add_u64 v[218:219], s[2:3], 0, v[154:155]
	s_add_i32 m0, s49, 0xc000
	ds_read_b128 v[186:189], v236
	ds_read_b128 v[190:193], v236 offset:1024
	ds_read_b128 v[194:197], v236 offset:2048
	ds_read_b128 v[198:201], v236 offset:3072
	ds_read_b128 v[202:205], v236 offset:4096
	ds_read_b128 v[206:209], v236 offset:5120
	ds_read_b128 v[210:213], v236 offset:6144
	ds_read_b128 v[214:217], v236 offset:7168
	global_load_lds_dwordx4 v[218:219], off
	v_lshl_add_u64 v[218:219], s[2:3], 0, v[156:157]
	s_add_i32 m0, s49, 0xe000
	s_nop 0
	global_load_lds_dwordx4 v[218:219], off
	s_waitcnt vmcnt(8)
	s_waitcnt lgkmcnt(0)
	s_barrier
	v_mfma_i32_16x16x64_i8 v[118:121], v[130:133], v[186:189], v[118:121]
	v_mfma_i32_16x16x64_i8 v[118:121], v[134:137], v[190:193], v[118:121]
	v_mfma_i32_16x16x64_i8 v[102:105], v[162:165], v[186:189], v[102:105]
	v_mfma_i32_16x16x64_i8 v[102:105], v[166:169], v[190:193], v[102:105]
	v_mfma_i32_16x16x64_i8 v[114:117], v[130:133], v[194:197], v[114:117]
	v_mfma_i32_16x16x64_i8 v[114:117], v[134:137], v[198:201], v[114:117]
	v_mfma_i32_16x16x64_i8 v[98:101], v[162:165], v[194:197], v[98:101]
	v_mfma_i32_16x16x64_i8 v[98:101], v[166:169], v[198:201], v[98:101]
	v_mfma_i32_16x16x64_i8 v[126:129], v[130:133], v[202:205], v[126:129]
	v_mfma_i32_16x16x64_i8 v[126:129], v[134:137], v[206:209], v[126:129]
	v_mfma_i32_16x16x64_i8 v[110:113], v[162:165], v[202:205], v[110:113]
	v_mfma_i32_16x16x64_i8 v[110:113], v[166:169], v[206:209], v[110:113]
	v_mfma_i32_16x16x64_i8 v[122:125], v[130:133], v[210:213], v[122:125]
	v_mfma_i32_16x16x64_i8 v[122:125], v[134:137], v[214:217], v[122:125]
	v_mfma_i32_16x16x64_i8 v[106:109], v[162:165], v[210:213], v[106:109]
	v_mfma_i32_16x16x64_i8 v[106:109], v[166:169], v[214:217], v[106:109]
	v_mfma_i32_16x16x64_i8 v[86:89], v[170:173], v[186:189], v[86:89]
	v_mfma_i32_16x16x64_i8 v[86:89], v[174:177], v[190:193], v[86:89]
	v_mfma_i32_16x16x64_i8 v[70:73], v[178:181], v[186:189], v[70:73]
	v_mfma_i32_16x16x64_i8 v[70:73], v[182:185], v[190:193], v[70:73]
	v_mfma_i32_16x16x64_i8 v[82:85], v[170:173], v[194:197], v[82:85]
	v_mfma_i32_16x16x64_i8 v[82:85], v[174:177], v[198:201], v[82:85]
	v_mfma_i32_16x16x64_i8 v[66:69], v[178:181], v[194:197], v[66:69]
	v_mfma_i32_16x16x64_i8 v[66:69], v[182:185], v[198:201], v[66:69]
	v_mfma_i32_16x16x64_i8 v[94:97], v[170:173], v[202:205], v[94:97]
	v_mfma_i32_16x16x64_i8 v[94:97], v[174:177], v[206:209], v[94:97]
	v_mfma_i32_16x16x64_i8 v[78:81], v[178:181], v[202:205], v[78:81]
	v_mfma_i32_16x16x64_i8 v[78:81], v[182:185], v[206:209], v[78:81]
	v_mfma_i32_16x16x64_i8 v[90:93], v[170:173], v[210:213], v[90:93]
	v_mfma_i32_16x16x64_i8 v[90:93], v[174:177], v[214:217], v[90:93]
	v_mfma_i32_16x16x64_i8 v[74:77], v[178:181], v[210:213], v[74:77]
	v_mfma_i32_16x16x64_i8 v[74:77], v[182:185], v[214:217], v[74:77]
	s_barrier
	s_add_i32 s2, s82, s47
	v_lshl_add_u64 v[218:219], s[18:19], 0, v[144:145]
	s_mov_b32 m0, s2
	ds_read_b128 v[186:189], v236 offset:16384
	ds_read_b128 v[190:193], v236 offset:17408
	ds_read_b128 v[194:197], v236 offset:18432
	ds_read_b128 v[198:201], v236 offset:19456
	ds_read_b128 v[202:205], v236 offset:20480
	ds_read_b128 v[206:209], v236 offset:21504
	ds_read_b128 v[210:213], v236 offset:22528
	ds_read_b128 v[214:217], v236 offset:23552
	global_load_lds_dwordx4 v[218:219], off
	s_add_i32 m0, s2, 0x2000
	s_add_u32 s2, s18, 0x80000
	v_lshl_add_u64 v[220:221], s[18:19], 0, v[148:149]
	s_addc_u32 s3, s19, 0
	s_add_i32 s94, s16, s47
	global_load_lds_dwordx4 v[220:221], off
	v_lshl_add_u64 v[222:223], s[2:3], 0, v[144:145]
	s_mov_b32 m0, s94
	v_lshl_add_u64 v[224:225], s[42:43], 0, v[146:147]
	global_load_lds_dwordx4 v[222:223], off
	v_lshl_add_u64 v[222:223], s[2:3], 0, v[148:149]
	s_add_i32 m0, s94, 0x2000
	s_nop 0
	global_load_lds_dwordx4 v[222:223], off
	v_lshl_add_u64 v[222:223], s[42:43], 0, v[142:143]
	s_mov_b32 m0, s49
	s_nop 0
	global_load_lds_dwordx4 v[222:223], off
	s_mov_b32 m0, s50
	s_nop 0
	global_load_lds_dwordx4 v[224:225], off
	s_waitcnt vmcnt(8)
	s_waitcnt lgkmcnt(0)
	s_barrier
	v_mfma_i32_16x16x64_i8 v[54:57], v[130:133], v[186:189], v[54:57]
	v_mfma_i32_16x16x64_i8 v[54:57], v[134:137], v[190:193], v[54:57]
	v_mfma_i32_16x16x64_i8 v[18:21], v[162:165], v[186:189], v[18:21]
	v_mfma_i32_16x16x64_i8 v[18:21], v[166:169], v[190:193], v[18:21]
	v_mfma_i32_16x16x64_i8 v[50:53], v[130:133], v[194:197], v[50:53]
	v_mfma_i32_16x16x64_i8 v[50:53], v[134:137], v[198:201], v[50:53]
	v_mfma_i32_16x16x64_i8 v[22:25], v[162:165], v[194:197], v[22:25]
	v_mfma_i32_16x16x64_i8 v[22:25], v[166:169], v[198:201], v[22:25]
	v_mfma_i32_16x16x64_i8 v[62:65], v[130:133], v[202:205], v[62:65]
	v_mfma_i32_16x16x64_i8 v[62:65], v[134:137], v[206:209], v[62:65]
	v_mfma_i32_16x16x64_i8 v[30:33], v[162:165], v[202:205], v[30:33]
	v_mfma_i32_16x16x64_i8 v[30:33], v[166:169], v[206:209], v[30:33]
	v_mfma_i32_16x16x64_i8 v[58:61], v[130:133], v[210:213], v[58:61]
	v_mfma_i32_16x16x64_i8 v[58:61], v[134:137], v[214:217], v[58:61]
	v_mfma_i32_16x16x64_i8 v[26:29], v[162:165], v[210:213], v[26:29]
	v_mfma_i32_16x16x64_i8 v[26:29], v[166:169], v[214:217], v[26:29]
	v_mfma_i32_16x16x64_i8 v[46:49], v[170:173], v[186:189], v[46:49]
	v_mfma_i32_16x16x64_i8 v[46:49], v[174:177], v[190:193], v[46:49]
	v_mfma_i32_16x16x64_i8 v[14:17], v[178:181], v[186:189], v[14:17]
	v_mfma_i32_16x16x64_i8 v[14:17], v[182:185], v[190:193], v[14:17]
	v_mfma_i32_16x16x64_i8 v[42:45], v[170:173], v[194:197], v[42:45]
	v_mfma_i32_16x16x64_i8 v[42:45], v[174:177], v[198:201], v[42:45]
	v_mfma_i32_16x16x64_i8 v[10:13], v[178:181], v[194:197], v[10:13]
	v_mfma_i32_16x16x64_i8 v[10:13], v[182:185], v[198:201], v[10:13]
	v_mfma_i32_16x16x64_i8 v[38:41], v[170:173], v[202:205], v[38:41]
	v_mfma_i32_16x16x64_i8 v[38:41], v[174:177], v[206:209], v[38:41]
	v_mfma_i32_16x16x64_i8 v[6:9], v[178:181], v[202:205], v[6:9]
	v_mfma_i32_16x16x64_i8 v[6:9], v[182:185], v[206:209], v[6:9]
	v_mfma_i32_16x16x64_i8 v[34:37], v[170:173], v[210:213], v[34:37]
	v_mfma_i32_16x16x64_i8 v[34:37], v[174:177], v[214:217], v[34:37]
	v_mfma_i32_16x16x64_i8 v[2:5], v[178:181], v[210:213], v[2:5]
	v_mfma_i32_16x16x64_i8 v[2:5], v[182:185], v[214:217], v[2:5]
	s_barrier
	s_add_i32 s94, 0, 0x18000
	s_add_i32 s95, 0, 0x1c000
	v_add_u32_e32 v166, s94, v232
	v_add_u32_e32 v182, s95, v232
	ds_read_b128 v[130:133], v166
	ds_read_b128 v[134:137], v166 offset:1024
	ds_read_b128 v[162:165], v166 offset:2048
	ds_read_b128 v[166:169], v166 offset:3072
	ds_read_b128 v[170:173], v182
	ds_read_b128 v[174:177], v182 offset:1024
	ds_read_b128 v[178:181], v182 offset:2048
	ds_read_b128 v[182:185], v182 offset:3072
	s_add_u32 s2, s42, 0x80000
	s_addc_u32 s3, s43, 0
	s_mov_b32 m0, s51
	v_lshl_add_u64 v[226:227], s[2:3], 0, v[142:143]
	ds_read_b128 v[186:189], v236 offset:32768
	ds_read_b128 v[190:193], v236 offset:33792
	ds_read_b128 v[194:197], v236 offset:34816
	ds_read_b128 v[198:201], v236 offset:35840
	ds_read_b128 v[202:205], v236 offset:36864
	ds_read_b128 v[206:209], v236 offset:37888
	ds_read_b128 v[210:213], v236 offset:38912
	ds_read_b128 v[214:217], v236 offset:39936
	global_load_lds_dwordx4 v[226:227], off
	v_lshl_add_u64 v[226:227], s[2:3], 0, v[146:147]
	s_mov_b32 m0, s54
	s_nop 0
	global_load_lds_dwordx4 v[226:227], off
	s_waitcnt vmcnt(8)
	s_waitcnt lgkmcnt(0)
	s_barrier
	v_mfma_i32_16x16x64_i8 v[118:121], v[130:133], v[186:189], v[118:121]
	v_mfma_i32_16x16x64_i8 v[118:121], v[134:137], v[190:193], v[118:121]
	v_mfma_i32_16x16x64_i8 v[102:105], v[162:165], v[186:189], v[102:105]
	v_mfma_i32_16x16x64_i8 v[102:105], v[166:169], v[190:193], v[102:105]
	v_mfma_i32_16x16x64_i8 v[114:117], v[130:133], v[194:197], v[114:117]
	v_mfma_i32_16x16x64_i8 v[114:117], v[134:137], v[198:201], v[114:117]
	v_mfma_i32_16x16x64_i8 v[98:101], v[162:165], v[194:197], v[98:101]
	v_mfma_i32_16x16x64_i8 v[98:101], v[166:169], v[198:201], v[98:101]
	v_mfma_i32_16x16x64_i8 v[126:129], v[130:133], v[202:205], v[126:129]
	v_mfma_i32_16x16x64_i8 v[126:129], v[134:137], v[206:209], v[126:129]
	v_mfma_i32_16x16x64_i8 v[110:113], v[162:165], v[202:205], v[110:113]
	v_mfma_i32_16x16x64_i8 v[110:113], v[166:169], v[206:209], v[110:113]
	v_mfma_i32_16x16x64_i8 v[122:125], v[130:133], v[210:213], v[122:125]
	v_mfma_i32_16x16x64_i8 v[122:125], v[134:137], v[214:217], v[122:125]
	v_mfma_i32_16x16x64_i8 v[106:109], v[162:165], v[210:213], v[106:109]
	v_mfma_i32_16x16x64_i8 v[106:109], v[166:169], v[214:217], v[106:109]
	v_mfma_i32_16x16x64_i8 v[86:89], v[170:173], v[186:189], v[86:89]
	v_mfma_i32_16x16x64_i8 v[86:89], v[174:177], v[190:193], v[86:89]
	v_mfma_i32_16x16x64_i8 v[70:73], v[178:181], v[186:189], v[70:73]
	v_mfma_i32_16x16x64_i8 v[70:73], v[182:185], v[190:193], v[70:73]
	v_mfma_i32_16x16x64_i8 v[82:85], v[170:173], v[194:197], v[82:85]
	v_mfma_i32_16x16x64_i8 v[82:85], v[174:177], v[198:201], v[82:85]
	v_mfma_i32_16x16x64_i8 v[66:69], v[178:181], v[194:197], v[66:69]
	v_mfma_i32_16x16x64_i8 v[66:69], v[182:185], v[198:201], v[66:69]
	v_mfma_i32_16x16x64_i8 v[94:97], v[170:173], v[202:205], v[94:97]
	v_mfma_i32_16x16x64_i8 v[94:97], v[174:177], v[206:209], v[94:97]
	v_mfma_i32_16x16x64_i8 v[78:81], v[178:181], v[202:205], v[78:81]
	v_mfma_i32_16x16x64_i8 v[78:81], v[182:185], v[206:209], v[78:81]
	v_mfma_i32_16x16x64_i8 v[90:93], v[170:173], v[210:213], v[90:93]
	v_mfma_i32_16x16x64_i8 v[90:93], v[174:177], v[214:217], v[90:93]
	v_mfma_i32_16x16x64_i8 v[74:77], v[178:181], v[210:213], v[74:77]
	v_mfma_i32_16x16x64_i8 v[74:77], v[182:185], v[214:217], v[74:77]
	s_barrier
	s_add_i32 s2, s94, s47
	v_lshl_add_u64 v[218:219], v[218:219], 0, s[14:15]
	s_mov_b32 m0, s2
	ds_read_b128 v[186:189], v236 offset:49152
	ds_read_b128 v[190:193], v236 offset:50176
	ds_read_b128 v[194:197], v236 offset:51200
	ds_read_b128 v[198:201], v236 offset:52224
	ds_read_b128 v[202:205], v236 offset:53248
	ds_read_b128 v[206:209], v236 offset:54272
	ds_read_b128 v[210:213], v236 offset:55296
	ds_read_b128 v[214:217], v236 offset:56320
	global_load_lds_dwordx4 v[218:219], off
	s_add_i32 m0, s2, 0x2000
	s_add_u32 s2, s18, 0x80080
	v_lshl_add_u64 v[218:219], v[220:221], 0, s[14:15]
	s_addc_u32 s3, s19, 0
	s_add_i32 s18, s95, s47
	global_load_lds_dwordx4 v[218:219], off
	v_lshl_add_u64 v[218:219], s[2:3], 0, v[144:145]
	s_mov_b32 m0, s18
	s_nop 0
	global_load_lds_dwordx4 v[218:219], off
	v_lshl_add_u64 v[218:219], s[2:3], 0, v[148:149]
	s_add_i32 m0, s18, 0x2000
	s_nop 0
	global_load_lds_dwordx4 v[218:219], off
	v_lshl_add_u64 v[218:219], v[222:223], 0, s[14:15]
	s_mov_b32 m0, s63
	s_nop 0
	global_load_lds_dwordx4 v[218:219], off
	v_lshl_add_u64 v[218:219], v[224:225], 0, s[14:15]
	s_mov_b32 m0, s64
	s_nop 0
	global_load_lds_dwordx4 v[218:219], off
	s_waitcnt vmcnt(8)
	s_waitcnt lgkmcnt(0)
	s_barrier
	v_mfma_i32_16x16x64_i8 v[54:57], v[130:133], v[186:189], v[54:57]
	v_mfma_i32_16x16x64_i8 v[54:57], v[134:137], v[190:193], v[54:57]
	v_mfma_i32_16x16x64_i8 v[18:21], v[162:165], v[186:189], v[18:21]
	v_mfma_i32_16x16x64_i8 v[18:21], v[166:169], v[190:193], v[18:21]
	v_mfma_i32_16x16x64_i8 v[50:53], v[130:133], v[194:197], v[50:53]
	v_mfma_i32_16x16x64_i8 v[50:53], v[134:137], v[198:201], v[50:53]
	v_mfma_i32_16x16x64_i8 v[22:25], v[162:165], v[194:197], v[22:25]
	v_mfma_i32_16x16x64_i8 v[22:25], v[166:169], v[198:201], v[22:25]
	v_mfma_i32_16x16x64_i8 v[62:65], v[130:133], v[202:205], v[62:65]
	v_mfma_i32_16x16x64_i8 v[62:65], v[134:137], v[206:209], v[62:65]
	v_mfma_i32_16x16x64_i8 v[30:33], v[162:165], v[202:205], v[30:33]
	v_mfma_i32_16x16x64_i8 v[30:33], v[166:169], v[206:209], v[30:33]
	v_mfma_i32_16x16x64_i8 v[58:61], v[130:133], v[210:213], v[58:61]
	v_mfma_i32_16x16x64_i8 v[58:61], v[134:137], v[214:217], v[58:61]
	v_mfma_i32_16x16x64_i8 v[26:29], v[162:165], v[210:213], v[26:29]
	v_mfma_i32_16x16x64_i8 v[26:29], v[166:169], v[214:217], v[26:29]
	v_mfma_i32_16x16x64_i8 v[46:49], v[170:173], v[186:189], v[46:49]
	v_mfma_i32_16x16x64_i8 v[46:49], v[174:177], v[190:193], v[46:49]
	v_mfma_i32_16x16x64_i8 v[14:17], v[178:181], v[186:189], v[14:17]
	v_mfma_i32_16x16x64_i8 v[14:17], v[182:185], v[190:193], v[14:17]
	v_mfma_i32_16x16x64_i8 v[42:45], v[170:173], v[194:197], v[42:45]
	v_mfma_i32_16x16x64_i8 v[42:45], v[174:177], v[198:201], v[42:45]
	v_mfma_i32_16x16x64_i8 v[10:13], v[178:181], v[194:197], v[10:13]
	v_mfma_i32_16x16x64_i8 v[10:13], v[182:185], v[198:201], v[10:13]
	v_mfma_i32_16x16x64_i8 v[38:41], v[170:173], v[202:205], v[38:41]
	v_mfma_i32_16x16x64_i8 v[38:41], v[174:177], v[206:209], v[38:41]
	v_mfma_i32_16x16x64_i8 v[6:9], v[178:181], v[202:205], v[6:9]
	v_mfma_i32_16x16x64_i8 v[6:9], v[182:185], v[206:209], v[6:9]
	v_mfma_i32_16x16x64_i8 v[34:37], v[170:173], v[210:213], v[34:37]
	v_mfma_i32_16x16x64_i8 v[34:37], v[174:177], v[214:217], v[34:37]
	v_mfma_i32_16x16x64_i8 v[2:5], v[178:181], v[210:213], v[2:5]
	v_mfma_i32_16x16x64_i8 v[2:5], v[182:185], v[214:217], v[2:5]
	s_barrier
	s_add_i32 s93, s93, 2
	s_add_u32 s91, s91, 0x100
	s_addc_u32 s92, s92, 0
	s_cmp_gt_u32 s93, 29
	s_mov_b64 s[2:3], s[4:5]
	s_cbranch_scc0 .LBB0_2056
	s_and_b64 vcc, exec, s[8:9]
	s_cbranch_vccz .LBB0_2059
	s_barrier

.LBB0_2240:
	s_add_u32 s69, s36, 0x100
	s_addc_u32 s70, s37, 0
	s_mov_b32 s71, -2
	ds_read_b128 v[130:133], v212
	ds_read_b128 v[134:137], v212 offset:1024
	ds_read_b128 v[138:141], v212 offset:2048
	ds_read_b128 v[142:145], v212 offset:3072
	ds_read_b128 v[146:149], v213
	ds_read_b128 v[150:153], v213 offset:1024
	ds_read_b128 v[154:157], v213 offset:2048
	ds_read_b128 v[158:161], v213 offset:3072
	s_add_u32 s36, s18, 0x100
	s_addc_u32 s37, s19, 0
	s_cmpk_eq_i32 s71, 0xdc
	s_cselect_b32 s41, s3, s37
	s_cselect_b32 s40, s2, s36
	s_cselect_b32 s39, s35, s70
	s_cselect_b32 s38, s34, s69
	v_lshl_add_u64 v[216:217], s[18:19], 0, v[178:179]
	s_add_i32 m0, s44, 0xc000
	ds_read_b128 v[162:165], v214
	ds_read_b128 v[166:169], v214 offset:1024
	ds_read_b128 v[186:189], v214 offset:2048
	ds_read_b128 v[190:193], v214 offset:3072
	ds_read_b128 v[194:197], v214 offset:4096
	ds_read_b128 v[198:201], v214 offset:5120
	ds_read_b128 v[202:205], v214 offset:6144
	ds_read_b128 v[206:209], v214 offset:7168
	global_load_lds_dwordx4 v[216:217], off
	v_lshl_add_u64 v[216:217], s[18:19], 0, v[180:181]
	s_add_i32 m0, s44, 0xe000
	s_nop 0
	global_load_lds_dwordx4 v[216:217], off
	s_waitcnt vmcnt(8)
	s_waitcnt lgkmcnt(0)
	s_barrier
	v_mfma_f32_16x16x32_bf16 v[126:129], v[130:133], v[162:165], 0
	v_mfma_f32_16x16x32_bf16 v[126:129], v[134:137], v[166:169], v[126:129]
	v_mfma_f32_16x16x32_bf16 v[122:125], v[138:141], v[162:165], 0
	v_mfma_f32_16x16x32_bf16 v[122:125], v[142:145], v[166:169], v[122:125]
	v_mfma_f32_16x16x32_bf16 v[110:113], v[130:133], v[186:189], 0
	v_mfma_f32_16x16x32_bf16 v[110:113], v[134:137], v[190:193], v[110:113]
	v_mfma_f32_16x16x32_bf16 v[106:109], v[138:141], v[186:189], 0
	v_mfma_f32_16x16x32_bf16 v[106:109], v[142:145], v[190:193], v[106:109]
	v_mfma_f32_16x16x32_bf16 v[94:97], v[130:133], v[194:197], 0
	v_mfma_f32_16x16x32_bf16 v[94:97], v[134:137], v[198:201], v[94:97]
	v_mfma_f32_16x16x32_bf16 v[90:93], v[138:141], v[194:197], 0
	v_mfma_f32_16x16x32_bf16 v[90:93], v[142:145], v[198:201], v[90:93]
	v_mfma_f32_16x16x32_bf16 v[78:81], v[130:133], v[202:205], 0
	v_mfma_f32_16x16x32_bf16 v[78:81], v[134:137], v[206:209], v[78:81]
	v_mfma_f32_16x16x32_bf16 v[74:77], v[138:141], v[202:205], 0
	v_mfma_f32_16x16x32_bf16 v[74:77], v[142:145], v[206:209], v[74:77]
	v_mfma_f32_16x16x32_bf16 v[118:121], v[146:149], v[162:165], 0
	v_mfma_f32_16x16x32_bf16 v[118:121], v[150:153], v[166:169], v[118:121]
	v_mfma_f32_16x16x32_bf16 v[114:117], v[154:157], v[162:165], 0
	v_mfma_f32_16x16x32_bf16 v[114:117], v[158:161], v[166:169], v[114:117]
	v_mfma_f32_16x16x32_bf16 v[102:105], v[146:149], v[186:189], 0
	v_mfma_f32_16x16x32_bf16 v[102:105], v[150:153], v[190:193], v[102:105]
	v_mfma_f32_16x16x32_bf16 v[98:101], v[154:157], v[186:189], 0
	v_mfma_f32_16x16x32_bf16 v[98:101], v[158:161], v[190:193], v[98:101]
	v_mfma_f32_16x16x32_bf16 v[86:89], v[146:149], v[194:197], 0
	v_mfma_f32_16x16x32_bf16 v[86:89], v[150:153], v[198:201], v[86:89]
	v_mfma_f32_16x16x32_bf16 v[82:85], v[154:157], v[194:197], 0
	v_mfma_f32_16x16x32_bf16 v[82:85], v[158:161], v[198:201], v[82:85]
	v_mfma_f32_16x16x32_bf16 v[70:73], v[146:149], v[202:205], 0
	v_mfma_f32_16x16x32_bf16 v[70:73], v[150:153], v[206:209], v[70:73]
	v_mfma_f32_16x16x32_bf16 v[66:69], v[154:157], v[202:205], 0
	v_mfma_f32_16x16x32_bf16 v[66:69], v[158:161], v[206:209], v[66:69]
	s_barrier
	s_add_i32 s18, s56, s43
	v_lshl_add_u64 v[216:217], s[38:39], 0, v[172:173]
	s_mov_b32 m0, s18
	ds_read_b128 v[162:165], v214 offset:16384
	ds_read_b128 v[166:169], v214 offset:17408
	ds_read_b128 v[186:189], v214 offset:18432
	ds_read_b128 v[190:193], v214 offset:19456
	ds_read_b128 v[194:197], v214 offset:20480
	ds_read_b128 v[198:201], v214 offset:21504
	ds_read_b128 v[202:205], v214 offset:22528
	ds_read_b128 v[206:209], v214 offset:23552
	global_load_lds_dwordx4 v[216:217], off
	s_add_i32 m0, s18, 0x2000
	s_add_u32 s18, s38, 0x380000
	v_lshl_add_u64 v[218:219], s[38:39], 0, v[176:177]
	s_addc_u32 s19, s39, 0
	s_add_i32 s72, s57, s43
	global_load_lds_dwordx4 v[218:219], off
	v_lshl_add_u64 v[220:221], s[18:19], 0, v[172:173]
	s_mov_b32 m0, s72
	v_lshl_add_u64 v[222:223], s[40:41], 0, v[174:175]
	global_load_lds_dwordx4 v[220:221], off
	v_lshl_add_u64 v[220:221], s[18:19], 0, v[176:177]
	s_add_i32 m0, s72, 0x2000
	s_nop 0
	global_load_lds_dwordx4 v[220:221], off
	v_lshl_add_u64 v[220:221], s[40:41], 0, v[170:171]
	s_mov_b32 m0, s44
	s_nop 0
	global_load_lds_dwordx4 v[220:221], off
	s_mov_b32 m0, s45
	s_nop 0
	global_load_lds_dwordx4 v[222:223], off
	s_waitcnt vmcnt(8)
	s_waitcnt lgkmcnt(0)
	s_barrier
	v_mfma_f32_16x16x32_bf16 v[62:65], v[130:133], v[162:165], 0
	v_mfma_f32_16x16x32_bf16 v[62:65], v[134:137], v[166:169], v[62:65]
	v_mfma_f32_16x16x32_bf16 v[58:61], v[138:141], v[162:165], 0
	v_mfma_f32_16x16x32_bf16 v[58:61], v[142:145], v[166:169], v[58:61]
	v_mfma_f32_16x16x32_bf16 v[46:49], v[130:133], v[186:189], 0
	v_mfma_f32_16x16x32_bf16 v[46:49], v[134:137], v[190:193], v[46:49]
	v_mfma_f32_16x16x32_bf16 v[42:45], v[138:141], v[186:189], 0
	v_mfma_f32_16x16x32_bf16 v[42:45], v[142:145], v[190:193], v[42:45]
	v_mfma_f32_16x16x32_bf16 v[30:33], v[130:133], v[194:197], 0
	v_mfma_f32_16x16x32_bf16 v[30:33], v[134:137], v[198:201], v[30:33]
	v_mfma_f32_16x16x32_bf16 v[26:29], v[138:141], v[194:197], 0
	v_mfma_f32_16x16x32_bf16 v[26:29], v[142:145], v[198:201], v[26:29]
	v_mfma_f32_16x16x32_bf16 v[14:17], v[130:133], v[202:205], 0
	v_mfma_f32_16x16x32_bf16 v[14:17], v[134:137], v[206:209], v[14:17]
	v_mfma_f32_16x16x32_bf16 v[10:13], v[138:141], v[202:205], 0
	v_mfma_f32_16x16x32_bf16 v[10:13], v[142:145], v[206:209], v[10:13]
	v_mfma_f32_16x16x32_bf16 v[54:57], v[146:149], v[162:165], 0
	v_mfma_f32_16x16x32_bf16 v[54:57], v[150:153], v[166:169], v[54:57]
	v_mfma_f32_16x16x32_bf16 v[50:53], v[154:157], v[162:165], 0
	v_mfma_f32_16x16x32_bf16 v[50:53], v[158:161], v[166:169], v[50:53]
	v_mfma_f32_16x16x32_bf16 v[38:41], v[146:149], v[186:189], 0
	v_mfma_f32_16x16x32_bf16 v[38:41], v[150:153], v[190:193], v[38:41]
	v_mfma_f32_16x16x32_bf16 v[34:37], v[154:157], v[186:189], 0
	v_mfma_f32_16x16x32_bf16 v[34:37], v[158:161], v[190:193], v[34:37]
	v_mfma_f32_16x16x32_bf16 v[22:25], v[146:149], v[194:197], 0
	v_mfma_f32_16x16x32_bf16 v[22:25], v[150:153], v[198:201], v[22:25]
	v_mfma_f32_16x16x32_bf16 v[18:21], v[154:157], v[194:197], 0
	v_mfma_f32_16x16x32_bf16 v[18:21], v[158:161], v[198:201], v[18:21]
	v_mfma_f32_16x16x32_bf16 v[6:9], v[146:149], v[202:205], 0
	v_mfma_f32_16x16x32_bf16 v[6:9], v[150:153], v[206:209], v[6:9]
	v_mfma_f32_16x16x32_bf16 v[2:5], v[154:157], v[202:205], 0
	v_mfma_f32_16x16x32_bf16 v[2:5], v[158:161], v[206:209], v[2:5]
	s_barrier
	s_add_i32 s72, 0, 0x18000
	s_add_i32 s73, 0, 0x1c000
	v_add_u32_e32 v142, s72, v211
	v_add_u32_e32 v158, s73, v211
	ds_read_b128 v[130:133], v142
	ds_read_b128 v[134:137], v142 offset:1024
	ds_read_b128 v[138:141], v142 offset:2048
	ds_read_b128 v[142:145], v142 offset:3072
	ds_read_b128 v[146:149], v158
	ds_read_b128 v[150:153], v158 offset:1024
	ds_read_b128 v[154:157], v158 offset:2048
	ds_read_b128 v[158:161], v158 offset:3072
	s_add_u32 s18, s40, 0x380000
	s_addc_u32 s19, s41, 0
	s_mov_b32 m0, s46
	v_lshl_add_u64 v[224:225], s[18:19], 0, v[170:171]
	ds_read_b128 v[162:165], v214 offset:32768
	ds_read_b128 v[166:169], v214 offset:33792
	ds_read_b128 v[186:189], v214 offset:34816
	ds_read_b128 v[190:193], v214 offset:35840
	ds_read_b128 v[194:197], v214 offset:36864
	ds_read_b128 v[198:201], v214 offset:37888
	ds_read_b128 v[202:205], v214 offset:38912
	ds_read_b128 v[206:209], v214 offset:39936
	global_load_lds_dwordx4 v[224:225], off
	v_lshl_add_u64 v[224:225], s[18:19], 0, v[174:175]
	s_mov_b32 m0, s47
	s_nop 0
	global_load_lds_dwordx4 v[224:225], off
	s_waitcnt vmcnt(8)
	s_waitcnt lgkmcnt(0)
	s_barrier
	v_mfma_f32_16x16x32_bf16 v[126:129], v[130:133], v[162:165], v[126:129]
	v_mfma_f32_16x16x32_bf16 v[126:129], v[134:137], v[166:169], v[126:129]
	v_mfma_f32_16x16x32_bf16 v[122:125], v[138:141], v[162:165], v[122:125]
	v_mfma_f32_16x16x32_bf16 v[122:125], v[142:145], v[166:169], v[122:125]
	v_mfma_f32_16x16x32_bf16 v[110:113], v[130:133], v[186:189], v[110:113]
	v_mfma_f32_16x16x32_bf16 v[110:113], v[134:137], v[190:193], v[110:113]
	v_mfma_f32_16x16x32_bf16 v[106:109], v[138:141], v[186:189], v[106:109]
	v_mfma_f32_16x16x32_bf16 v[106:109], v[142:145], v[190:193], v[106:109]
	v_mfma_f32_16x16x32_bf16 v[94:97], v[130:133], v[194:197], v[94:97]
	v_mfma_f32_16x16x32_bf16 v[94:97], v[134:137], v[198:201], v[94:97]
	v_mfma_f32_16x16x32_bf16 v[90:93], v[138:141], v[194:197], v[90:93]
	v_mfma_f32_16x16x32_bf16 v[90:93], v[142:145], v[198:201], v[90:93]
	v_mfma_f32_16x16x32_bf16 v[78:81], v[130:133], v[202:205], v[78:81]
	v_mfma_f32_16x16x32_bf16 v[78:81], v[134:137], v[206:209], v[78:81]
	v_mfma_f32_16x16x32_bf16 v[74:77], v[138:141], v[202:205], v[74:77]
	v_mfma_f32_16x16x32_bf16 v[74:77], v[142:145], v[206:209], v[74:77]
	v_mfma_f32_16x16x32_bf16 v[118:121], v[146:149], v[162:165], v[118:121]
	v_mfma_f32_16x16x32_bf16 v[118:121], v[150:153], v[166:169], v[118:121]
	v_mfma_f32_16x16x32_bf16 v[114:117], v[154:157], v[162:165], v[114:117]
	v_mfma_f32_16x16x32_bf16 v[114:117], v[158:161], v[166:169], v[114:117]
	v_mfma_f32_16x16x32_bf16 v[102:105], v[146:149], v[186:189], v[102:105]
	v_mfma_f32_16x16x32_bf16 v[102:105], v[150:153], v[190:193], v[102:105]
	v_mfma_f32_16x16x32_bf16 v[98:101], v[154:157], v[186:189], v[98:101]
	v_mfma_f32_16x16x32_bf16 v[98:101], v[158:161], v[190:193], v[98:101]
	v_mfma_f32_16x16x32_bf16 v[86:89], v[146:149], v[194:197], v[86:89]
	v_mfma_f32_16x16x32_bf16 v[86:89], v[150:153], v[198:201], v[86:89]
	v_mfma_f32_16x16x32_bf16 v[82:85], v[154:157], v[194:197], v[82:85]
	v_mfma_f32_16x16x32_bf16 v[82:85], v[158:161], v[198:201], v[82:85]
	v_mfma_f32_16x16x32_bf16 v[70:73], v[146:149], v[202:205], v[70:73]
	v_mfma_f32_16x16x32_bf16 v[70:73], v[150:153], v[206:209], v[70:73]
	v_mfma_f32_16x16x32_bf16 v[66:69], v[154:157], v[202:205], v[66:69]
	v_mfma_f32_16x16x32_bf16 v[66:69], v[158:161], v[206:209], v[66:69]
	s_barrier
	s_add_i32 s18, s72, s43
	v_lshl_add_u64 v[216:217], v[216:217], 0, s[8:9]
	s_mov_b32 m0, s18
	ds_read_b128 v[162:165], v214 offset:49152
	ds_read_b128 v[166:169], v214 offset:50176
	ds_read_b128 v[186:189], v214 offset:51200
	ds_read_b128 v[190:193], v214 offset:52224
	ds_read_b128 v[194:197], v214 offset:53248
	ds_read_b128 v[198:201], v214 offset:54272
	ds_read_b128 v[202:205], v214 offset:55296
	ds_read_b128 v[206:209], v214 offset:56320
	global_load_lds_dwordx4 v[216:217], off
	s_add_i32 m0, s18, 0x2000
	s_add_u32 s18, s38, 0x380080
	v_lshl_add_u64 v[216:217], v[218:219], 0, s[8:9]
	s_addc_u32 s19, s39, 0
	s_add_i32 s38, s73, s43
	global_load_lds_dwordx4 v[216:217], off
	v_lshl_add_u64 v[216:217], s[18:19], 0, v[172:173]
	s_mov_b32 m0, s38
	s_nop 0
	global_load_lds_dwordx4 v[216:217], off
	v_lshl_add_u64 v[216:217], s[18:19], 0, v[176:177]
	s_add_i32 m0, s38, 0x2000
	s_nop 0
	global_load_lds_dwordx4 v[216:217], off
	v_lshl_add_u64 v[216:217], v[220:221], 0, s[8:9]
	s_mov_b32 m0, s51
	s_nop 0
	global_load_lds_dwordx4 v[216:217], off
	v_lshl_add_u64 v[216:217], v[222:223], 0, s[8:9]
	s_mov_b32 m0, s54
	s_nop 0
	global_load_lds_dwordx4 v[216:217], off
	s_waitcnt vmcnt(8)
	s_waitcnt lgkmcnt(0)
	s_barrier
	v_mfma_f32_16x16x32_bf16 v[62:65], v[130:133], v[162:165], v[62:65]
	v_mfma_f32_16x16x32_bf16 v[62:65], v[134:137], v[166:169], v[62:65]
	v_mfma_f32_16x16x32_bf16 v[58:61], v[138:141], v[162:165], v[58:61]
	v_mfma_f32_16x16x32_bf16 v[58:61], v[142:145], v[166:169], v[58:61]
	v_mfma_f32_16x16x32_bf16 v[46:49], v[130:133], v[186:189], v[46:49]
	v_mfma_f32_16x16x32_bf16 v[46:49], v[134:137], v[190:193], v[46:49]
	v_mfma_f32_16x16x32_bf16 v[42:45], v[138:141], v[186:189], v[42:45]
	v_mfma_f32_16x16x32_bf16 v[42:45], v[142:145], v[190:193], v[42:45]
	v_mfma_f32_16x16x32_bf16 v[30:33], v[130:133], v[194:197], v[30:33]
	v_mfma_f32_16x16x32_bf16 v[30:33], v[134:137], v[198:201], v[30:33]
	v_mfma_f32_16x16x32_bf16 v[26:29], v[138:141], v[194:197], v[26:29]
	v_mfma_f32_16x16x32_bf16 v[26:29], v[142:145], v[198:201], v[26:29]
	v_mfma_f32_16x16x32_bf16 v[14:17], v[130:133], v[202:205], v[14:17]
	v_mfma_f32_16x16x32_bf16 v[14:17], v[134:137], v[206:209], v[14:17]
	v_mfma_f32_16x16x32_bf16 v[10:13], v[138:141], v[202:205], v[10:13]
	v_mfma_f32_16x16x32_bf16 v[10:13], v[142:145], v[206:209], v[10:13]
	v_mfma_f32_16x16x32_bf16 v[54:57], v[146:149], v[162:165], v[54:57]
	v_mfma_f32_16x16x32_bf16 v[54:57], v[150:153], v[166:169], v[54:57]
	v_mfma_f32_16x16x32_bf16 v[50:53], v[154:157], v[162:165], v[50:53]
	v_mfma_f32_16x16x32_bf16 v[50:53], v[158:161], v[166:169], v[50:53]
	v_mfma_f32_16x16x32_bf16 v[38:41], v[146:149], v[186:189], v[38:41]
	v_mfma_f32_16x16x32_bf16 v[38:41], v[150:153], v[190:193], v[38:41]
	v_mfma_f32_16x16x32_bf16 v[34:37], v[154:157], v[186:189], v[34:37]
	v_mfma_f32_16x16x32_bf16 v[34:37], v[158:161], v[190:193], v[34:37]
	v_mfma_f32_16x16x32_bf16 v[22:25], v[146:149], v[194:197], v[22:25]
	v_mfma_f32_16x16x32_bf16 v[22:25], v[150:153], v[198:201], v[22:25]
	v_mfma_f32_16x16x32_bf16 v[18:21], v[154:157], v[194:197], v[18:21]
	v_mfma_f32_16x16x32_bf16 v[18:21], v[158:161], v[198:201], v[18:21]
	v_mfma_f32_16x16x32_bf16 v[6:9], v[146:149], v[202:205], v[6:9]
	v_mfma_f32_16x16x32_bf16 v[6:9], v[150:153], v[206:209], v[6:9]
	v_mfma_f32_16x16x32_bf16 v[2:5], v[154:157], v[202:205], v[2:5]
	v_mfma_f32_16x16x32_bf16 v[2:5], v[158:161], v[206:209], v[2:5]
	s_barrier
	s_add_i32 s71, s71, 2
	s_add_u32 s69, s69, 0x100
	s_addc_u32 s70, s70, 0
	s_cmpk_gt_u32 s71, 0xdd
	s_mov_b64 s[18:19], s[36:37]
.LBB0_2241:
	ds_read_b128 v[130:133], v212
	ds_read_b128 v[134:137], v212 offset:1024
	ds_read_b128 v[138:141], v212 offset:2048
	ds_read_b128 v[142:145], v212 offset:3072
	ds_read_b128 v[146:149], v213
	ds_read_b128 v[150:153], v213 offset:1024
	ds_read_b128 v[154:157], v213 offset:2048
	ds_read_b128 v[158:161], v213 offset:3072
	s_add_u32 s36, s18, 0x100
	s_addc_u32 s37, s19, 0
	s_cmpk_eq_i32 s71, 0xdc
	s_cselect_b32 s41, s3, s37
	s_cselect_b32 s40, s2, s36
	s_cselect_b32 s39, s35, s70
	s_cselect_b32 s38, s34, s69
	v_lshl_add_u64 v[216:217], s[18:19], 0, v[178:179]
	s_add_i32 m0, s44, 0xc000
	ds_read_b128 v[162:165], v214
	ds_read_b128 v[166:169], v214 offset:1024
	ds_read_b128 v[186:189], v214 offset:2048
	ds_read_b128 v[190:193], v214 offset:3072
	ds_read_b128 v[194:197], v214 offset:4096
	ds_read_b128 v[198:201], v214 offset:5120
	ds_read_b128 v[202:205], v214 offset:6144
	ds_read_b128 v[206:209], v214 offset:7168
	global_load_lds_dwordx4 v[216:217], off
	v_lshl_add_u64 v[216:217], s[18:19], 0, v[180:181]
	s_add_i32 m0, s44, 0xe000
	s_nop 0
	global_load_lds_dwordx4 v[216:217], off
	s_waitcnt vmcnt(8)
	s_waitcnt lgkmcnt(0)
	s_barrier
	v_mfma_f32_16x16x32_bf16 v[126:129], v[130:133], v[162:165], v[126:129]
	v_mfma_f32_16x16x32_bf16 v[126:129], v[134:137], v[166:169], v[126:129]
	v_mfma_f32_16x16x32_bf16 v[122:125], v[138:141], v[162:165], v[122:125]
	v_mfma_f32_16x16x32_bf16 v[122:125], v[142:145], v[166:169], v[122:125]
	v_mfma_f32_16x16x32_bf16 v[110:113], v[130:133], v[186:189], v[110:113]
	v_mfma_f32_16x16x32_bf16 v[110:113], v[134:137], v[190:193], v[110:113]
	v_mfma_f32_16x16x32_bf16 v[106:109], v[138:141], v[186:189], v[106:109]
	v_mfma_f32_16x16x32_bf16 v[106:109], v[142:145], v[190:193], v[106:109]
	v_mfma_f32_16x16x32_bf16 v[94:97], v[130:133], v[194:197], v[94:97]
	v_mfma_f32_16x16x32_bf16 v[94:97], v[134:137], v[198:201], v[94:97]
	v_mfma_f32_16x16x32_bf16 v[90:93], v[138:141], v[194:197], v[90:93]
	v_mfma_f32_16x16x32_bf16 v[90:93], v[142:145], v[198:201], v[90:93]
	v_mfma_f32_16x16x32_bf16 v[78:81], v[130:133], v[202:205], v[78:81]
	v_mfma_f32_16x16x32_bf16 v[78:81], v[134:137], v[206:209], v[78:81]
	v_mfma_f32_16x16x32_bf16 v[74:77], v[138:141], v[202:205], v[74:77]
	v_mfma_f32_16x16x32_bf16 v[74:77], v[142:145], v[206:209], v[74:77]
	v_mfma_f32_16x16x32_bf16 v[118:121], v[146:149], v[162:165], v[118:121]
	v_mfma_f32_16x16x32_bf16 v[118:121], v[150:153], v[166:169], v[118:121]
	v_mfma_f32_16x16x32_bf16 v[114:117], v[154:157], v[162:165], v[114:117]
	v_mfma_f32_16x16x32_bf16 v[114:117], v[158:161], v[166:169], v[114:117]
	v_mfma_f32_16x16x32_bf16 v[102:105], v[146:149], v[186:189], v[102:105]
	v_mfma_f32_16x16x32_bf16 v[102:105], v[150:153], v[190:193], v[102:105]
	v_mfma_f32_16x16x32_bf16 v[98:101], v[154:157], v[186:189], v[98:101]
	v_mfma_f32_16x16x32_bf16 v[98:101], v[158:161], v[190:193], v[98:101]
	v_mfma_f32_16x16x32_bf16 v[86:89], v[146:149], v[194:197], v[86:89]
	v_mfma_f32_16x16x32_bf16 v[86:89], v[150:153], v[198:201], v[86:89]
	v_mfma_f32_16x16x32_bf16 v[82:85], v[154:157], v[194:197], v[82:85]
	v_mfma_f32_16x16x32_bf16 v[82:85], v[158:161], v[198:201], v[82:85]
	v_mfma_f32_16x16x32_bf16 v[70:73], v[146:149], v[202:205], v[70:73]
	v_mfma_f32_16x16x32_bf16 v[70:73], v[150:153], v[206:209], v[70:73]
	v_mfma_f32_16x16x32_bf16 v[66:69], v[154:157], v[202:205], v[66:69]
	v_mfma_f32_16x16x32_bf16 v[66:69], v[158:161], v[206:209], v[66:69]
	s_barrier
	s_add_i32 s18, s56, s43
	v_lshl_add_u64 v[216:217], s[38:39], 0, v[172:173]
	s_mov_b32 m0, s18
	ds_read_b128 v[162:165], v214 offset:16384
	ds_read_b128 v[166:169], v214 offset:17408
	ds_read_b128 v[186:189], v214 offset:18432
	ds_read_b128 v[190:193], v214 offset:19456
	ds_read_b128 v[194:197], v214 offset:20480
	ds_read_b128 v[198:201], v214 offset:21504
	ds_read_b128 v[202:205], v214 offset:22528
	ds_read_b128 v[206:209], v214 offset:23552
	global_load_lds_dwordx4 v[216:217], off
	s_add_i32 m0, s18, 0x2000
	s_add_u32 s18, s38, 0x380000
	v_lshl_add_u64 v[218:219], s[38:39], 0, v[176:177]
	s_addc_u32 s19, s39, 0
	s_add_i32 s72, s57, s43
	global_load_lds_dwordx4 v[218:219], off
	v_lshl_add_u64 v[220:221], s[18:19], 0, v[172:173]
	s_mov_b32 m0, s72
	v_lshl_add_u64 v[222:223], s[40:41], 0, v[174:175]
	global_load_lds_dwordx4 v[220:221], off
	v_lshl_add_u64 v[220:221], s[18:19], 0, v[176:177]
	s_add_i32 m0, s72, 0x2000
	s_nop 0
	global_load_lds_dwordx4 v[220:221], off
	v_lshl_add_u64 v[220:221], s[40:41], 0, v[170:171]
	s_mov_b32 m0, s44
	s_nop 0
	global_load_lds_dwordx4 v[220:221], off
	s_mov_b32 m0, s45
	s_nop 0
	global_load_lds_dwordx4 v[222:223], off
	s_waitcnt vmcnt(8)
	s_waitcnt lgkmcnt(0)
	s_barrier
	v_mfma_f32_16x16x32_bf16 v[62:65], v[130:133], v[162:165], v[62:65]
	v_mfma_f32_16x16x32_bf16 v[62:65], v[134:137], v[166:169], v[62:65]
	v_mfma_f32_16x16x32_bf16 v[58:61], v[138:141], v[162:165], v[58:61]
	v_mfma_f32_16x16x32_bf16 v[58:61], v[142:145], v[166:169], v[58:61]
	v_mfma_f32_16x16x32_bf16 v[46:49], v[130:133], v[186:189], v[46:49]
	v_mfma_f32_16x16x32_bf16 v[46:49], v[134:137], v[190:193], v[46:49]
	v_mfma_f32_16x16x32_bf16 v[42:45], v[138:141], v[186:189], v[42:45]
	v_mfma_f32_16x16x32_bf16 v[42:45], v[142:145], v[190:193], v[42:45]
	v_mfma_f32_16x16x32_bf16 v[30:33], v[130:133], v[194:197], v[30:33]
	v_mfma_f32_16x16x32_bf16 v[30:33], v[134:137], v[198:201], v[30:33]
	v_mfma_f32_16x16x32_bf16 v[26:29], v[138:141], v[194:197], v[26:29]
	v_mfma_f32_16x16x32_bf16 v[26:29], v[142:145], v[198:201], v[26:29]
	v_mfma_f32_16x16x32_bf16 v[14:17], v[130:133], v[202:205], v[14:17]
	v_mfma_f32_16x16x32_bf16 v[14:17], v[134:137], v[206:209], v[14:17]
	v_mfma_f32_16x16x32_bf16 v[10:13], v[138:141], v[202:205], v[10:13]
	v_mfma_f32_16x16x32_bf16 v[10:13], v[142:145], v[206:209], v[10:13]
	v_mfma_f32_16x16x32_bf16 v[54:57], v[146:149], v[162:165], v[54:57]
	v_mfma_f32_16x16x32_bf16 v[54:57], v[150:153], v[166:169], v[54:57]
	v_mfma_f32_16x16x32_bf16 v[50:53], v[154:157], v[162:165], v[50:53]
	v_mfma_f32_16x16x32_bf16 v[50:53], v[158:161], v[166:169], v[50:53]
	v_mfma_f32_16x16x32_bf16 v[38:41], v[146:149], v[186:189], v[38:41]
	v_mfma_f32_16x16x32_bf16 v[38:41], v[150:153], v[190:193], v[38:41]
	v_mfma_f32_16x16x32_bf16 v[34:37], v[154:157], v[186:189], v[34:37]
	v_mfma_f32_16x16x32_bf16 v[34:37], v[158:161], v[190:193], v[34:37]
	v_mfma_f32_16x16x32_bf16 v[22:25], v[146:149], v[194:197], v[22:25]
	v_mfma_f32_16x16x32_bf16 v[22:25], v[150:153], v[198:201], v[22:25]
	v_mfma_f32_16x16x32_bf16 v[18:21], v[154:157], v[194:197], v[18:21]
	v_mfma_f32_16x16x32_bf16 v[18:21], v[158:161], v[198:201], v[18:21]
	v_mfma_f32_16x16x32_bf16 v[6:9], v[146:149], v[202:205], v[6:9]
	v_mfma_f32_16x16x32_bf16 v[6:9], v[150:153], v[206:209], v[6:9]
	v_mfma_f32_16x16x32_bf16 v[2:5], v[154:157], v[202:205], v[2:5]
	v_mfma_f32_16x16x32_bf16 v[2:5], v[158:161], v[206:209], v[2:5]
	s_barrier
	s_add_i32 s72, 0, 0x18000
	s_add_i32 s73, 0, 0x1c000
	v_add_u32_e32 v142, s72, v211
	v_add_u32_e32 v158, s73, v211
	ds_read_b128 v[130:133], v142
	ds_read_b128 v[134:137], v142 offset:1024
	ds_read_b128 v[138:141], v142 offset:2048
	ds_read_b128 v[142:145], v142 offset:3072
	ds_read_b128 v[146:149], v158
	ds_read_b128 v[150:153], v158 offset:1024
	ds_read_b128 v[154:157], v158 offset:2048
	ds_read_b128 v[158:161], v158 offset:3072
	s_add_u32 s18, s40, 0x380000
	s_addc_u32 s19, s41, 0
	s_mov_b32 m0, s46
	v_lshl_add_u64 v[224:225], s[18:19], 0, v[170:171]
	ds_read_b128 v[162:165], v214 offset:32768
	ds_read_b128 v[166:169], v214 offset:33792
	ds_read_b128 v[186:189], v214 offset:34816
	ds_read_b128 v[190:193], v214 offset:35840
	ds_read_b128 v[194:197], v214 offset:36864
	ds_read_b128 v[198:201], v214 offset:37888
	ds_read_b128 v[202:205], v214 offset:38912
	ds_read_b128 v[206:209], v214 offset:39936
	global_load_lds_dwordx4 v[224:225], off
	v_lshl_add_u64 v[224:225], s[18:19], 0, v[174:175]
	s_mov_b32 m0, s47
	s_nop 0
	global_load_lds_dwordx4 v[224:225], off
	s_waitcnt vmcnt(8)
	s_waitcnt lgkmcnt(0)
	s_barrier
	v_mfma_f32_16x16x32_bf16 v[126:129], v[130:133], v[162:165], v[126:129]
	v_mfma_f32_16x16x32_bf16 v[126:129], v[134:137], v[166:169], v[126:129]
	v_mfma_f32_16x16x32_bf16 v[122:125], v[138:141], v[162:165], v[122:125]
	v_mfma_f32_16x16x32_bf16 v[122:125], v[142:145], v[166:169], v[122:125]
	v_mfma_f32_16x16x32_bf16 v[110:113], v[130:133], v[186:189], v[110:113]
	v_mfma_f32_16x16x32_bf16 v[110:113], v[134:137], v[190:193], v[110:113]
	v_mfma_f32_16x16x32_bf16 v[106:109], v[138:141], v[186:189], v[106:109]
	v_mfma_f32_16x16x32_bf16 v[106:109], v[142:145], v[190:193], v[106:109]
	v_mfma_f32_16x16x32_bf16 v[94:97], v[130:133], v[194:197], v[94:97]
	v_mfma_f32_16x16x32_bf16 v[94:97], v[134:137], v[198:201], v[94:97]
	v_mfma_f32_16x16x32_bf16 v[90:93], v[138:141], v[194:197], v[90:93]
	v_mfma_f32_16x16x32_bf16 v[90:93], v[142:145], v[198:201], v[90:93]
	v_mfma_f32_16x16x32_bf16 v[78:81], v[130:133], v[202:205], v[78:81]
	v_mfma_f32_16x16x32_bf16 v[78:81], v[134:137], v[206:209], v[78:81]
	v_mfma_f32_16x16x32_bf16 v[74:77], v[138:141], v[202:205], v[74:77]
	v_mfma_f32_16x16x32_bf16 v[74:77], v[142:145], v[206:209], v[74:77]
	v_mfma_f32_16x16x32_bf16 v[118:121], v[146:149], v[162:165], v[118:121]
	v_mfma_f32_16x16x32_bf16 v[118:121], v[150:153], v[166:169], v[118:121]
	v_mfma_f32_16x16x32_bf16 v[114:117], v[154:157], v[162:165], v[114:117]
	v_mfma_f32_16x16x32_bf16 v[114:117], v[158:161], v[166:169], v[114:117]
	v_mfma_f32_16x16x32_bf16 v[102:105], v[146:149], v[186:189], v[102:105]
	v_mfma_f32_16x16x32_bf16 v[102:105], v[150:153], v[190:193], v[102:105]
	v_mfma_f32_16x16x32_bf16 v[98:101], v[154:157], v[186:189], v[98:101]
	v_mfma_f32_16x16x32_bf16 v[98:101], v[158:161], v[190:193], v[98:101]
	v_mfma_f32_16x16x32_bf16 v[86:89], v[146:149], v[194:197], v[86:89]
	v_mfma_f32_16x16x32_bf16 v[86:89], v[150:153], v[198:201], v[86:89]
	v_mfma_f32_16x16x32_bf16 v[82:85], v[154:157], v[194:197], v[82:85]
	v_mfma_f32_16x16x32_bf16 v[82:85], v[158:161], v[198:201], v[82:85]
	v_mfma_f32_16x16x32_bf16 v[70:73], v[146:149], v[202:205], v[70:73]
	v_mfma_f32_16x16x32_bf16 v[70:73], v[150:153], v[206:209], v[70:73]
	v_mfma_f32_16x16x32_bf16 v[66:69], v[154:157], v[202:205], v[66:69]
	v_mfma_f32_16x16x32_bf16 v[66:69], v[158:161], v[206:209], v[66:69]
	s_barrier
	s_add_i32 s18, s72, s43
	v_lshl_add_u64 v[216:217], v[216:217], 0, s[8:9]
	s_mov_b32 m0, s18
	ds_read_b128 v[162:165], v214 offset:49152
	ds_read_b128 v[166:169], v214 offset:50176
	ds_read_b128 v[186:189], v214 offset:51200
	ds_read_b128 v[190:193], v214 offset:52224
	ds_read_b128 v[194:197], v214 offset:53248
	ds_read_b128 v[198:201], v214 offset:54272
	ds_read_b128 v[202:205], v214 offset:55296
	ds_read_b128 v[206:209], v214 offset:56320
	global_load_lds_dwordx4 v[216:217], off
	s_add_i32 m0, s18, 0x2000
	s_add_u32 s18, s38, 0x380080
	v_lshl_add_u64 v[216:217], v[218:219], 0, s[8:9]
	s_addc_u32 s19, s39, 0
	s_add_i32 s38, s73, s43
	global_load_lds_dwordx4 v[216:217], off
	v_lshl_add_u64 v[216:217], s[18:19], 0, v[172:173]
	s_mov_b32 m0, s38
	s_nop 0
	global_load_lds_dwordx4 v[216:217], off
	v_lshl_add_u64 v[216:217], s[18:19], 0, v[176:177]
	s_add_i32 m0, s38, 0x2000
	s_nop 0
	global_load_lds_dwordx4 v[216:217], off
	v_lshl_add_u64 v[216:217], v[220:221], 0, s[8:9]
	s_mov_b32 m0, s51
	s_nop 0
	global_load_lds_dwordx4 v[216:217], off
	v_lshl_add_u64 v[216:217], v[222:223], 0, s[8:9]
	s_mov_b32 m0, s54
	s_nop 0
	global_load_lds_dwordx4 v[216:217], off
	s_waitcnt vmcnt(8)
	s_waitcnt lgkmcnt(0)
	s_barrier
	v_mfma_f32_16x16x32_bf16 v[62:65], v[130:133], v[162:165], v[62:65]
	v_mfma_f32_16x16x32_bf16 v[62:65], v[134:137], v[166:169], v[62:65]
	v_mfma_f32_16x16x32_bf16 v[58:61], v[138:141], v[162:165], v[58:61]
	v_mfma_f32_16x16x32_bf16 v[58:61], v[142:145], v[166:169], v[58:61]
	v_mfma_f32_16x16x32_bf16 v[46:49], v[130:133], v[186:189], v[46:49]
	v_mfma_f32_16x16x32_bf16 v[46:49], v[134:137], v[190:193], v[46:49]
	v_mfma_f32_16x16x32_bf16 v[42:45], v[138:141], v[186:189], v[42:45]
	v_mfma_f32_16x16x32_bf16 v[42:45], v[142:145], v[190:193], v[42:45]
	v_mfma_f32_16x16x32_bf16 v[30:33], v[130:133], v[194:197], v[30:33]
	v_mfma_f32_16x16x32_bf16 v[30:33], v[134:137], v[198:201], v[30:33]
	v_mfma_f32_16x16x32_bf16 v[26:29], v[138:141], v[194:197], v[26:29]
	v_mfma_f32_16x16x32_bf16 v[26:29], v[142:145], v[198:201], v[26:29]
	v_mfma_f32_16x16x32_bf16 v[14:17], v[130:133], v[202:205], v[14:17]
	v_mfma_f32_16x16x32_bf16 v[14:17], v[134:137], v[206:209], v[14:17]
	v_mfma_f32_16x16x32_bf16 v[10:13], v[138:141], v[202:205], v[10:13]
	v_mfma_f32_16x16x32_bf16 v[10:13], v[142:145], v[206:209], v[10:13]
	v_mfma_f32_16x16x32_bf16 v[54:57], v[146:149], v[162:165], v[54:57]
	v_mfma_f32_16x16x32_bf16 v[54:57], v[150:153], v[166:169], v[54:57]
	v_mfma_f32_16x16x32_bf16 v[50:53], v[154:157], v[162:165], v[50:53]
	v_mfma_f32_16x16x32_bf16 v[50:53], v[158:161], v[166:169], v[50:53]
	v_mfma_f32_16x16x32_bf16 v[38:41], v[146:149], v[186:189], v[38:41]
	v_mfma_f32_16x16x32_bf16 v[38:41], v[150:153], v[190:193], v[38:41]
	v_mfma_f32_16x16x32_bf16 v[34:37], v[154:157], v[186:189], v[34:37]
	v_mfma_f32_16x16x32_bf16 v[34:37], v[158:161], v[190:193], v[34:37]
	v_mfma_f32_16x16x32_bf16 v[22:25], v[146:149], v[194:197], v[22:25]
	v_mfma_f32_16x16x32_bf16 v[22:25], v[150:153], v[198:201], v[22:25]
	v_mfma_f32_16x16x32_bf16 v[18:21], v[154:157], v[194:197], v[18:21]
	v_mfma_f32_16x16x32_bf16 v[18:21], v[158:161], v[198:201], v[18:21]
	v_mfma_f32_16x16x32_bf16 v[6:9], v[146:149], v[202:205], v[6:9]
	v_mfma_f32_16x16x32_bf16 v[6:9], v[150:153], v[206:209], v[6:9]
	v_mfma_f32_16x16x32_bf16 v[2:5], v[154:157], v[202:205], v[2:5]
	v_mfma_f32_16x16x32_bf16 v[2:5], v[158:161], v[206:209], v[2:5]
	s_barrier
	s_add_i32 s71, s71, 2
	s_add_u32 s69, s69, 0x100
	s_addc_u32 s70, s70, 0
	s_cmpk_gt_u32 s71, 0xdd
	s_mov_b64 s[18:19], s[36:37]
	s_cbranch_scc0 .LBB0_2241
	s_and_b64 vcc, exec, s[10:11]
	s_cbranch_vccz .LBB0_2244
	s_barrier
